# adaLN modulation k-loop software-pipelined across k-chunks (next chunk loads issued as registers free up, counted vmcnt) + seam-0 grid sync replaced by the XCD barrier
# speedup vs baseline: 1.0116x; 1.0020x over previous
; __device__ __forceinline__ float sigmoidf_(float x) { return 1.0f / (1.0f + __expf(-x)); }
; __device__ __forceinline__ void phase_prologue(const Frame& F) {
;     ...
;             f32x2 acc[12][2];
; #pragma unroll
;             for (int c = 0; c < 12; ++c) { acc[c][0] = (f32x2){0.f, 0.f}; acc[c][1] = (f32x2){0.f, 0.f}; }
;             for (int kc = 0; kc < 8; ++kc) {
;                 __syncthreads();
;                 for (int i = 0; i < 24; ++i) { const int idx = tid + 512 * i, cd = idx >> 8, kk = idx & 255;
;                     const float cv = cd < 16 ? cp[cd * D + kc * 256 + kk] : cs[(cd - 16) * D + kc * 256 + kk];
;                     sT[kk * 52 + cd] = cv * sigmoidf_(cv); }
;                 __syncthreads();
;                 if (tid < 480) {
; #pragma unroll 2
;                     for (int kk = kl; kk < 256; kk += 10) {
;                         const f32x4 w4 = *(const f32x4*)(wada + (size_t)(kc * 256 + kk) * MODW + 48 * cb + 4 * cgp);
.Lmod_noremap:
.LBB0_10:
	s_ashr_i32 s15, s14, 31
	s_mul_i32 s6, s29, 48
	s_lshl_b64 s[20:21], s[14:15], 2
	s_ashr_i32 s7, s6, 31
	v_mov_b32_e32 v50, v51
	v_lshl_add_u64 v[56:57], s[6:7], 2, v[52:53]
	v_lshl_add_u64 v[58:59], v[52:53], 0, s[20:21]
	s_mov_b64 s[22:23], 0
	s_mov_b32 s15, 10
	v_mov_b64_e32 v[32:33], v[50:51]
	v_mov_b64_e32 v[30:31], v[50:51]
	v_mov_b64_e32 v[40:41], v[50:51]
	v_mov_b64_e32 v[38:39], v[50:51]
	v_mov_b64_e32 v[44:45], v[50:51]
	v_mov_b64_e32 v[42:43], v[50:51]
	v_mov_b64_e32 v[48:49], v[50:51]
	v_mov_b64_e32 v[46:47], v[50:51]
	v_mov_b64_e32 v[34:35], v[50:51]
	v_mov_b64_e32 v[36:37], v[50:51]
	v_mov_b64_e32 v[26:27], v[50:51]
	v_mov_b64_e32 v[28:29], v[50:51]
	v_mov_b64_e32 v[22:23], v[50:51]
	v_mov_b64_e32 v[24:25], v[50:51]
	v_mov_b64_e32 v[18:19], v[50:51]
	v_mov_b64_e32 v[20:21], v[50:51]
	v_mov_b64_e32 v[14:15], v[50:51]
	v_mov_b64_e32 v[16:17], v[50:51]
	v_mov_b64_e32 v[10:11], v[50:51]
	v_mov_b64_e32 v[12:13], v[50:51]
	v_mov_b64_e32 v[6:7], v[50:51]
	v_mov_b64_e32 v[8:9], v[50:51]
	v_mov_b64_e32 v[2:3], v[50:51]
	v_mov_b64_e32 v[4:5], v[50:51]
	v_lshrrev_b32_e32 v78, 8, v192
	v_and_b32_e32 v79, 0xff, v192
	v_lshlrev_b32_e32 v76, 13, v78
	v_lshl_or_b32 v76, v79, 2, v76
	v_mul_u32_u24_e32 v77, 0xd0, v79
	v_lshl_add_u32 v77, v78, 2, v77
	v_mov_b32_e32 v236, 0x78000
	v_mov_b32_e32 v237, 0
	v_cndmask_b32_e64 v236, v236, 0, s[4:5]
	s_mov_b32 s12, 0x78000
	s_mov_b32 s13, 0
	s_mov_b32 s30, 0
	s_mov_b32 s31, 0
	s_mov_b32 s6, 0
	s_add_u32 s8, s48, s6
	s_addc_u32 s9, s49, 0
	global_load_dword v80, v76, s[8:9]
	s_add_u32 s8, s8, 0x4000
	s_addc_u32 s9, s9, 0
	global_load_dword v81, v76, s[8:9]
	s_add_u32 s8, s8, 0x4000
	s_addc_u32 s9, s9, 0
	global_load_dword v82, v76, s[8:9]
	s_add_u32 s8, s8, 0x4000
	s_addc_u32 s9, s9, 0
	global_load_dword v83, v76, s[8:9]
	s_add_u32 s8, s8, 0x4000
	s_addc_u32 s9, s9, 0
	global_load_dword v84, v76, s[8:9]
	s_add_u32 s8, s8, 0x4000
	s_addc_u32 s9, s9, 0
	global_load_dword v85, v76, s[8:9]
	s_add_u32 s8, s8, 0x4000
	s_addc_u32 s9, s9, 0
	global_load_dword v86, v76, s[8:9]
	s_add_u32 s8, s8, 0x4000
	s_addc_u32 s9, s9, 0
	global_load_dword v87, v76, s[8:9]
	s_add_u32 s8, s50, s6
	s_addc_u32 s9, s51, 0
	global_load_dword v88, v76, s[8:9]
	s_add_u32 s8, s8, 0x4000
	s_addc_u32 s9, s9, 0
	global_load_dword v89, v76, s[8:9]
	s_add_u32 s8, s8, 0x4000
	s_addc_u32 s9, s9, 0
	global_load_dword v90, v76, s[8:9]
	s_add_u32 s8, s8, 0x4000
	s_addc_u32 s9, s9, 0
	global_load_dword v91, v76, s[8:9]
	s_add_u32 s8, s8, 0x4000
	s_addc_u32 s9, s9, 0
	global_load_dword v92, v76, s[8:9]
	s_add_u32 s8, s8, 0x4000
	s_addc_u32 s9, s9, 0
	global_load_dword v93, v76, s[8:9]
	s_add_u32 s8, s8, 0x4000
	s_addc_u32 s9, s9, 0
	global_load_dword v94, v76, s[8:9]
	s_add_u32 s8, s8, 0x4000
	s_addc_u32 s9, s9, 0
	global_load_dword v95, v76, s[8:9]
	s_add_u32 s8, s8, 0x4000
	s_addc_u32 s9, s9, 0
	global_load_dword v96, v76, s[8:9]
	s_add_u32 s8, s8, 0x4000
	s_addc_u32 s9, s9, 0
	global_load_dword v97, v76, s[8:9]
	s_add_u32 s8, s8, 0x4000
	s_addc_u32 s9, s9, 0
	global_load_dword v98, v76, s[8:9]
	s_add_u32 s8, s8, 0x4000
	s_addc_u32 s9, s9, 0
	global_load_dword v99, v76, s[8:9]
	s_add_u32 s8, s8, 0x4000
	s_addc_u32 s9, s9, 0
	global_load_dword v100, v76, s[8:9]
	s_add_u32 s8, s8, 0x4000
	s_addc_u32 s9, s9, 0
	global_load_dword v101, v76, s[8:9]
	s_add_u32 s8, s8, 0x4000
	s_addc_u32 s9, s9, 0
	global_load_dword v102, v76, s[8:9]
	s_add_u32 s8, s8, 0x4000
	s_addc_u32 s9, s9, 0
	global_load_dword v103, v76, s[8:9]
	s_and_saveexec_b64 s[10:11], s[0:1]
	v_or_b32_e32 v78, s31, v1
	v_mad_u64_u32 v[234:235], s[6:7], v78, s24, v[58:59]
	global_load_dwordx4 v[104:107], v[234:235], off
	v_lshl_add_u64 v[234:235], v[234:235], 0, s[12:13]
	global_load_dwordx4 v[108:111], v[234:235], off
	v_lshl_add_u64 v[234:235], v[234:235], 0, s[12:13]
	global_load_dwordx4 v[112:115], v[234:235], off
	v_lshl_add_u64 v[234:235], v[234:235], 0, s[12:13]
	global_load_dwordx4 v[116:119], v[234:235], off
	v_lshl_add_u64 v[234:235], v[234:235], 0, s[12:13]
	global_load_dwordx4 v[120:123], v[234:235], off
	v_lshl_add_u64 v[234:235], v[234:235], 0, s[12:13]
	global_load_dwordx4 v[124:127], v[234:235], off
	v_lshl_add_u64 v[234:235], v[234:235], 0, s[12:13]
	global_load_dwordx4 v[128:131], v[234:235], off
	v_lshl_add_u64 v[234:235], v[234:235], 0, s[12:13]
	global_load_dwordx4 v[132:135], v[234:235], off
	v_lshl_add_u64 v[234:235], v[234:235], 0, s[12:13]
	global_load_dwordx4 v[136:139], v[234:235], off
	v_lshl_add_u64 v[234:235], v[234:235], 0, s[12:13]
	global_load_dwordx4 v[140:143], v[234:235], off
	v_lshl_add_u64 v[234:235], v[234:235], 0, s[12:13]
	global_load_dwordx4 v[144:147], v[234:235], off
	v_lshl_add_u64 v[234:235], v[234:235], 0, s[12:13]
	global_load_dwordx4 v[148:151], v[234:235], off
	v_lshl_add_u64 v[234:235], v[234:235], 0, s[12:13]
	global_load_dwordx4 v[152:155], v[234:235], off
	v_lshl_add_u64 v[234:235], v[234:235], 0, s[12:13]
	global_load_dwordx4 v[156:159], v[234:235], off
	v_lshl_add_u64 v[234:235], v[234:235], 0, s[12:13]
	global_load_dwordx4 v[160:163], v[234:235], off
	v_lshl_add_u64 v[234:235], v[234:235], 0, s[12:13]
	global_load_dwordx4 v[164:167], v[234:235], off
	v_lshl_add_u64 v[234:235], v[234:235], 0, s[12:13]
	global_load_dwordx4 v[168:171], v[234:235], off
	v_lshl_add_u64 v[234:235], v[234:235], 0, s[12:13]
	global_load_dwordx4 v[172:175], v[234:235], off
	v_lshl_add_u64 v[234:235], v[234:235], 0, s[12:13]
	global_load_dwordx4 v[176:179], v[234:235], off
	v_lshl_add_u64 v[234:235], v[234:235], 0, s[12:13]
	global_load_dwordx4 v[180:183], v[234:235], off
	v_lshl_add_u64 v[234:235], v[234:235], 0, s[12:13]
	global_load_dwordx4 v[184:187], v[234:235], off
	v_lshl_add_u64 v[234:235], v[234:235], 0, s[12:13]
	global_load_dwordx4 v[188:191], v[234:235], off
	v_lshl_add_u64 v[234:235], v[234:235], 0, s[12:13]
	global_load_dwordx4 v[194:197], v[234:235], off
	v_lshl_add_u64 v[234:235], v[234:235], 0, s[12:13]
	global_load_dwordx4 v[198:201], v[234:235], off
	v_lshl_add_u64 v[234:235], v[234:235], 0, s[12:13]
	global_load_dwordx4 v[202:205], v[234:235], off
	v_lshl_add_u64 v[234:235], v[234:235], 0, v[236:237]
	global_load_dwordx4 v[206:209], v[234:235], off
	s_mov_b64 exec, s[10:11]
; __device__ __forceinline__ float sigmoidf_(float x) { return 1.0f / (1.0f + __expf(-x)); }
; __device__ __forceinline__ void phase_prologue(const Frame& F) {
;     ...
;                 __syncthreads();
;                 for (int i = 0; i < 24; ++i) { const int idx = tid + 512 * i, cd = idx >> 8, kk = idx & 255;
;                     const float cv = cd < 16 ? cp[cd * D + kc * 256 + kk] : cs[(cd - 16) * D + kc * 256 + kk];
;                     sT[kk * 52 + cd] = cv * sigmoidf_(cv); }
;                 __syncthreads();
.Lmod_kc:
	s_barrier
	s_waitcnt vmcnt(26)
	v_mul_f32_e32 v210, 0xbfb8aa3b, v80
	v_mul_f32_e32 v211, 0xbfb8aa3b, v81
	v_mul_f32_e32 v212, 0xbfb8aa3b, v82
	v_mul_f32_e32 v213, 0xbfb8aa3b, v83
	v_exp_f32_e32 v210, v210
	v_exp_f32_e32 v211, v211
	v_exp_f32_e32 v212, v212
	v_exp_f32_e32 v213, v213
	v_add_f32_e32 v210, 1.0, v210
	v_add_f32_e32 v211, 1.0, v211
	v_add_f32_e32 v212, 1.0, v212
	v_add_f32_e32 v213, 1.0, v213
	v_rcp_f32_e32 v210, v210
	v_rcp_f32_e32 v211, v211
	v_rcp_f32_e32 v212, v212
	v_rcp_f32_e32 v213, v213
	v_mul_f32_e32 v210, v80, v210
	v_mul_f32_e32 v211, v81, v211
	v_mul_f32_e32 v212, v82, v212
	v_mul_f32_e32 v213, v83, v213
	ds_write_b32 v77, v210 offset:0
	ds_write_b32 v77, v211 offset:8
	ds_write_b32 v77, v212 offset:16
	ds_write_b32 v77, v213 offset:24
	v_mul_f32_e32 v214, 0xbfb8aa3b, v84
	v_mul_f32_e32 v215, 0xbfb8aa3b, v85
	v_mul_f32_e32 v216, 0xbfb8aa3b, v86
	v_mul_f32_e32 v217, 0xbfb8aa3b, v87
	v_exp_f32_e32 v214, v214
	v_exp_f32_e32 v215, v215
	v_exp_f32_e32 v216, v216
	v_exp_f32_e32 v217, v217
	v_add_f32_e32 v214, 1.0, v214
	v_add_f32_e32 v215, 1.0, v215
	v_add_f32_e32 v216, 1.0, v216
	v_add_f32_e32 v217, 1.0, v217
	v_rcp_f32_e32 v214, v214
	v_rcp_f32_e32 v215, v215
	v_rcp_f32_e32 v216, v216
	v_rcp_f32_e32 v217, v217
	v_mul_f32_e32 v214, v84, v214
	v_mul_f32_e32 v215, v85, v215
	v_mul_f32_e32 v216, v86, v216
	v_mul_f32_e32 v217, v87, v217
	ds_write_b32 v77, v214 offset:32
	ds_write_b32 v77, v215 offset:40
	ds_write_b32 v77, v216 offset:48
	ds_write_b32 v77, v217 offset:56
	v_mul_f32_e32 v218, 0xbfb8aa3b, v88
	v_mul_f32_e32 v219, 0xbfb8aa3b, v89
	v_mul_f32_e32 v220, 0xbfb8aa3b, v90
	v_mul_f32_e32 v221, 0xbfb8aa3b, v91
	v_exp_f32_e32 v218, v218
	v_exp_f32_e32 v219, v219
	v_exp_f32_e32 v220, v220
	v_exp_f32_e32 v221, v221
	v_add_f32_e32 v218, 1.0, v218
	v_add_f32_e32 v219, 1.0, v219
	v_add_f32_e32 v220, 1.0, v220
	v_add_f32_e32 v221, 1.0, v221
	v_rcp_f32_e32 v218, v218
	v_rcp_f32_e32 v219, v219
	v_rcp_f32_e32 v220, v220
	v_rcp_f32_e32 v221, v221
	v_mul_f32_e32 v218, v88, v218
	v_mul_f32_e32 v219, v89, v219
	v_mul_f32_e32 v220, v90, v220
	v_mul_f32_e32 v221, v91, v221
	ds_write_b32 v77, v218 offset:64
	ds_write_b32 v77, v219 offset:72
	ds_write_b32 v77, v220 offset:80
	ds_write_b32 v77, v221 offset:88
	v_mul_f32_e32 v222, 0xbfb8aa3b, v92
	v_mul_f32_e32 v223, 0xbfb8aa3b, v93
	v_mul_f32_e32 v224, 0xbfb8aa3b, v94
	v_mul_f32_e32 v225, 0xbfb8aa3b, v95
	v_exp_f32_e32 v222, v222
	v_exp_f32_e32 v223, v223
	v_exp_f32_e32 v224, v224
	v_exp_f32_e32 v225, v225
	v_add_f32_e32 v222, 1.0, v222
	v_add_f32_e32 v223, 1.0, v223
	v_add_f32_e32 v224, 1.0, v224
	v_add_f32_e32 v225, 1.0, v225
	v_rcp_f32_e32 v222, v222
	v_rcp_f32_e32 v223, v223
	v_rcp_f32_e32 v224, v224
	v_rcp_f32_e32 v225, v225
	v_mul_f32_e32 v222, v92, v222
	v_mul_f32_e32 v223, v93, v223
	v_mul_f32_e32 v224, v94, v224
	v_mul_f32_e32 v225, v95, v225
	ds_write_b32 v77, v222 offset:96
	ds_write_b32 v77, v223 offset:104
	ds_write_b32 v77, v224 offset:112
	ds_write_b32 v77, v225 offset:120
	v_mul_f32_e32 v226, 0xbfb8aa3b, v96
	v_mul_f32_e32 v227, 0xbfb8aa3b, v97
	v_mul_f32_e32 v228, 0xbfb8aa3b, v98
	v_mul_f32_e32 v229, 0xbfb8aa3b, v99
	v_exp_f32_e32 v226, v226
	v_exp_f32_e32 v227, v227
	v_exp_f32_e32 v228, v228
	v_exp_f32_e32 v229, v229
	v_add_f32_e32 v226, 1.0, v226
	v_add_f32_e32 v227, 1.0, v227
	v_add_f32_e32 v228, 1.0, v228
	v_add_f32_e32 v229, 1.0, v229
	v_rcp_f32_e32 v226, v226
	v_rcp_f32_e32 v227, v227
	v_rcp_f32_e32 v228, v228
	v_rcp_f32_e32 v229, v229
	v_mul_f32_e32 v226, v96, v226
	v_mul_f32_e32 v227, v97, v227
	v_mul_f32_e32 v228, v98, v228
	v_mul_f32_e32 v229, v99, v229
	ds_write_b32 v77, v226 offset:128
	ds_write_b32 v77, v227 offset:136
	ds_write_b32 v77, v228 offset:144
	ds_write_b32 v77, v229 offset:152
	v_mul_f32_e32 v230, 0xbfb8aa3b, v100
	v_mul_f32_e32 v231, 0xbfb8aa3b, v101
	v_mul_f32_e32 v232, 0xbfb8aa3b, v102
	v_mul_f32_e32 v233, 0xbfb8aa3b, v103
	v_exp_f32_e32 v230, v230
	v_exp_f32_e32 v231, v231
	v_exp_f32_e32 v232, v232
	v_exp_f32_e32 v233, v233
	v_add_f32_e32 v230, 1.0, v230
	v_add_f32_e32 v231, 1.0, v231
	v_add_f32_e32 v232, 1.0, v232
	v_add_f32_e32 v233, 1.0, v233
	v_rcp_f32_e32 v230, v230
	v_rcp_f32_e32 v231, v231
	v_rcp_f32_e32 v232, v232
	v_rcp_f32_e32 v233, v233
	v_mul_f32_e32 v230, v100, v230
	v_mul_f32_e32 v231, v101, v231
	v_mul_f32_e32 v232, v102, v232
	v_mul_f32_e32 v233, v103, v233
	ds_write_b32 v77, v230 offset:160
	ds_write_b32 v77, v231 offset:168
	ds_write_b32 v77, v232 offset:176
	ds_write_b32 v77, v233 offset:184
	s_waitcnt lgkmcnt(0)
	s_barrier
; #define LAS __attribute__((address_space(3)))
; __device__ __forceinline__ float sigmoidf_(float x) { return 1.0f / (1.0f + __expf(-x)); }
; __device__ __forceinline__ void phase_prologue(const Frame& F) {
;     ...
;                 for (int i = 0; i < 24; ++i) { const int idx = tid + 512 * i, cd = idx >> 8, kk = idx & 255;
;                     const float cv = cd < 16 ? cp[cd * D + kc * 256 + kk] : cs[(cd - 16) * D + kc * 256 + kk];
;                     sT[kk * 52 + cd] = cv * sigmoidf_(cv); }
;                 __syncthreads();
;                 if (tid < 480) {
; #pragma unroll 2
;                     for (int kk = kl; kk < 256; kk += 10) {
;                         const f32x4 w4 = *(const f32x4*)(wada + (size_t)(kc * 256 + kk) * MODW + 48 * cb + 4 * cgp);
;                         const f32x2 w01 = (f32x2){w4[0], w4[1]}, w23 = (f32x2){w4[2], w4[3]};
;                         const LAS f32x4* sp = (const LAS f32x4*)(sT + kk * 52 + 12 * cdg);
;                         const f32x4 s0 = sp[0], s1 = sp[1], s2 = sp[2];
; #pragma unroll
;                         for (int c = 0; c < 4; ++c) {
;                             acc[c][0] = __builtin_elementwise_fma((f32x2){s0[c], s0[c]}, w01, acc[c][0]); acc[c][1] = __builtin_elementwise_fma((f32x2){s0[c], s0[c]}, w23, acc[c][1]);
;                             acc[4 + c][0] = __builtin_elementwise_fma((f32x2){s1[c], s1[c]}, w01, acc[4 + c][0]); acc[4 + c][1] = __builtin_elementwise_fma((f32x2){s1[c], s1[c]}, w23, acc[4 + c][1]);
;                             acc[8 + c][0] = __builtin_elementwise_fma((f32x2){s2[c], s2[c]}, w01, acc[8 + c][0]); acc[8 + c][1] = __builtin_elementwise_fma((f32x2){s2[c], s2[c]}, w23, acc[8 + c][1]); }
;                     }
	s_lshl_b32 s31, s30, 8
	s_add_i32 s6, s30, 1
	s_lshl_b32 s6, s6, 10
	s_add_u32 s8, s48, s6
	s_addc_u32 s9, s49, 0
	global_load_dword v80, v76, s[8:9]
	s_add_u32 s8, s8, 0x4000
	s_addc_u32 s9, s9, 0
	global_load_dword v81, v76, s[8:9]
	s_add_u32 s8, s8, 0x4000
	s_addc_u32 s9, s9, 0
	global_load_dword v82, v76, s[8:9]
	s_add_u32 s8, s8, 0x4000
	s_addc_u32 s9, s9, 0
	global_load_dword v83, v76, s[8:9]
	s_add_u32 s8, s8, 0x4000
	s_addc_u32 s9, s9, 0
	global_load_dword v84, v76, s[8:9]
	s_add_u32 s8, s8, 0x4000
	s_addc_u32 s9, s9, 0
	global_load_dword v85, v76, s[8:9]
	s_add_u32 s8, s8, 0x4000
	s_addc_u32 s9, s9, 0
	global_load_dword v86, v76, s[8:9]
	s_add_u32 s8, s8, 0x4000
	s_addc_u32 s9, s9, 0
	global_load_dword v87, v76, s[8:9]
	s_add_u32 s8, s50, s6
	s_addc_u32 s9, s51, 0
	global_load_dword v88, v76, s[8:9]
	s_add_u32 s8, s8, 0x4000
	s_addc_u32 s9, s9, 0
	global_load_dword v89, v76, s[8:9]
	s_add_u32 s8, s8, 0x4000
	s_addc_u32 s9, s9, 0
	global_load_dword v90, v76, s[8:9]
	s_add_u32 s8, s8, 0x4000
	s_addc_u32 s9, s9, 0
	global_load_dword v91, v76, s[8:9]
	s_add_u32 s8, s8, 0x4000
	s_addc_u32 s9, s9, 0
	global_load_dword v92, v76, s[8:9]
	s_add_u32 s8, s8, 0x4000
	s_addc_u32 s9, s9, 0
	global_load_dword v93, v76, s[8:9]
	s_add_u32 s8, s8, 0x4000
	s_addc_u32 s9, s9, 0
	global_load_dword v94, v76, s[8:9]
	s_add_u32 s8, s8, 0x4000
	s_addc_u32 s9, s9, 0
	global_load_dword v95, v76, s[8:9]
	s_add_u32 s8, s8, 0x4000
	s_addc_u32 s9, s9, 0
	global_load_dword v96, v76, s[8:9]
	s_add_u32 s8, s8, 0x4000
	s_addc_u32 s9, s9, 0
	global_load_dword v97, v76, s[8:9]
	s_add_u32 s8, s8, 0x4000
	s_addc_u32 s9, s9, 0
	global_load_dword v98, v76, s[8:9]
	s_add_u32 s8, s8, 0x4000
	s_addc_u32 s9, s9, 0
	global_load_dword v99, v76, s[8:9]
	s_add_u32 s8, s8, 0x4000
	s_addc_u32 s9, s9, 0
	global_load_dword v100, v76, s[8:9]
	s_add_u32 s8, s8, 0x4000
	s_addc_u32 s9, s9, 0
	global_load_dword v101, v76, s[8:9]
	s_add_u32 s8, s8, 0x4000
	s_addc_u32 s9, s9, 0
	global_load_dword v102, v76, s[8:9]
	s_add_u32 s8, s8, 0x4000
	s_addc_u32 s9, s9, 0
	global_load_dword v103, v76, s[8:9]
	s_and_saveexec_b64 s[10:11], s[0:1]
	s_add_i32 s7, s31, 0x100
	v_or_b32_e32 v78, s7, v1
	v_mad_u64_u32 v[234:235], s[6:7], v78, s24, v[58:59]
	ds_read_b128 v[210:213], v74 offset:0
	ds_read_b128 v[214:217], v74 offset:16
	ds_read_b128 v[218:221], v74 offset:32
	ds_read_b128 v[222:225], v74 offset:2080
	ds_read_b128 v[226:229], v74 offset:2096
	ds_read_b128 v[230:233], v74 offset:2112
	s_waitcnt vmcnt(49) lgkmcnt(3)
	v_pk_fma_f32 v[46:47], v[210:211], v[104:105], v[46:47] op_sel_hi:[0,1,1]
	v_pk_fma_f32 v[48:49], v[210:211], v[106:107], v[48:49] op_sel_hi:[0,1,1]
	v_pk_fma_f32 v[34:35], v[214:215], v[104:105], v[34:35] op_sel_hi:[0,1,1]
	v_pk_fma_f32 v[36:37], v[214:215], v[106:107], v[36:37] op_sel_hi:[0,1,1]
	v_pk_fma_f32 v[14:15], v[218:219], v[104:105], v[14:15] op_sel_hi:[0,1,1]
	v_pk_fma_f32 v[16:17], v[218:219], v[106:107], v[16:17] op_sel_hi:[0,1,1]
	v_pk_fma_f32 v[42:43], v[210:211], v[104:105], v[42:43] op_sel:[1,0,0]
	v_pk_fma_f32 v[44:45], v[210:211], v[106:107], v[44:45] op_sel:[1,0,0]
	v_pk_fma_f32 v[26:27], v[214:215], v[104:105], v[26:27] op_sel:[1,0,0]
	v_pk_fma_f32 v[28:29], v[214:215], v[106:107], v[28:29] op_sel:[1,0,0]
	v_pk_fma_f32 v[10:11], v[218:219], v[104:105], v[10:11] op_sel:[1,0,0]
	v_pk_fma_f32 v[12:13], v[218:219], v[106:107], v[12:13] op_sel:[1,0,0]
	v_pk_fma_f32 v[38:39], v[212:213], v[104:105], v[38:39] op_sel_hi:[0,1,1]
	v_pk_fma_f32 v[40:41], v[212:213], v[106:107], v[40:41] op_sel_hi:[0,1,1]
	v_pk_fma_f32 v[22:23], v[216:217], v[104:105], v[22:23] op_sel_hi:[0,1,1]
	v_pk_fma_f32 v[24:25], v[216:217], v[106:107], v[24:25] op_sel_hi:[0,1,1]
	v_pk_fma_f32 v[6:7], v[220:221], v[104:105], v[6:7] op_sel_hi:[0,1,1]
	v_pk_fma_f32 v[8:9], v[220:221], v[106:107], v[8:9] op_sel_hi:[0,1,1]
	v_pk_fma_f32 v[30:31], v[212:213], v[104:105], v[30:31] op_sel:[1,0,0]
	v_pk_fma_f32 v[32:33], v[212:213], v[106:107], v[32:33] op_sel:[1,0,0]
	v_pk_fma_f32 v[18:19], v[216:217], v[104:105], v[18:19] op_sel:[1,0,0]
	v_pk_fma_f32 v[20:21], v[216:217], v[106:107], v[20:21] op_sel:[1,0,0]
	v_pk_fma_f32 v[2:3], v[220:221], v[104:105], v[2:3] op_sel:[1,0,0]
	v_pk_fma_f32 v[4:5], v[220:221], v[106:107], v[4:5] op_sel:[1,0,0]
	global_load_dwordx4 v[104:107], v[234:235], off
	v_lshl_add_u64 v[234:235], v[234:235], 0, s[12:13]
	ds_read_b128 v[210:213], v74 offset:4160
	ds_read_b128 v[214:217], v74 offset:4176
	ds_read_b128 v[218:221], v74 offset:4192
	s_waitcnt vmcnt(49) lgkmcnt(3)
	v_pk_fma_f32 v[46:47], v[222:223], v[108:109], v[46:47] op_sel_hi:[0,1,1]
	v_pk_fma_f32 v[48:49], v[222:223], v[110:111], v[48:49] op_sel_hi:[0,1,1]
	v_pk_fma_f32 v[34:35], v[226:227], v[108:109], v[34:35] op_sel_hi:[0,1,1]
	v_pk_fma_f32 v[36:37], v[226:227], v[110:111], v[36:37] op_sel_hi:[0,1,1]
	v_pk_fma_f32 v[14:15], v[230:231], v[108:109], v[14:15] op_sel_hi:[0,1,1]
	v_pk_fma_f32 v[16:17], v[230:231], v[110:111], v[16:17] op_sel_hi:[0,1,1]
	v_pk_fma_f32 v[42:43], v[222:223], v[108:109], v[42:43] op_sel:[1,0,0]
	v_pk_fma_f32 v[44:45], v[222:223], v[110:111], v[44:45] op_sel:[1,0,0]
	v_pk_fma_f32 v[26:27], v[226:227], v[108:109], v[26:27] op_sel:[1,0,0]
	v_pk_fma_f32 v[28:29], v[226:227], v[110:111], v[28:29] op_sel:[1,0,0]
	v_pk_fma_f32 v[10:11], v[230:231], v[108:109], v[10:11] op_sel:[1,0,0]
	v_pk_fma_f32 v[12:13], v[230:231], v[110:111], v[12:13] op_sel:[1,0,0]
	v_pk_fma_f32 v[38:39], v[224:225], v[108:109], v[38:39] op_sel_hi:[0,1,1]
	v_pk_fma_f32 v[40:41], v[224:225], v[110:111], v[40:41] op_sel_hi:[0,1,1]
	v_pk_fma_f32 v[22:23], v[228:229], v[108:109], v[22:23] op_sel_hi:[0,1,1]
	v_pk_fma_f32 v[24:25], v[228:229], v[110:111], v[24:25] op_sel_hi:[0,1,1]
	v_pk_fma_f32 v[6:7], v[232:233], v[108:109], v[6:7] op_sel_hi:[0,1,1]
	v_pk_fma_f32 v[8:9], v[232:233], v[110:111], v[8:9] op_sel_hi:[0,1,1]
	v_pk_fma_f32 v[30:31], v[224:225], v[108:109], v[30:31] op_sel:[1,0,0]
	v_pk_fma_f32 v[32:33], v[224:225], v[110:111], v[32:33] op_sel:[1,0,0]
	v_pk_fma_f32 v[18:19], v[228:229], v[108:109], v[18:19] op_sel:[1,0,0]
	v_pk_fma_f32 v[20:21], v[228:229], v[110:111], v[20:21] op_sel:[1,0,0]
	v_pk_fma_f32 v[2:3], v[232:233], v[108:109], v[2:3] op_sel:[1,0,0]
	v_pk_fma_f32 v[4:5], v[232:233], v[110:111], v[4:5] op_sel:[1,0,0]
	global_load_dwordx4 v[108:111], v[234:235], off
	v_lshl_add_u64 v[234:235], v[234:235], 0, s[12:13]
	ds_read_b128 v[222:225], v74 offset:6240
	ds_read_b128 v[226:229], v74 offset:6256
	ds_read_b128 v[230:233], v74 offset:6272
	s_waitcnt vmcnt(49) lgkmcnt(3)
; #define LAS __attribute__((address_space(3)))
; __device__ __forceinline__ void phase_prologue(const Frame& F) {
;     ...
;                 if (tid < 480) {
; #pragma unroll 2
;                     for (int kk = kl; kk < 256; kk += 10) {
;                         const f32x4 w4 = *(const f32x4*)(wada + (size_t)(kc * 256 + kk) * MODW + 48 * cb + 4 * cgp);
;                         const f32x2 w01 = (f32x2){w4[0], w4[1]}, w23 = (f32x2){w4[2], w4[3]};
;                         const LAS f32x4* sp = (const LAS f32x4*)(sT + kk * 52 + 12 * cdg);
;                         const f32x4 s0 = sp[0], s1 = sp[1], s2 = sp[2];
; #pragma unroll
;                         for (int c = 0; c < 4; ++c) {
;                             acc[c][0] = __builtin_elementwise_fma((f32x2){s0[c], s0[c]}, w01, acc[c][0]); acc[c][1] = __builtin_elementwise_fma((f32x2){s0[c], s0[c]}, w23, acc[c][1]);
;                             acc[4 + c][0] = __builtin_elementwise_fma((f32x2){s1[c], s1[c]}, w01, acc[4 + c][0]); acc[4 + c][1] = __builtin_elementwise_fma((f32x2){s1[c], s1[c]}, w23, acc[4 + c][1]);
;                             acc[8 + c][0] = __builtin_elementwise_fma((f32x2){s2[c], s2[c]}, w01, acc[8 + c][0]); acc[8 + c][1] = __builtin_elementwise_fma((f32x2){s2[c], s2[c]}, w23, acc[8 + c][1]); }
;                     }
	v_pk_fma_f32 v[46:47], v[210:211], v[112:113], v[46:47] op_sel_hi:[0,1,1]
	v_pk_fma_f32 v[48:49], v[210:211], v[114:115], v[48:49] op_sel_hi:[0,1,1]
	v_pk_fma_f32 v[34:35], v[214:215], v[112:113], v[34:35] op_sel_hi:[0,1,1]
	v_pk_fma_f32 v[36:37], v[214:215], v[114:115], v[36:37] op_sel_hi:[0,1,1]
	v_pk_fma_f32 v[14:15], v[218:219], v[112:113], v[14:15] op_sel_hi:[0,1,1]
	v_pk_fma_f32 v[16:17], v[218:219], v[114:115], v[16:17] op_sel_hi:[0,1,1]
	v_pk_fma_f32 v[42:43], v[210:211], v[112:113], v[42:43] op_sel:[1,0,0]
	v_pk_fma_f32 v[44:45], v[210:211], v[114:115], v[44:45] op_sel:[1,0,0]
	v_pk_fma_f32 v[26:27], v[214:215], v[112:113], v[26:27] op_sel:[1,0,0]
	v_pk_fma_f32 v[28:29], v[214:215], v[114:115], v[28:29] op_sel:[1,0,0]
	v_pk_fma_f32 v[10:11], v[218:219], v[112:113], v[10:11] op_sel:[1,0,0]
	v_pk_fma_f32 v[12:13], v[218:219], v[114:115], v[12:13] op_sel:[1,0,0]
	v_pk_fma_f32 v[38:39], v[212:213], v[112:113], v[38:39] op_sel_hi:[0,1,1]
	v_pk_fma_f32 v[40:41], v[212:213], v[114:115], v[40:41] op_sel_hi:[0,1,1]
	v_pk_fma_f32 v[22:23], v[216:217], v[112:113], v[22:23] op_sel_hi:[0,1,1]
	v_pk_fma_f32 v[24:25], v[216:217], v[114:115], v[24:25] op_sel_hi:[0,1,1]
	v_pk_fma_f32 v[6:7], v[220:221], v[112:113], v[6:7] op_sel_hi:[0,1,1]
	v_pk_fma_f32 v[8:9], v[220:221], v[114:115], v[8:9] op_sel_hi:[0,1,1]
	v_pk_fma_f32 v[30:31], v[212:213], v[112:113], v[30:31] op_sel:[1,0,0]
	v_pk_fma_f32 v[32:33], v[212:213], v[114:115], v[32:33] op_sel:[1,0,0]
	v_pk_fma_f32 v[18:19], v[216:217], v[112:113], v[18:19] op_sel:[1,0,0]
	v_pk_fma_f32 v[20:21], v[216:217], v[114:115], v[20:21] op_sel:[1,0,0]
	v_pk_fma_f32 v[2:3], v[220:221], v[112:113], v[2:3] op_sel:[1,0,0]
	v_pk_fma_f32 v[4:5], v[220:221], v[114:115], v[4:5] op_sel:[1,0,0]
	global_load_dwordx4 v[112:115], v[234:235], off
	v_lshl_add_u64 v[234:235], v[234:235], 0, s[12:13]
	ds_read_b128 v[210:213], v74 offset:8320
	ds_read_b128 v[214:217], v74 offset:8336
	ds_read_b128 v[218:221], v74 offset:8352
	s_waitcnt vmcnt(49) lgkmcnt(3)
	v_pk_fma_f32 v[46:47], v[222:223], v[116:117], v[46:47] op_sel_hi:[0,1,1]
	v_pk_fma_f32 v[48:49], v[222:223], v[118:119], v[48:49] op_sel_hi:[0,1,1]
	v_pk_fma_f32 v[34:35], v[226:227], v[116:117], v[34:35] op_sel_hi:[0,1,1]
	v_pk_fma_f32 v[36:37], v[226:227], v[118:119], v[36:37] op_sel_hi:[0,1,1]
	v_pk_fma_f32 v[14:15], v[230:231], v[116:117], v[14:15] op_sel_hi:[0,1,1]
	v_pk_fma_f32 v[16:17], v[230:231], v[118:119], v[16:17] op_sel_hi:[0,1,1]
	v_pk_fma_f32 v[42:43], v[222:223], v[116:117], v[42:43] op_sel:[1,0,0]
	v_pk_fma_f32 v[44:45], v[222:223], v[118:119], v[44:45] op_sel:[1,0,0]
	v_pk_fma_f32 v[26:27], v[226:227], v[116:117], v[26:27] op_sel:[1,0,0]
	v_pk_fma_f32 v[28:29], v[226:227], v[118:119], v[28:29] op_sel:[1,0,0]
	v_pk_fma_f32 v[10:11], v[230:231], v[116:117], v[10:11] op_sel:[1,0,0]
	v_pk_fma_f32 v[12:13], v[230:231], v[118:119], v[12:13] op_sel:[1,0,0]
	v_pk_fma_f32 v[38:39], v[224:225], v[116:117], v[38:39] op_sel_hi:[0,1,1]
	v_pk_fma_f32 v[40:41], v[224:225], v[118:119], v[40:41] op_sel_hi:[0,1,1]
	v_pk_fma_f32 v[22:23], v[228:229], v[116:117], v[22:23] op_sel_hi:[0,1,1]
	v_pk_fma_f32 v[24:25], v[228:229], v[118:119], v[24:25] op_sel_hi:[0,1,1]
	v_pk_fma_f32 v[6:7], v[232:233], v[116:117], v[6:7] op_sel_hi:[0,1,1]
	v_pk_fma_f32 v[8:9], v[232:233], v[118:119], v[8:9] op_sel_hi:[0,1,1]
	v_pk_fma_f32 v[30:31], v[224:225], v[116:117], v[30:31] op_sel:[1,0,0]
	v_pk_fma_f32 v[32:33], v[224:225], v[118:119], v[32:33] op_sel:[1,0,0]
	v_pk_fma_f32 v[18:19], v[228:229], v[116:117], v[18:19] op_sel:[1,0,0]
	v_pk_fma_f32 v[20:21], v[228:229], v[118:119], v[20:21] op_sel:[1,0,0]
	v_pk_fma_f32 v[2:3], v[232:233], v[116:117], v[2:3] op_sel:[1,0,0]
	v_pk_fma_f32 v[4:5], v[232:233], v[118:119], v[4:5] op_sel:[1,0,0]
	global_load_dwordx4 v[116:119], v[234:235], off
	v_lshl_add_u64 v[234:235], v[234:235], 0, s[12:13]
	ds_read_b128 v[222:225], v74 offset:10400
	ds_read_b128 v[226:229], v74 offset:10416
	ds_read_b128 v[230:233], v74 offset:10432
	s_waitcnt vmcnt(49) lgkmcnt(3)
	v_pk_fma_f32 v[46:47], v[210:211], v[120:121], v[46:47] op_sel_hi:[0,1,1]
	v_pk_fma_f32 v[48:49], v[210:211], v[122:123], v[48:49] op_sel_hi:[0,1,1]
	v_pk_fma_f32 v[34:35], v[214:215], v[120:121], v[34:35] op_sel_hi:[0,1,1]
	v_pk_fma_f32 v[36:37], v[214:215], v[122:123], v[36:37] op_sel_hi:[0,1,1]
	v_pk_fma_f32 v[14:15], v[218:219], v[120:121], v[14:15] op_sel_hi:[0,1,1]
	v_pk_fma_f32 v[16:17], v[218:219], v[122:123], v[16:17] op_sel_hi:[0,1,1]
	v_pk_fma_f32 v[42:43], v[210:211], v[120:121], v[42:43] op_sel:[1,0,0]
	v_pk_fma_f32 v[44:45], v[210:211], v[122:123], v[44:45] op_sel:[1,0,0]
	v_pk_fma_f32 v[26:27], v[214:215], v[120:121], v[26:27] op_sel:[1,0,0]
	v_pk_fma_f32 v[28:29], v[214:215], v[122:123], v[28:29] op_sel:[1,0,0]
	v_pk_fma_f32 v[10:11], v[218:219], v[120:121], v[10:11] op_sel:[1,0,0]
	v_pk_fma_f32 v[12:13], v[218:219], v[122:123], v[12:13] op_sel:[1,0,0]
	v_pk_fma_f32 v[38:39], v[212:213], v[120:121], v[38:39] op_sel_hi:[0,1,1]
	v_pk_fma_f32 v[40:41], v[212:213], v[122:123], v[40:41] op_sel_hi:[0,1,1]
	v_pk_fma_f32 v[22:23], v[216:217], v[120:121], v[22:23] op_sel_hi:[0,1,1]
	v_pk_fma_f32 v[24:25], v[216:217], v[122:123], v[24:25] op_sel_hi:[0,1,1]
	v_pk_fma_f32 v[6:7], v[220:221], v[120:121], v[6:7] op_sel_hi:[0,1,1]
	v_pk_fma_f32 v[8:9], v[220:221], v[122:123], v[8:9] op_sel_hi:[0,1,1]
	v_pk_fma_f32 v[30:31], v[212:213], v[120:121], v[30:31] op_sel:[1,0,0]
	v_pk_fma_f32 v[32:33], v[212:213], v[122:123], v[32:33] op_sel:[1,0,0]
	v_pk_fma_f32 v[18:19], v[216:217], v[120:121], v[18:19] op_sel:[1,0,0]
	v_pk_fma_f32 v[20:21], v[216:217], v[122:123], v[20:21] op_sel:[1,0,0]
	v_pk_fma_f32 v[2:3], v[220:221], v[120:121], v[2:3] op_sel:[1,0,0]
	v_pk_fma_f32 v[4:5], v[220:221], v[122:123], v[4:5] op_sel:[1,0,0]
	global_load_dwordx4 v[120:123], v[234:235], off
	v_lshl_add_u64 v[234:235], v[234:235], 0, s[12:13]
	ds_read_b128 v[210:213], v74 offset:12480
	ds_read_b128 v[214:217], v74 offset:12496
	ds_read_b128 v[218:221], v74 offset:12512
	s_waitcnt vmcnt(49) lgkmcnt(3)
; #define LAS __attribute__((address_space(3)))
; __device__ __forceinline__ void phase_prologue(const Frame& F) {
;     ...
;                 if (tid < 480) {
; #pragma unroll 2
;                     for (int kk = kl; kk < 256; kk += 10) {
;                         const f32x4 w4 = *(const f32x4*)(wada + (size_t)(kc * 256 + kk) * MODW + 48 * cb + 4 * cgp);
;                         const f32x2 w01 = (f32x2){w4[0], w4[1]}, w23 = (f32x2){w4[2], w4[3]};
;                         const LAS f32x4* sp = (const LAS f32x4*)(sT + kk * 52 + 12 * cdg);
;                         const f32x4 s0 = sp[0], s1 = sp[1], s2 = sp[2];
; #pragma unroll
;                         for (int c = 0; c < 4; ++c) {
;                             acc[c][0] = __builtin_elementwise_fma((f32x2){s0[c], s0[c]}, w01, acc[c][0]); acc[c][1] = __builtin_elementwise_fma((f32x2){s0[c], s0[c]}, w23, acc[c][1]);
;                             acc[4 + c][0] = __builtin_elementwise_fma((f32x2){s1[c], s1[c]}, w01, acc[4 + c][0]); acc[4 + c][1] = __builtin_elementwise_fma((f32x2){s1[c], s1[c]}, w23, acc[4 + c][1]);
;                             acc[8 + c][0] = __builtin_elementwise_fma((f32x2){s2[c], s2[c]}, w01, acc[8 + c][0]); acc[8 + c][1] = __builtin_elementwise_fma((f32x2){s2[c], s2[c]}, w23, acc[8 + c][1]); }
;                     }
	v_pk_fma_f32 v[46:47], v[222:223], v[124:125], v[46:47] op_sel_hi:[0,1,1]
	v_pk_fma_f32 v[48:49], v[222:223], v[126:127], v[48:49] op_sel_hi:[0,1,1]
	v_pk_fma_f32 v[34:35], v[226:227], v[124:125], v[34:35] op_sel_hi:[0,1,1]
	v_pk_fma_f32 v[36:37], v[226:227], v[126:127], v[36:37] op_sel_hi:[0,1,1]
	v_pk_fma_f32 v[14:15], v[230:231], v[124:125], v[14:15] op_sel_hi:[0,1,1]
	v_pk_fma_f32 v[16:17], v[230:231], v[126:127], v[16:17] op_sel_hi:[0,1,1]
	v_pk_fma_f32 v[42:43], v[222:223], v[124:125], v[42:43] op_sel:[1,0,0]
	v_pk_fma_f32 v[44:45], v[222:223], v[126:127], v[44:45] op_sel:[1,0,0]
	v_pk_fma_f32 v[26:27], v[226:227], v[124:125], v[26:27] op_sel:[1,0,0]
	v_pk_fma_f32 v[28:29], v[226:227], v[126:127], v[28:29] op_sel:[1,0,0]
	v_pk_fma_f32 v[10:11], v[230:231], v[124:125], v[10:11] op_sel:[1,0,0]
	v_pk_fma_f32 v[12:13], v[230:231], v[126:127], v[12:13] op_sel:[1,0,0]
	v_pk_fma_f32 v[38:39], v[224:225], v[124:125], v[38:39] op_sel_hi:[0,1,1]
	v_pk_fma_f32 v[40:41], v[224:225], v[126:127], v[40:41] op_sel_hi:[0,1,1]
	v_pk_fma_f32 v[22:23], v[228:229], v[124:125], v[22:23] op_sel_hi:[0,1,1]
	v_pk_fma_f32 v[24:25], v[228:229], v[126:127], v[24:25] op_sel_hi:[0,1,1]
	v_pk_fma_f32 v[6:7], v[232:233], v[124:125], v[6:7] op_sel_hi:[0,1,1]
	v_pk_fma_f32 v[8:9], v[232:233], v[126:127], v[8:9] op_sel_hi:[0,1,1]
	v_pk_fma_f32 v[30:31], v[224:225], v[124:125], v[30:31] op_sel:[1,0,0]
	v_pk_fma_f32 v[32:33], v[224:225], v[126:127], v[32:33] op_sel:[1,0,0]
	v_pk_fma_f32 v[18:19], v[228:229], v[124:125], v[18:19] op_sel:[1,0,0]
	v_pk_fma_f32 v[20:21], v[228:229], v[126:127], v[20:21] op_sel:[1,0,0]
	v_pk_fma_f32 v[2:3], v[232:233], v[124:125], v[2:3] op_sel:[1,0,0]
	v_pk_fma_f32 v[4:5], v[232:233], v[126:127], v[4:5] op_sel:[1,0,0]
	global_load_dwordx4 v[124:127], v[234:235], off
	v_lshl_add_u64 v[234:235], v[234:235], 0, s[12:13]
	ds_read_b128 v[222:225], v74 offset:14560
	ds_read_b128 v[226:229], v74 offset:14576
	ds_read_b128 v[230:233], v74 offset:14592
	s_waitcnt vmcnt(49) lgkmcnt(3)
	v_pk_fma_f32 v[46:47], v[210:211], v[128:129], v[46:47] op_sel_hi:[0,1,1]
	v_pk_fma_f32 v[48:49], v[210:211], v[130:131], v[48:49] op_sel_hi:[0,1,1]
	v_pk_fma_f32 v[34:35], v[214:215], v[128:129], v[34:35] op_sel_hi:[0,1,1]
	v_pk_fma_f32 v[36:37], v[214:215], v[130:131], v[36:37] op_sel_hi:[0,1,1]
	v_pk_fma_f32 v[14:15], v[218:219], v[128:129], v[14:15] op_sel_hi:[0,1,1]
	v_pk_fma_f32 v[16:17], v[218:219], v[130:131], v[16:17] op_sel_hi:[0,1,1]
	v_pk_fma_f32 v[42:43], v[210:211], v[128:129], v[42:43] op_sel:[1,0,0]
	v_pk_fma_f32 v[44:45], v[210:211], v[130:131], v[44:45] op_sel:[1,0,0]
	v_pk_fma_f32 v[26:27], v[214:215], v[128:129], v[26:27] op_sel:[1,0,0]
	v_pk_fma_f32 v[28:29], v[214:215], v[130:131], v[28:29] op_sel:[1,0,0]
	v_pk_fma_f32 v[10:11], v[218:219], v[128:129], v[10:11] op_sel:[1,0,0]
	v_pk_fma_f32 v[12:13], v[218:219], v[130:131], v[12:13] op_sel:[1,0,0]
	v_pk_fma_f32 v[38:39], v[212:213], v[128:129], v[38:39] op_sel_hi:[0,1,1]
	v_pk_fma_f32 v[40:41], v[212:213], v[130:131], v[40:41] op_sel_hi:[0,1,1]
	v_pk_fma_f32 v[22:23], v[216:217], v[128:129], v[22:23] op_sel_hi:[0,1,1]
	v_pk_fma_f32 v[24:25], v[216:217], v[130:131], v[24:25] op_sel_hi:[0,1,1]
	v_pk_fma_f32 v[6:7], v[220:221], v[128:129], v[6:7] op_sel_hi:[0,1,1]
	v_pk_fma_f32 v[8:9], v[220:221], v[130:131], v[8:9] op_sel_hi:[0,1,1]
	v_pk_fma_f32 v[30:31], v[212:213], v[128:129], v[30:31] op_sel:[1,0,0]
	v_pk_fma_f32 v[32:33], v[212:213], v[130:131], v[32:33] op_sel:[1,0,0]
	v_pk_fma_f32 v[18:19], v[216:217], v[128:129], v[18:19] op_sel:[1,0,0]
	v_pk_fma_f32 v[20:21], v[216:217], v[130:131], v[20:21] op_sel:[1,0,0]
	v_pk_fma_f32 v[2:3], v[220:221], v[128:129], v[2:3] op_sel:[1,0,0]
	v_pk_fma_f32 v[4:5], v[220:221], v[130:131], v[4:5] op_sel:[1,0,0]
	global_load_dwordx4 v[128:131], v[234:235], off
	v_lshl_add_u64 v[234:235], v[234:235], 0, s[12:13]
	ds_read_b128 v[210:213], v74 offset:16640
	ds_read_b128 v[214:217], v74 offset:16656
	ds_read_b128 v[218:221], v74 offset:16672
	s_waitcnt vmcnt(49) lgkmcnt(3)
	v_pk_fma_f32 v[46:47], v[222:223], v[132:133], v[46:47] op_sel_hi:[0,1,1]
	v_pk_fma_f32 v[48:49], v[222:223], v[134:135], v[48:49] op_sel_hi:[0,1,1]
	v_pk_fma_f32 v[34:35], v[226:227], v[132:133], v[34:35] op_sel_hi:[0,1,1]
	v_pk_fma_f32 v[36:37], v[226:227], v[134:135], v[36:37] op_sel_hi:[0,1,1]
	v_pk_fma_f32 v[14:15], v[230:231], v[132:133], v[14:15] op_sel_hi:[0,1,1]
	v_pk_fma_f32 v[16:17], v[230:231], v[134:135], v[16:17] op_sel_hi:[0,1,1]
	v_pk_fma_f32 v[42:43], v[222:223], v[132:133], v[42:43] op_sel:[1,0,0]
	v_pk_fma_f32 v[44:45], v[222:223], v[134:135], v[44:45] op_sel:[1,0,0]
	v_pk_fma_f32 v[26:27], v[226:227], v[132:133], v[26:27] op_sel:[1,0,0]
	v_pk_fma_f32 v[28:29], v[226:227], v[134:135], v[28:29] op_sel:[1,0,0]
	v_pk_fma_f32 v[10:11], v[230:231], v[132:133], v[10:11] op_sel:[1,0,0]
	v_pk_fma_f32 v[12:13], v[230:231], v[134:135], v[12:13] op_sel:[1,0,0]
	v_pk_fma_f32 v[38:39], v[224:225], v[132:133], v[38:39] op_sel_hi:[0,1,1]
	v_pk_fma_f32 v[40:41], v[224:225], v[134:135], v[40:41] op_sel_hi:[0,1,1]
	v_pk_fma_f32 v[22:23], v[228:229], v[132:133], v[22:23] op_sel_hi:[0,1,1]
	v_pk_fma_f32 v[24:25], v[228:229], v[134:135], v[24:25] op_sel_hi:[0,1,1]
	v_pk_fma_f32 v[6:7], v[232:233], v[132:133], v[6:7] op_sel_hi:[0,1,1]
	v_pk_fma_f32 v[8:9], v[232:233], v[134:135], v[8:9] op_sel_hi:[0,1,1]
	v_pk_fma_f32 v[30:31], v[224:225], v[132:133], v[30:31] op_sel:[1,0,0]
	v_pk_fma_f32 v[32:33], v[224:225], v[134:135], v[32:33] op_sel:[1,0,0]
	v_pk_fma_f32 v[18:19], v[228:229], v[132:133], v[18:19] op_sel:[1,0,0]
	v_pk_fma_f32 v[20:21], v[228:229], v[134:135], v[20:21] op_sel:[1,0,0]
	v_pk_fma_f32 v[2:3], v[232:233], v[132:133], v[2:3] op_sel:[1,0,0]
	v_pk_fma_f32 v[4:5], v[232:233], v[134:135], v[4:5] op_sel:[1,0,0]
	global_load_dwordx4 v[132:135], v[234:235], off
	v_lshl_add_u64 v[234:235], v[234:235], 0, s[12:13]
	ds_read_b128 v[222:225], v74 offset:18720
	ds_read_b128 v[226:229], v74 offset:18736
	ds_read_b128 v[230:233], v74 offset:18752
	s_waitcnt vmcnt(49) lgkmcnt(3)
; #define LAS __attribute__((address_space(3)))
; __device__ __forceinline__ void phase_prologue(const Frame& F) {
;     ...
;                 if (tid < 480) {
; #pragma unroll 2
;                     for (int kk = kl; kk < 256; kk += 10) {
;                         const f32x4 w4 = *(const f32x4*)(wada + (size_t)(kc * 256 + kk) * MODW + 48 * cb + 4 * cgp);
;                         const f32x2 w01 = (f32x2){w4[0], w4[1]}, w23 = (f32x2){w4[2], w4[3]};
;                         const LAS f32x4* sp = (const LAS f32x4*)(sT + kk * 52 + 12 * cdg);
;                         const f32x4 s0 = sp[0], s1 = sp[1], s2 = sp[2];
; #pragma unroll
;                         for (int c = 0; c < 4; ++c) {
;                             acc[c][0] = __builtin_elementwise_fma((f32x2){s0[c], s0[c]}, w01, acc[c][0]); acc[c][1] = __builtin_elementwise_fma((f32x2){s0[c], s0[c]}, w23, acc[c][1]);
;                             acc[4 + c][0] = __builtin_elementwise_fma((f32x2){s1[c], s1[c]}, w01, acc[4 + c][0]); acc[4 + c][1] = __builtin_elementwise_fma((f32x2){s1[c], s1[c]}, w23, acc[4 + c][1]);
;                             acc[8 + c][0] = __builtin_elementwise_fma((f32x2){s2[c], s2[c]}, w01, acc[8 + c][0]); acc[8 + c][1] = __builtin_elementwise_fma((f32x2){s2[c], s2[c]}, w23, acc[8 + c][1]); }
;                     }
	v_pk_fma_f32 v[46:47], v[210:211], v[136:137], v[46:47] op_sel_hi:[0,1,1]
	v_pk_fma_f32 v[48:49], v[210:211], v[138:139], v[48:49] op_sel_hi:[0,1,1]
	v_pk_fma_f32 v[34:35], v[214:215], v[136:137], v[34:35] op_sel_hi:[0,1,1]
	v_pk_fma_f32 v[36:37], v[214:215], v[138:139], v[36:37] op_sel_hi:[0,1,1]
	v_pk_fma_f32 v[14:15], v[218:219], v[136:137], v[14:15] op_sel_hi:[0,1,1]
	v_pk_fma_f32 v[16:17], v[218:219], v[138:139], v[16:17] op_sel_hi:[0,1,1]
	v_pk_fma_f32 v[42:43], v[210:211], v[136:137], v[42:43] op_sel:[1,0,0]
	v_pk_fma_f32 v[44:45], v[210:211], v[138:139], v[44:45] op_sel:[1,0,0]
	v_pk_fma_f32 v[26:27], v[214:215], v[136:137], v[26:27] op_sel:[1,0,0]
	v_pk_fma_f32 v[28:29], v[214:215], v[138:139], v[28:29] op_sel:[1,0,0]
	v_pk_fma_f32 v[10:11], v[218:219], v[136:137], v[10:11] op_sel:[1,0,0]
	v_pk_fma_f32 v[12:13], v[218:219], v[138:139], v[12:13] op_sel:[1,0,0]
	v_pk_fma_f32 v[38:39], v[212:213], v[136:137], v[38:39] op_sel_hi:[0,1,1]
	v_pk_fma_f32 v[40:41], v[212:213], v[138:139], v[40:41] op_sel_hi:[0,1,1]
	v_pk_fma_f32 v[22:23], v[216:217], v[136:137], v[22:23] op_sel_hi:[0,1,1]
	v_pk_fma_f32 v[24:25], v[216:217], v[138:139], v[24:25] op_sel_hi:[0,1,1]
	v_pk_fma_f32 v[6:7], v[220:221], v[136:137], v[6:7] op_sel_hi:[0,1,1]
	v_pk_fma_f32 v[8:9], v[220:221], v[138:139], v[8:9] op_sel_hi:[0,1,1]
	v_pk_fma_f32 v[30:31], v[212:213], v[136:137], v[30:31] op_sel:[1,0,0]
	v_pk_fma_f32 v[32:33], v[212:213], v[138:139], v[32:33] op_sel:[1,0,0]
	v_pk_fma_f32 v[18:19], v[216:217], v[136:137], v[18:19] op_sel:[1,0,0]
	v_pk_fma_f32 v[20:21], v[216:217], v[138:139], v[20:21] op_sel:[1,0,0]
	v_pk_fma_f32 v[2:3], v[220:221], v[136:137], v[2:3] op_sel:[1,0,0]
	v_pk_fma_f32 v[4:5], v[220:221], v[138:139], v[4:5] op_sel:[1,0,0]
	global_load_dwordx4 v[136:139], v[234:235], off
	v_lshl_add_u64 v[234:235], v[234:235], 0, s[12:13]
	ds_read_b128 v[210:213], v74 offset:20800
	ds_read_b128 v[214:217], v74 offset:20816
	ds_read_b128 v[218:221], v74 offset:20832
	s_waitcnt vmcnt(49) lgkmcnt(3)
	v_pk_fma_f32 v[46:47], v[222:223], v[140:141], v[46:47] op_sel_hi:[0,1,1]
	v_pk_fma_f32 v[48:49], v[222:223], v[142:143], v[48:49] op_sel_hi:[0,1,1]
	v_pk_fma_f32 v[34:35], v[226:227], v[140:141], v[34:35] op_sel_hi:[0,1,1]
	v_pk_fma_f32 v[36:37], v[226:227], v[142:143], v[36:37] op_sel_hi:[0,1,1]
	v_pk_fma_f32 v[14:15], v[230:231], v[140:141], v[14:15] op_sel_hi:[0,1,1]
	v_pk_fma_f32 v[16:17], v[230:231], v[142:143], v[16:17] op_sel_hi:[0,1,1]
	v_pk_fma_f32 v[42:43], v[222:223], v[140:141], v[42:43] op_sel:[1,0,0]
	v_pk_fma_f32 v[44:45], v[222:223], v[142:143], v[44:45] op_sel:[1,0,0]
	v_pk_fma_f32 v[26:27], v[226:227], v[140:141], v[26:27] op_sel:[1,0,0]
	v_pk_fma_f32 v[28:29], v[226:227], v[142:143], v[28:29] op_sel:[1,0,0]
	v_pk_fma_f32 v[10:11], v[230:231], v[140:141], v[10:11] op_sel:[1,0,0]
	v_pk_fma_f32 v[12:13], v[230:231], v[142:143], v[12:13] op_sel:[1,0,0]
	v_pk_fma_f32 v[38:39], v[224:225], v[140:141], v[38:39] op_sel_hi:[0,1,1]
	v_pk_fma_f32 v[40:41], v[224:225], v[142:143], v[40:41] op_sel_hi:[0,1,1]
	v_pk_fma_f32 v[22:23], v[228:229], v[140:141], v[22:23] op_sel_hi:[0,1,1]
	v_pk_fma_f32 v[24:25], v[228:229], v[142:143], v[24:25] op_sel_hi:[0,1,1]
	v_pk_fma_f32 v[6:7], v[232:233], v[140:141], v[6:7] op_sel_hi:[0,1,1]
	v_pk_fma_f32 v[8:9], v[232:233], v[142:143], v[8:9] op_sel_hi:[0,1,1]
	v_pk_fma_f32 v[30:31], v[224:225], v[140:141], v[30:31] op_sel:[1,0,0]
	v_pk_fma_f32 v[32:33], v[224:225], v[142:143], v[32:33] op_sel:[1,0,0]
	v_pk_fma_f32 v[18:19], v[228:229], v[140:141], v[18:19] op_sel:[1,0,0]
	v_pk_fma_f32 v[20:21], v[228:229], v[142:143], v[20:21] op_sel:[1,0,0]
	v_pk_fma_f32 v[2:3], v[232:233], v[140:141], v[2:3] op_sel:[1,0,0]
	v_pk_fma_f32 v[4:5], v[232:233], v[142:143], v[4:5] op_sel:[1,0,0]
	global_load_dwordx4 v[140:143], v[234:235], off
	v_lshl_add_u64 v[234:235], v[234:235], 0, s[12:13]
	ds_read_b128 v[222:225], v74 offset:22880
	ds_read_b128 v[226:229], v74 offset:22896
	ds_read_b128 v[230:233], v74 offset:22912
	s_waitcnt vmcnt(49) lgkmcnt(3)
	v_pk_fma_f32 v[46:47], v[210:211], v[144:145], v[46:47] op_sel_hi:[0,1,1]
	v_pk_fma_f32 v[48:49], v[210:211], v[146:147], v[48:49] op_sel_hi:[0,1,1]
	v_pk_fma_f32 v[34:35], v[214:215], v[144:145], v[34:35] op_sel_hi:[0,1,1]
	v_pk_fma_f32 v[36:37], v[214:215], v[146:147], v[36:37] op_sel_hi:[0,1,1]
	v_pk_fma_f32 v[14:15], v[218:219], v[144:145], v[14:15] op_sel_hi:[0,1,1]
	v_pk_fma_f32 v[16:17], v[218:219], v[146:147], v[16:17] op_sel_hi:[0,1,1]
	v_pk_fma_f32 v[42:43], v[210:211], v[144:145], v[42:43] op_sel:[1,0,0]
	v_pk_fma_f32 v[44:45], v[210:211], v[146:147], v[44:45] op_sel:[1,0,0]
	v_pk_fma_f32 v[26:27], v[214:215], v[144:145], v[26:27] op_sel:[1,0,0]
	v_pk_fma_f32 v[28:29], v[214:215], v[146:147], v[28:29] op_sel:[1,0,0]
	v_pk_fma_f32 v[10:11], v[218:219], v[144:145], v[10:11] op_sel:[1,0,0]
	v_pk_fma_f32 v[12:13], v[218:219], v[146:147], v[12:13] op_sel:[1,0,0]
	v_pk_fma_f32 v[38:39], v[212:213], v[144:145], v[38:39] op_sel_hi:[0,1,1]
	v_pk_fma_f32 v[40:41], v[212:213], v[146:147], v[40:41] op_sel_hi:[0,1,1]
	v_pk_fma_f32 v[22:23], v[216:217], v[144:145], v[22:23] op_sel_hi:[0,1,1]
	v_pk_fma_f32 v[24:25], v[216:217], v[146:147], v[24:25] op_sel_hi:[0,1,1]
	v_pk_fma_f32 v[6:7], v[220:221], v[144:145], v[6:7] op_sel_hi:[0,1,1]
	v_pk_fma_f32 v[8:9], v[220:221], v[146:147], v[8:9] op_sel_hi:[0,1,1]
	v_pk_fma_f32 v[30:31], v[212:213], v[144:145], v[30:31] op_sel:[1,0,0]
	v_pk_fma_f32 v[32:33], v[212:213], v[146:147], v[32:33] op_sel:[1,0,0]
	v_pk_fma_f32 v[18:19], v[216:217], v[144:145], v[18:19] op_sel:[1,0,0]
	v_pk_fma_f32 v[20:21], v[216:217], v[146:147], v[20:21] op_sel:[1,0,0]
	v_pk_fma_f32 v[2:3], v[220:221], v[144:145], v[2:3] op_sel:[1,0,0]
	v_pk_fma_f32 v[4:5], v[220:221], v[146:147], v[4:5] op_sel:[1,0,0]
	global_load_dwordx4 v[144:147], v[234:235], off
	v_lshl_add_u64 v[234:235], v[234:235], 0, s[12:13]
	ds_read_b128 v[210:213], v74 offset:24960
	ds_read_b128 v[214:217], v74 offset:24976
	ds_read_b128 v[218:221], v74 offset:24992
	s_waitcnt vmcnt(49) lgkmcnt(3)
; #define LAS __attribute__((address_space(3)))
; __device__ __forceinline__ void phase_prologue(const Frame& F) {
;     ...
;                 if (tid < 480) {
; #pragma unroll 2
;                     for (int kk = kl; kk < 256; kk += 10) {
;                         const f32x4 w4 = *(const f32x4*)(wada + (size_t)(kc * 256 + kk) * MODW + 48 * cb + 4 * cgp);
;                         const f32x2 w01 = (f32x2){w4[0], w4[1]}, w23 = (f32x2){w4[2], w4[3]};
;                         const LAS f32x4* sp = (const LAS f32x4*)(sT + kk * 52 + 12 * cdg);
;                         const f32x4 s0 = sp[0], s1 = sp[1], s2 = sp[2];
; #pragma unroll
;                         for (int c = 0; c < 4; ++c) {
;                             acc[c][0] = __builtin_elementwise_fma((f32x2){s0[c], s0[c]}, w01, acc[c][0]); acc[c][1] = __builtin_elementwise_fma((f32x2){s0[c], s0[c]}, w23, acc[c][1]);
;                             acc[4 + c][0] = __builtin_elementwise_fma((f32x2){s1[c], s1[c]}, w01, acc[4 + c][0]); acc[4 + c][1] = __builtin_elementwise_fma((f32x2){s1[c], s1[c]}, w23, acc[4 + c][1]);
;                             acc[8 + c][0] = __builtin_elementwise_fma((f32x2){s2[c], s2[c]}, w01, acc[8 + c][0]); acc[8 + c][1] = __builtin_elementwise_fma((f32x2){s2[c], s2[c]}, w23, acc[8 + c][1]); }
;                     }
	v_pk_fma_f32 v[46:47], v[222:223], v[148:149], v[46:47] op_sel_hi:[0,1,1]
	v_pk_fma_f32 v[48:49], v[222:223], v[150:151], v[48:49] op_sel_hi:[0,1,1]
	v_pk_fma_f32 v[34:35], v[226:227], v[148:149], v[34:35] op_sel_hi:[0,1,1]
	v_pk_fma_f32 v[36:37], v[226:227], v[150:151], v[36:37] op_sel_hi:[0,1,1]
	v_pk_fma_f32 v[14:15], v[230:231], v[148:149], v[14:15] op_sel_hi:[0,1,1]
	v_pk_fma_f32 v[16:17], v[230:231], v[150:151], v[16:17] op_sel_hi:[0,1,1]
	v_pk_fma_f32 v[42:43], v[222:223], v[148:149], v[42:43] op_sel:[1,0,0]
	v_pk_fma_f32 v[44:45], v[222:223], v[150:151], v[44:45] op_sel:[1,0,0]
	v_pk_fma_f32 v[26:27], v[226:227], v[148:149], v[26:27] op_sel:[1,0,0]
	v_pk_fma_f32 v[28:29], v[226:227], v[150:151], v[28:29] op_sel:[1,0,0]
	v_pk_fma_f32 v[10:11], v[230:231], v[148:149], v[10:11] op_sel:[1,0,0]
	v_pk_fma_f32 v[12:13], v[230:231], v[150:151], v[12:13] op_sel:[1,0,0]
	v_pk_fma_f32 v[38:39], v[224:225], v[148:149], v[38:39] op_sel_hi:[0,1,1]
	v_pk_fma_f32 v[40:41], v[224:225], v[150:151], v[40:41] op_sel_hi:[0,1,1]
	v_pk_fma_f32 v[22:23], v[228:229], v[148:149], v[22:23] op_sel_hi:[0,1,1]
	v_pk_fma_f32 v[24:25], v[228:229], v[150:151], v[24:25] op_sel_hi:[0,1,1]
	v_pk_fma_f32 v[6:7], v[232:233], v[148:149], v[6:7] op_sel_hi:[0,1,1]
	v_pk_fma_f32 v[8:9], v[232:233], v[150:151], v[8:9] op_sel_hi:[0,1,1]
	v_pk_fma_f32 v[30:31], v[224:225], v[148:149], v[30:31] op_sel:[1,0,0]
	v_pk_fma_f32 v[32:33], v[224:225], v[150:151], v[32:33] op_sel:[1,0,0]
	v_pk_fma_f32 v[18:19], v[228:229], v[148:149], v[18:19] op_sel:[1,0,0]
	v_pk_fma_f32 v[20:21], v[228:229], v[150:151], v[20:21] op_sel:[1,0,0]
	v_pk_fma_f32 v[2:3], v[232:233], v[148:149], v[2:3] op_sel:[1,0,0]
	v_pk_fma_f32 v[4:5], v[232:233], v[150:151], v[4:5] op_sel:[1,0,0]
	global_load_dwordx4 v[148:151], v[234:235], off
	v_lshl_add_u64 v[234:235], v[234:235], 0, s[12:13]
	ds_read_b128 v[222:225], v74 offset:27040
	ds_read_b128 v[226:229], v74 offset:27056
	ds_read_b128 v[230:233], v74 offset:27072
	s_waitcnt vmcnt(49) lgkmcnt(3)
	v_pk_fma_f32 v[46:47], v[210:211], v[152:153], v[46:47] op_sel_hi:[0,1,1]
	v_pk_fma_f32 v[48:49], v[210:211], v[154:155], v[48:49] op_sel_hi:[0,1,1]
	v_pk_fma_f32 v[34:35], v[214:215], v[152:153], v[34:35] op_sel_hi:[0,1,1]
	v_pk_fma_f32 v[36:37], v[214:215], v[154:155], v[36:37] op_sel_hi:[0,1,1]
	v_pk_fma_f32 v[14:15], v[218:219], v[152:153], v[14:15] op_sel_hi:[0,1,1]
	v_pk_fma_f32 v[16:17], v[218:219], v[154:155], v[16:17] op_sel_hi:[0,1,1]
	v_pk_fma_f32 v[42:43], v[210:211], v[152:153], v[42:43] op_sel:[1,0,0]
	v_pk_fma_f32 v[44:45], v[210:211], v[154:155], v[44:45] op_sel:[1,0,0]
	v_pk_fma_f32 v[26:27], v[214:215], v[152:153], v[26:27] op_sel:[1,0,0]
	v_pk_fma_f32 v[28:29], v[214:215], v[154:155], v[28:29] op_sel:[1,0,0]
	v_pk_fma_f32 v[10:11], v[218:219], v[152:153], v[10:11] op_sel:[1,0,0]
	v_pk_fma_f32 v[12:13], v[218:219], v[154:155], v[12:13] op_sel:[1,0,0]
	v_pk_fma_f32 v[38:39], v[212:213], v[152:153], v[38:39] op_sel_hi:[0,1,1]
	v_pk_fma_f32 v[40:41], v[212:213], v[154:155], v[40:41] op_sel_hi:[0,1,1]
	v_pk_fma_f32 v[22:23], v[216:217], v[152:153], v[22:23] op_sel_hi:[0,1,1]
	v_pk_fma_f32 v[24:25], v[216:217], v[154:155], v[24:25] op_sel_hi:[0,1,1]
	v_pk_fma_f32 v[6:7], v[220:221], v[152:153], v[6:7] op_sel_hi:[0,1,1]
	v_pk_fma_f32 v[8:9], v[220:221], v[154:155], v[8:9] op_sel_hi:[0,1,1]
	v_pk_fma_f32 v[30:31], v[212:213], v[152:153], v[30:31] op_sel:[1,0,0]
	v_pk_fma_f32 v[32:33], v[212:213], v[154:155], v[32:33] op_sel:[1,0,0]
	v_pk_fma_f32 v[18:19], v[216:217], v[152:153], v[18:19] op_sel:[1,0,0]
	v_pk_fma_f32 v[20:21], v[216:217], v[154:155], v[20:21] op_sel:[1,0,0]
	v_pk_fma_f32 v[2:3], v[220:221], v[152:153], v[2:3] op_sel:[1,0,0]
	v_pk_fma_f32 v[4:5], v[220:221], v[154:155], v[4:5] op_sel:[1,0,0]
	global_load_dwordx4 v[152:155], v[234:235], off
	v_lshl_add_u64 v[234:235], v[234:235], 0, s[12:13]
	ds_read_b128 v[210:213], v74 offset:29120
	ds_read_b128 v[214:217], v74 offset:29136
	ds_read_b128 v[218:221], v74 offset:29152
	s_waitcnt vmcnt(49) lgkmcnt(3)
	v_pk_fma_f32 v[46:47], v[222:223], v[156:157], v[46:47] op_sel_hi:[0,1,1]
	v_pk_fma_f32 v[48:49], v[222:223], v[158:159], v[48:49] op_sel_hi:[0,1,1]
	v_pk_fma_f32 v[34:35], v[226:227], v[156:157], v[34:35] op_sel_hi:[0,1,1]
	v_pk_fma_f32 v[36:37], v[226:227], v[158:159], v[36:37] op_sel_hi:[0,1,1]
	v_pk_fma_f32 v[14:15], v[230:231], v[156:157], v[14:15] op_sel_hi:[0,1,1]
	v_pk_fma_f32 v[16:17], v[230:231], v[158:159], v[16:17] op_sel_hi:[0,1,1]
	v_pk_fma_f32 v[42:43], v[222:223], v[156:157], v[42:43] op_sel:[1,0,0]
	v_pk_fma_f32 v[44:45], v[222:223], v[158:159], v[44:45] op_sel:[1,0,0]
	v_pk_fma_f32 v[26:27], v[226:227], v[156:157], v[26:27] op_sel:[1,0,0]
	v_pk_fma_f32 v[28:29], v[226:227], v[158:159], v[28:29] op_sel:[1,0,0]
	v_pk_fma_f32 v[10:11], v[230:231], v[156:157], v[10:11] op_sel:[1,0,0]
	v_pk_fma_f32 v[12:13], v[230:231], v[158:159], v[12:13] op_sel:[1,0,0]
	v_pk_fma_f32 v[38:39], v[224:225], v[156:157], v[38:39] op_sel_hi:[0,1,1]
	v_pk_fma_f32 v[40:41], v[224:225], v[158:159], v[40:41] op_sel_hi:[0,1,1]
	v_pk_fma_f32 v[22:23], v[228:229], v[156:157], v[22:23] op_sel_hi:[0,1,1]
	v_pk_fma_f32 v[24:25], v[228:229], v[158:159], v[24:25] op_sel_hi:[0,1,1]
	v_pk_fma_f32 v[6:7], v[232:233], v[156:157], v[6:7] op_sel_hi:[0,1,1]
	v_pk_fma_f32 v[8:9], v[232:233], v[158:159], v[8:9] op_sel_hi:[0,1,1]
	v_pk_fma_f32 v[30:31], v[224:225], v[156:157], v[30:31] op_sel:[1,0,0]
	v_pk_fma_f32 v[32:33], v[224:225], v[158:159], v[32:33] op_sel:[1,0,0]
	v_pk_fma_f32 v[18:19], v[228:229], v[156:157], v[18:19] op_sel:[1,0,0]
	v_pk_fma_f32 v[20:21], v[228:229], v[158:159], v[20:21] op_sel:[1,0,0]
	v_pk_fma_f32 v[2:3], v[232:233], v[156:157], v[2:3] op_sel:[1,0,0]
	v_pk_fma_f32 v[4:5], v[232:233], v[158:159], v[4:5] op_sel:[1,0,0]
	global_load_dwordx4 v[156:159], v[234:235], off
	v_lshl_add_u64 v[234:235], v[234:235], 0, s[12:13]
	ds_read_b128 v[222:225], v74 offset:31200
	ds_read_b128 v[226:229], v74 offset:31216
	ds_read_b128 v[230:233], v74 offset:31232
	s_waitcnt vmcnt(49) lgkmcnt(3)
; #define LAS __attribute__((address_space(3)))
; __device__ __forceinline__ void phase_prologue(const Frame& F) {
;     ...
;                 if (tid < 480) {
; #pragma unroll 2
;                     for (int kk = kl; kk < 256; kk += 10) {
;                         const f32x4 w4 = *(const f32x4*)(wada + (size_t)(kc * 256 + kk) * MODW + 48 * cb + 4 * cgp);
;                         const f32x2 w01 = (f32x2){w4[0], w4[1]}, w23 = (f32x2){w4[2], w4[3]};
;                         const LAS f32x4* sp = (const LAS f32x4*)(sT + kk * 52 + 12 * cdg);
;                         const f32x4 s0 = sp[0], s1 = sp[1], s2 = sp[2];
; #pragma unroll
;                         for (int c = 0; c < 4; ++c) {
;                             acc[c][0] = __builtin_elementwise_fma((f32x2){s0[c], s0[c]}, w01, acc[c][0]); acc[c][1] = __builtin_elementwise_fma((f32x2){s0[c], s0[c]}, w23, acc[c][1]);
;                             acc[4 + c][0] = __builtin_elementwise_fma((f32x2){s1[c], s1[c]}, w01, acc[4 + c][0]); acc[4 + c][1] = __builtin_elementwise_fma((f32x2){s1[c], s1[c]}, w23, acc[4 + c][1]);
;                             acc[8 + c][0] = __builtin_elementwise_fma((f32x2){s2[c], s2[c]}, w01, acc[8 + c][0]); acc[8 + c][1] = __builtin_elementwise_fma((f32x2){s2[c], s2[c]}, w23, acc[8 + c][1]); }
;                     }
	v_pk_fma_f32 v[46:47], v[210:211], v[160:161], v[46:47] op_sel_hi:[0,1,1]
	v_pk_fma_f32 v[48:49], v[210:211], v[162:163], v[48:49] op_sel_hi:[0,1,1]
	v_pk_fma_f32 v[34:35], v[214:215], v[160:161], v[34:35] op_sel_hi:[0,1,1]
	v_pk_fma_f32 v[36:37], v[214:215], v[162:163], v[36:37] op_sel_hi:[0,1,1]
	v_pk_fma_f32 v[14:15], v[218:219], v[160:161], v[14:15] op_sel_hi:[0,1,1]
	v_pk_fma_f32 v[16:17], v[218:219], v[162:163], v[16:17] op_sel_hi:[0,1,1]
	v_pk_fma_f32 v[42:43], v[210:211], v[160:161], v[42:43] op_sel:[1,0,0]
	v_pk_fma_f32 v[44:45], v[210:211], v[162:163], v[44:45] op_sel:[1,0,0]
	v_pk_fma_f32 v[26:27], v[214:215], v[160:161], v[26:27] op_sel:[1,0,0]
	v_pk_fma_f32 v[28:29], v[214:215], v[162:163], v[28:29] op_sel:[1,0,0]
	v_pk_fma_f32 v[10:11], v[218:219], v[160:161], v[10:11] op_sel:[1,0,0]
	v_pk_fma_f32 v[12:13], v[218:219], v[162:163], v[12:13] op_sel:[1,0,0]
	v_pk_fma_f32 v[38:39], v[212:213], v[160:161], v[38:39] op_sel_hi:[0,1,1]
	v_pk_fma_f32 v[40:41], v[212:213], v[162:163], v[40:41] op_sel_hi:[0,1,1]
	v_pk_fma_f32 v[22:23], v[216:217], v[160:161], v[22:23] op_sel_hi:[0,1,1]
	v_pk_fma_f32 v[24:25], v[216:217], v[162:163], v[24:25] op_sel_hi:[0,1,1]
	v_pk_fma_f32 v[6:7], v[220:221], v[160:161], v[6:7] op_sel_hi:[0,1,1]
	v_pk_fma_f32 v[8:9], v[220:221], v[162:163], v[8:9] op_sel_hi:[0,1,1]
	v_pk_fma_f32 v[30:31], v[212:213], v[160:161], v[30:31] op_sel:[1,0,0]
	v_pk_fma_f32 v[32:33], v[212:213], v[162:163], v[32:33] op_sel:[1,0,0]
	v_pk_fma_f32 v[18:19], v[216:217], v[160:161], v[18:19] op_sel:[1,0,0]
	v_pk_fma_f32 v[20:21], v[216:217], v[162:163], v[20:21] op_sel:[1,0,0]
	v_pk_fma_f32 v[2:3], v[220:221], v[160:161], v[2:3] op_sel:[1,0,0]
	v_pk_fma_f32 v[4:5], v[220:221], v[162:163], v[4:5] op_sel:[1,0,0]
	global_load_dwordx4 v[160:163], v[234:235], off
	v_lshl_add_u64 v[234:235], v[234:235], 0, s[12:13]
	ds_read_b128 v[210:213], v74 offset:33280
	ds_read_b128 v[214:217], v74 offset:33296
	ds_read_b128 v[218:221], v74 offset:33312
	s_waitcnt vmcnt(49) lgkmcnt(3)
	v_pk_fma_f32 v[46:47], v[222:223], v[164:165], v[46:47] op_sel_hi:[0,1,1]
	v_pk_fma_f32 v[48:49], v[222:223], v[166:167], v[48:49] op_sel_hi:[0,1,1]
	v_pk_fma_f32 v[34:35], v[226:227], v[164:165], v[34:35] op_sel_hi:[0,1,1]
	v_pk_fma_f32 v[36:37], v[226:227], v[166:167], v[36:37] op_sel_hi:[0,1,1]
	v_pk_fma_f32 v[14:15], v[230:231], v[164:165], v[14:15] op_sel_hi:[0,1,1]
	v_pk_fma_f32 v[16:17], v[230:231], v[166:167], v[16:17] op_sel_hi:[0,1,1]
	v_pk_fma_f32 v[42:43], v[222:223], v[164:165], v[42:43] op_sel:[1,0,0]
	v_pk_fma_f32 v[44:45], v[222:223], v[166:167], v[44:45] op_sel:[1,0,0]
	v_pk_fma_f32 v[26:27], v[226:227], v[164:165], v[26:27] op_sel:[1,0,0]
	v_pk_fma_f32 v[28:29], v[226:227], v[166:167], v[28:29] op_sel:[1,0,0]
	v_pk_fma_f32 v[10:11], v[230:231], v[164:165], v[10:11] op_sel:[1,0,0]
	v_pk_fma_f32 v[12:13], v[230:231], v[166:167], v[12:13] op_sel:[1,0,0]
	v_pk_fma_f32 v[38:39], v[224:225], v[164:165], v[38:39] op_sel_hi:[0,1,1]
	v_pk_fma_f32 v[40:41], v[224:225], v[166:167], v[40:41] op_sel_hi:[0,1,1]
	v_pk_fma_f32 v[22:23], v[228:229], v[164:165], v[22:23] op_sel_hi:[0,1,1]
	v_pk_fma_f32 v[24:25], v[228:229], v[166:167], v[24:25] op_sel_hi:[0,1,1]
	v_pk_fma_f32 v[6:7], v[232:233], v[164:165], v[6:7] op_sel_hi:[0,1,1]
	v_pk_fma_f32 v[8:9], v[232:233], v[166:167], v[8:9] op_sel_hi:[0,1,1]
	v_pk_fma_f32 v[30:31], v[224:225], v[164:165], v[30:31] op_sel:[1,0,0]
	v_pk_fma_f32 v[32:33], v[224:225], v[166:167], v[32:33] op_sel:[1,0,0]
	v_pk_fma_f32 v[18:19], v[228:229], v[164:165], v[18:19] op_sel:[1,0,0]
	v_pk_fma_f32 v[20:21], v[228:229], v[166:167], v[20:21] op_sel:[1,0,0]
	v_pk_fma_f32 v[2:3], v[232:233], v[164:165], v[2:3] op_sel:[1,0,0]
	v_pk_fma_f32 v[4:5], v[232:233], v[166:167], v[4:5] op_sel:[1,0,0]
	global_load_dwordx4 v[164:167], v[234:235], off
	v_lshl_add_u64 v[234:235], v[234:235], 0, s[12:13]
	ds_read_b128 v[222:225], v74 offset:35360
	ds_read_b128 v[226:229], v74 offset:35376
	ds_read_b128 v[230:233], v74 offset:35392
	s_waitcnt vmcnt(49) lgkmcnt(3)
	v_pk_fma_f32 v[46:47], v[210:211], v[168:169], v[46:47] op_sel_hi:[0,1,1]
	v_pk_fma_f32 v[48:49], v[210:211], v[170:171], v[48:49] op_sel_hi:[0,1,1]
	v_pk_fma_f32 v[34:35], v[214:215], v[168:169], v[34:35] op_sel_hi:[0,1,1]
	v_pk_fma_f32 v[36:37], v[214:215], v[170:171], v[36:37] op_sel_hi:[0,1,1]
	v_pk_fma_f32 v[14:15], v[218:219], v[168:169], v[14:15] op_sel_hi:[0,1,1]
	v_pk_fma_f32 v[16:17], v[218:219], v[170:171], v[16:17] op_sel_hi:[0,1,1]
	v_pk_fma_f32 v[42:43], v[210:211], v[168:169], v[42:43] op_sel:[1,0,0]
	v_pk_fma_f32 v[44:45], v[210:211], v[170:171], v[44:45] op_sel:[1,0,0]
	v_pk_fma_f32 v[26:27], v[214:215], v[168:169], v[26:27] op_sel:[1,0,0]
	v_pk_fma_f32 v[28:29], v[214:215], v[170:171], v[28:29] op_sel:[1,0,0]
	v_pk_fma_f32 v[10:11], v[218:219], v[168:169], v[10:11] op_sel:[1,0,0]
	v_pk_fma_f32 v[12:13], v[218:219], v[170:171], v[12:13] op_sel:[1,0,0]
	v_pk_fma_f32 v[38:39], v[212:213], v[168:169], v[38:39] op_sel_hi:[0,1,1]
	v_pk_fma_f32 v[40:41], v[212:213], v[170:171], v[40:41] op_sel_hi:[0,1,1]
	v_pk_fma_f32 v[22:23], v[216:217], v[168:169], v[22:23] op_sel_hi:[0,1,1]
	v_pk_fma_f32 v[24:25], v[216:217], v[170:171], v[24:25] op_sel_hi:[0,1,1]
	v_pk_fma_f32 v[6:7], v[220:221], v[168:169], v[6:7] op_sel_hi:[0,1,1]
	v_pk_fma_f32 v[8:9], v[220:221], v[170:171], v[8:9] op_sel_hi:[0,1,1]
	v_pk_fma_f32 v[30:31], v[212:213], v[168:169], v[30:31] op_sel:[1,0,0]
	v_pk_fma_f32 v[32:33], v[212:213], v[170:171], v[32:33] op_sel:[1,0,0]
	v_pk_fma_f32 v[18:19], v[216:217], v[168:169], v[18:19] op_sel:[1,0,0]
	v_pk_fma_f32 v[20:21], v[216:217], v[170:171], v[20:21] op_sel:[1,0,0]
	v_pk_fma_f32 v[2:3], v[220:221], v[168:169], v[2:3] op_sel:[1,0,0]
	v_pk_fma_f32 v[4:5], v[220:221], v[170:171], v[4:5] op_sel:[1,0,0]
	global_load_dwordx4 v[168:171], v[234:235], off
	v_lshl_add_u64 v[234:235], v[234:235], 0, s[12:13]
	ds_read_b128 v[210:213], v74 offset:37440
	ds_read_b128 v[214:217], v74 offset:37456
	ds_read_b128 v[218:221], v74 offset:37472
	s_waitcnt vmcnt(49) lgkmcnt(3)
; #define LAS __attribute__((address_space(3)))
; __device__ __forceinline__ void phase_prologue(const Frame& F) {
;     ...
;                 if (tid < 480) {
; #pragma unroll 2
;                     for (int kk = kl; kk < 256; kk += 10) {
;                         const f32x4 w4 = *(const f32x4*)(wada + (size_t)(kc * 256 + kk) * MODW + 48 * cb + 4 * cgp);
;                         const f32x2 w01 = (f32x2){w4[0], w4[1]}, w23 = (f32x2){w4[2], w4[3]};
;                         const LAS f32x4* sp = (const LAS f32x4*)(sT + kk * 52 + 12 * cdg);
;                         const f32x4 s0 = sp[0], s1 = sp[1], s2 = sp[2];
; #pragma unroll
;                         for (int c = 0; c < 4; ++c) {
;                             acc[c][0] = __builtin_elementwise_fma((f32x2){s0[c], s0[c]}, w01, acc[c][0]); acc[c][1] = __builtin_elementwise_fma((f32x2){s0[c], s0[c]}, w23, acc[c][1]);
;                             acc[4 + c][0] = __builtin_elementwise_fma((f32x2){s1[c], s1[c]}, w01, acc[4 + c][0]); acc[4 + c][1] = __builtin_elementwise_fma((f32x2){s1[c], s1[c]}, w23, acc[4 + c][1]);
;                             acc[8 + c][0] = __builtin_elementwise_fma((f32x2){s2[c], s2[c]}, w01, acc[8 + c][0]); acc[8 + c][1] = __builtin_elementwise_fma((f32x2){s2[c], s2[c]}, w23, acc[8 + c][1]); }
;                     }
	v_pk_fma_f32 v[46:47], v[222:223], v[172:173], v[46:47] op_sel_hi:[0,1,1]
	v_pk_fma_f32 v[48:49], v[222:223], v[174:175], v[48:49] op_sel_hi:[0,1,1]
	v_pk_fma_f32 v[34:35], v[226:227], v[172:173], v[34:35] op_sel_hi:[0,1,1]
	v_pk_fma_f32 v[36:37], v[226:227], v[174:175], v[36:37] op_sel_hi:[0,1,1]
	v_pk_fma_f32 v[14:15], v[230:231], v[172:173], v[14:15] op_sel_hi:[0,1,1]
	v_pk_fma_f32 v[16:17], v[230:231], v[174:175], v[16:17] op_sel_hi:[0,1,1]
	v_pk_fma_f32 v[42:43], v[222:223], v[172:173], v[42:43] op_sel:[1,0,0]
	v_pk_fma_f32 v[44:45], v[222:223], v[174:175], v[44:45] op_sel:[1,0,0]
	v_pk_fma_f32 v[26:27], v[226:227], v[172:173], v[26:27] op_sel:[1,0,0]
	v_pk_fma_f32 v[28:29], v[226:227], v[174:175], v[28:29] op_sel:[1,0,0]
	v_pk_fma_f32 v[10:11], v[230:231], v[172:173], v[10:11] op_sel:[1,0,0]
	v_pk_fma_f32 v[12:13], v[230:231], v[174:175], v[12:13] op_sel:[1,0,0]
	v_pk_fma_f32 v[38:39], v[224:225], v[172:173], v[38:39] op_sel_hi:[0,1,1]
	v_pk_fma_f32 v[40:41], v[224:225], v[174:175], v[40:41] op_sel_hi:[0,1,1]
	v_pk_fma_f32 v[22:23], v[228:229], v[172:173], v[22:23] op_sel_hi:[0,1,1]
	v_pk_fma_f32 v[24:25], v[228:229], v[174:175], v[24:25] op_sel_hi:[0,1,1]
	v_pk_fma_f32 v[6:7], v[232:233], v[172:173], v[6:7] op_sel_hi:[0,1,1]
	v_pk_fma_f32 v[8:9], v[232:233], v[174:175], v[8:9] op_sel_hi:[0,1,1]
	v_pk_fma_f32 v[30:31], v[224:225], v[172:173], v[30:31] op_sel:[1,0,0]
	v_pk_fma_f32 v[32:33], v[224:225], v[174:175], v[32:33] op_sel:[1,0,0]
	v_pk_fma_f32 v[18:19], v[228:229], v[172:173], v[18:19] op_sel:[1,0,0]
	v_pk_fma_f32 v[20:21], v[228:229], v[174:175], v[20:21] op_sel:[1,0,0]
	v_pk_fma_f32 v[2:3], v[232:233], v[172:173], v[2:3] op_sel:[1,0,0]
	v_pk_fma_f32 v[4:5], v[232:233], v[174:175], v[4:5] op_sel:[1,0,0]
	global_load_dwordx4 v[172:175], v[234:235], off
	v_lshl_add_u64 v[234:235], v[234:235], 0, s[12:13]
	ds_read_b128 v[222:225], v74 offset:39520
	ds_read_b128 v[226:229], v74 offset:39536
	ds_read_b128 v[230:233], v74 offset:39552
	s_waitcnt vmcnt(49) lgkmcnt(3)
	v_pk_fma_f32 v[46:47], v[210:211], v[176:177], v[46:47] op_sel_hi:[0,1,1]
	v_pk_fma_f32 v[48:49], v[210:211], v[178:179], v[48:49] op_sel_hi:[0,1,1]
	v_pk_fma_f32 v[34:35], v[214:215], v[176:177], v[34:35] op_sel_hi:[0,1,1]
	v_pk_fma_f32 v[36:37], v[214:215], v[178:179], v[36:37] op_sel_hi:[0,1,1]
	v_pk_fma_f32 v[14:15], v[218:219], v[176:177], v[14:15] op_sel_hi:[0,1,1]
	v_pk_fma_f32 v[16:17], v[218:219], v[178:179], v[16:17] op_sel_hi:[0,1,1]
	v_pk_fma_f32 v[42:43], v[210:211], v[176:177], v[42:43] op_sel:[1,0,0]
	v_pk_fma_f32 v[44:45], v[210:211], v[178:179], v[44:45] op_sel:[1,0,0]
	v_pk_fma_f32 v[26:27], v[214:215], v[176:177], v[26:27] op_sel:[1,0,0]
	v_pk_fma_f32 v[28:29], v[214:215], v[178:179], v[28:29] op_sel:[1,0,0]
	v_pk_fma_f32 v[10:11], v[218:219], v[176:177], v[10:11] op_sel:[1,0,0]
	v_pk_fma_f32 v[12:13], v[218:219], v[178:179], v[12:13] op_sel:[1,0,0]
	v_pk_fma_f32 v[38:39], v[212:213], v[176:177], v[38:39] op_sel_hi:[0,1,1]
	v_pk_fma_f32 v[40:41], v[212:213], v[178:179], v[40:41] op_sel_hi:[0,1,1]
	v_pk_fma_f32 v[22:23], v[216:217], v[176:177], v[22:23] op_sel_hi:[0,1,1]
	v_pk_fma_f32 v[24:25], v[216:217], v[178:179], v[24:25] op_sel_hi:[0,1,1]
	v_pk_fma_f32 v[6:7], v[220:221], v[176:177], v[6:7] op_sel_hi:[0,1,1]
	v_pk_fma_f32 v[8:9], v[220:221], v[178:179], v[8:9] op_sel_hi:[0,1,1]
	v_pk_fma_f32 v[30:31], v[212:213], v[176:177], v[30:31] op_sel:[1,0,0]
	v_pk_fma_f32 v[32:33], v[212:213], v[178:179], v[32:33] op_sel:[1,0,0]
	v_pk_fma_f32 v[18:19], v[216:217], v[176:177], v[18:19] op_sel:[1,0,0]
	v_pk_fma_f32 v[20:21], v[216:217], v[178:179], v[20:21] op_sel:[1,0,0]
	v_pk_fma_f32 v[2:3], v[220:221], v[176:177], v[2:3] op_sel:[1,0,0]
	v_pk_fma_f32 v[4:5], v[220:221], v[178:179], v[4:5] op_sel:[1,0,0]
	global_load_dwordx4 v[176:179], v[234:235], off
	v_lshl_add_u64 v[234:235], v[234:235], 0, s[12:13]
	ds_read_b128 v[210:213], v74 offset:41600
	ds_read_b128 v[214:217], v74 offset:41616
	ds_read_b128 v[218:221], v74 offset:41632
	s_waitcnt vmcnt(49) lgkmcnt(3)
	v_pk_fma_f32 v[46:47], v[222:223], v[180:181], v[46:47] op_sel_hi:[0,1,1]
	v_pk_fma_f32 v[48:49], v[222:223], v[182:183], v[48:49] op_sel_hi:[0,1,1]
	v_pk_fma_f32 v[34:35], v[226:227], v[180:181], v[34:35] op_sel_hi:[0,1,1]
	v_pk_fma_f32 v[36:37], v[226:227], v[182:183], v[36:37] op_sel_hi:[0,1,1]
	v_pk_fma_f32 v[14:15], v[230:231], v[180:181], v[14:15] op_sel_hi:[0,1,1]
	v_pk_fma_f32 v[16:17], v[230:231], v[182:183], v[16:17] op_sel_hi:[0,1,1]
	v_pk_fma_f32 v[42:43], v[222:223], v[180:181], v[42:43] op_sel:[1,0,0]
	v_pk_fma_f32 v[44:45], v[222:223], v[182:183], v[44:45] op_sel:[1,0,0]
	v_pk_fma_f32 v[26:27], v[226:227], v[180:181], v[26:27] op_sel:[1,0,0]
	v_pk_fma_f32 v[28:29], v[226:227], v[182:183], v[28:29] op_sel:[1,0,0]
	v_pk_fma_f32 v[10:11], v[230:231], v[180:181], v[10:11] op_sel:[1,0,0]
	v_pk_fma_f32 v[12:13], v[230:231], v[182:183], v[12:13] op_sel:[1,0,0]
	v_pk_fma_f32 v[38:39], v[224:225], v[180:181], v[38:39] op_sel_hi:[0,1,1]
	v_pk_fma_f32 v[40:41], v[224:225], v[182:183], v[40:41] op_sel_hi:[0,1,1]
	v_pk_fma_f32 v[22:23], v[228:229], v[180:181], v[22:23] op_sel_hi:[0,1,1]
	v_pk_fma_f32 v[24:25], v[228:229], v[182:183], v[24:25] op_sel_hi:[0,1,1]
	v_pk_fma_f32 v[6:7], v[232:233], v[180:181], v[6:7] op_sel_hi:[0,1,1]
	v_pk_fma_f32 v[8:9], v[232:233], v[182:183], v[8:9] op_sel_hi:[0,1,1]
	v_pk_fma_f32 v[30:31], v[224:225], v[180:181], v[30:31] op_sel:[1,0,0]
	v_pk_fma_f32 v[32:33], v[224:225], v[182:183], v[32:33] op_sel:[1,0,0]
	v_pk_fma_f32 v[18:19], v[228:229], v[180:181], v[18:19] op_sel:[1,0,0]
	v_pk_fma_f32 v[20:21], v[228:229], v[182:183], v[20:21] op_sel:[1,0,0]
	v_pk_fma_f32 v[2:3], v[232:233], v[180:181], v[2:3] op_sel:[1,0,0]
	v_pk_fma_f32 v[4:5], v[232:233], v[182:183], v[4:5] op_sel:[1,0,0]
	global_load_dwordx4 v[180:183], v[234:235], off
	v_lshl_add_u64 v[234:235], v[234:235], 0, s[12:13]
	ds_read_b128 v[222:225], v74 offset:43680
	ds_read_b128 v[226:229], v74 offset:43696
	ds_read_b128 v[230:233], v74 offset:43712
	s_waitcnt vmcnt(49) lgkmcnt(3)
; #define LAS __attribute__((address_space(3)))
; __device__ __forceinline__ void phase_prologue(const Frame& F) {
;     ...
;                 if (tid < 480) {
; #pragma unroll 2
;                     for (int kk = kl; kk < 256; kk += 10) {
;                         const f32x4 w4 = *(const f32x4*)(wada + (size_t)(kc * 256 + kk) * MODW + 48 * cb + 4 * cgp);
;                         const f32x2 w01 = (f32x2){w4[0], w4[1]}, w23 = (f32x2){w4[2], w4[3]};
;                         const LAS f32x4* sp = (const LAS f32x4*)(sT + kk * 52 + 12 * cdg);
;                         const f32x4 s0 = sp[0], s1 = sp[1], s2 = sp[2];
; #pragma unroll
;                         for (int c = 0; c < 4; ++c) {
;                             acc[c][0] = __builtin_elementwise_fma((f32x2){s0[c], s0[c]}, w01, acc[c][0]); acc[c][1] = __builtin_elementwise_fma((f32x2){s0[c], s0[c]}, w23, acc[c][1]);
;                             acc[4 + c][0] = __builtin_elementwise_fma((f32x2){s1[c], s1[c]}, w01, acc[4 + c][0]); acc[4 + c][1] = __builtin_elementwise_fma((f32x2){s1[c], s1[c]}, w23, acc[4 + c][1]);
;                             acc[8 + c][0] = __builtin_elementwise_fma((f32x2){s2[c], s2[c]}, w01, acc[8 + c][0]); acc[8 + c][1] = __builtin_elementwise_fma((f32x2){s2[c], s2[c]}, w23, acc[8 + c][1]); }
;                     }
	v_pk_fma_f32 v[46:47], v[210:211], v[184:185], v[46:47] op_sel_hi:[0,1,1]
	v_pk_fma_f32 v[48:49], v[210:211], v[186:187], v[48:49] op_sel_hi:[0,1,1]
	v_pk_fma_f32 v[34:35], v[214:215], v[184:185], v[34:35] op_sel_hi:[0,1,1]
	v_pk_fma_f32 v[36:37], v[214:215], v[186:187], v[36:37] op_sel_hi:[0,1,1]
	v_pk_fma_f32 v[14:15], v[218:219], v[184:185], v[14:15] op_sel_hi:[0,1,1]
	v_pk_fma_f32 v[16:17], v[218:219], v[186:187], v[16:17] op_sel_hi:[0,1,1]
	v_pk_fma_f32 v[42:43], v[210:211], v[184:185], v[42:43] op_sel:[1,0,0]
	v_pk_fma_f32 v[44:45], v[210:211], v[186:187], v[44:45] op_sel:[1,0,0]
	v_pk_fma_f32 v[26:27], v[214:215], v[184:185], v[26:27] op_sel:[1,0,0]
	v_pk_fma_f32 v[28:29], v[214:215], v[186:187], v[28:29] op_sel:[1,0,0]
	v_pk_fma_f32 v[10:11], v[218:219], v[184:185], v[10:11] op_sel:[1,0,0]
	v_pk_fma_f32 v[12:13], v[218:219], v[186:187], v[12:13] op_sel:[1,0,0]
	v_pk_fma_f32 v[38:39], v[212:213], v[184:185], v[38:39] op_sel_hi:[0,1,1]
	v_pk_fma_f32 v[40:41], v[212:213], v[186:187], v[40:41] op_sel_hi:[0,1,1]
	v_pk_fma_f32 v[22:23], v[216:217], v[184:185], v[22:23] op_sel_hi:[0,1,1]
	v_pk_fma_f32 v[24:25], v[216:217], v[186:187], v[24:25] op_sel_hi:[0,1,1]
	v_pk_fma_f32 v[6:7], v[220:221], v[184:185], v[6:7] op_sel_hi:[0,1,1]
	v_pk_fma_f32 v[8:9], v[220:221], v[186:187], v[8:9] op_sel_hi:[0,1,1]
	v_pk_fma_f32 v[30:31], v[212:213], v[184:185], v[30:31] op_sel:[1,0,0]
	v_pk_fma_f32 v[32:33], v[212:213], v[186:187], v[32:33] op_sel:[1,0,0]
	v_pk_fma_f32 v[18:19], v[216:217], v[184:185], v[18:19] op_sel:[1,0,0]
	v_pk_fma_f32 v[20:21], v[216:217], v[186:187], v[20:21] op_sel:[1,0,0]
	v_pk_fma_f32 v[2:3], v[220:221], v[184:185], v[2:3] op_sel:[1,0,0]
	v_pk_fma_f32 v[4:5], v[220:221], v[186:187], v[4:5] op_sel:[1,0,0]
	global_load_dwordx4 v[184:187], v[234:235], off
	v_lshl_add_u64 v[234:235], v[234:235], 0, s[12:13]
	ds_read_b128 v[210:213], v74 offset:45760
	ds_read_b128 v[214:217], v74 offset:45776
	ds_read_b128 v[218:221], v74 offset:45792
	s_waitcnt vmcnt(49) lgkmcnt(3)
	v_pk_fma_f32 v[46:47], v[222:223], v[188:189], v[46:47] op_sel_hi:[0,1,1]
	v_pk_fma_f32 v[48:49], v[222:223], v[190:191], v[48:49] op_sel_hi:[0,1,1]
	v_pk_fma_f32 v[34:35], v[226:227], v[188:189], v[34:35] op_sel_hi:[0,1,1]
	v_pk_fma_f32 v[36:37], v[226:227], v[190:191], v[36:37] op_sel_hi:[0,1,1]
	v_pk_fma_f32 v[14:15], v[230:231], v[188:189], v[14:15] op_sel_hi:[0,1,1]
	v_pk_fma_f32 v[16:17], v[230:231], v[190:191], v[16:17] op_sel_hi:[0,1,1]
	v_pk_fma_f32 v[42:43], v[222:223], v[188:189], v[42:43] op_sel:[1,0,0]
	v_pk_fma_f32 v[44:45], v[222:223], v[190:191], v[44:45] op_sel:[1,0,0]
	v_pk_fma_f32 v[26:27], v[226:227], v[188:189], v[26:27] op_sel:[1,0,0]
	v_pk_fma_f32 v[28:29], v[226:227], v[190:191], v[28:29] op_sel:[1,0,0]
	v_pk_fma_f32 v[10:11], v[230:231], v[188:189], v[10:11] op_sel:[1,0,0]
	v_pk_fma_f32 v[12:13], v[230:231], v[190:191], v[12:13] op_sel:[1,0,0]
	v_pk_fma_f32 v[38:39], v[224:225], v[188:189], v[38:39] op_sel_hi:[0,1,1]
	v_pk_fma_f32 v[40:41], v[224:225], v[190:191], v[40:41] op_sel_hi:[0,1,1]
	v_pk_fma_f32 v[22:23], v[228:229], v[188:189], v[22:23] op_sel_hi:[0,1,1]
	v_pk_fma_f32 v[24:25], v[228:229], v[190:191], v[24:25] op_sel_hi:[0,1,1]
	v_pk_fma_f32 v[6:7], v[232:233], v[188:189], v[6:7] op_sel_hi:[0,1,1]
	v_pk_fma_f32 v[8:9], v[232:233], v[190:191], v[8:9] op_sel_hi:[0,1,1]
	v_pk_fma_f32 v[30:31], v[224:225], v[188:189], v[30:31] op_sel:[1,0,0]
	v_pk_fma_f32 v[32:33], v[224:225], v[190:191], v[32:33] op_sel:[1,0,0]
	v_pk_fma_f32 v[18:19], v[228:229], v[188:189], v[18:19] op_sel:[1,0,0]
	v_pk_fma_f32 v[20:21], v[228:229], v[190:191], v[20:21] op_sel:[1,0,0]
	v_pk_fma_f32 v[2:3], v[232:233], v[188:189], v[2:3] op_sel:[1,0,0]
	v_pk_fma_f32 v[4:5], v[232:233], v[190:191], v[4:5] op_sel:[1,0,0]
	global_load_dwordx4 v[188:191], v[234:235], off
	v_lshl_add_u64 v[234:235], v[234:235], 0, s[12:13]
	ds_read_b128 v[222:225], v74 offset:47840
	ds_read_b128 v[226:229], v74 offset:47856
	ds_read_b128 v[230:233], v74 offset:47872
	s_waitcnt vmcnt(49) lgkmcnt(3)
	v_pk_fma_f32 v[46:47], v[210:211], v[194:195], v[46:47] op_sel_hi:[0,1,1]
	v_pk_fma_f32 v[48:49], v[210:211], v[196:197], v[48:49] op_sel_hi:[0,1,1]
	v_pk_fma_f32 v[34:35], v[214:215], v[194:195], v[34:35] op_sel_hi:[0,1,1]
	v_pk_fma_f32 v[36:37], v[214:215], v[196:197], v[36:37] op_sel_hi:[0,1,1]
	v_pk_fma_f32 v[14:15], v[218:219], v[194:195], v[14:15] op_sel_hi:[0,1,1]
	v_pk_fma_f32 v[16:17], v[218:219], v[196:197], v[16:17] op_sel_hi:[0,1,1]
	v_pk_fma_f32 v[42:43], v[210:211], v[194:195], v[42:43] op_sel:[1,0,0]
	v_pk_fma_f32 v[44:45], v[210:211], v[196:197], v[44:45] op_sel:[1,0,0]
	v_pk_fma_f32 v[26:27], v[214:215], v[194:195], v[26:27] op_sel:[1,0,0]
	v_pk_fma_f32 v[28:29], v[214:215], v[196:197], v[28:29] op_sel:[1,0,0]
	v_pk_fma_f32 v[10:11], v[218:219], v[194:195], v[10:11] op_sel:[1,0,0]
	v_pk_fma_f32 v[12:13], v[218:219], v[196:197], v[12:13] op_sel:[1,0,0]
	v_pk_fma_f32 v[38:39], v[212:213], v[194:195], v[38:39] op_sel_hi:[0,1,1]
	v_pk_fma_f32 v[40:41], v[212:213], v[196:197], v[40:41] op_sel_hi:[0,1,1]
	v_pk_fma_f32 v[22:23], v[216:217], v[194:195], v[22:23] op_sel_hi:[0,1,1]
	v_pk_fma_f32 v[24:25], v[216:217], v[196:197], v[24:25] op_sel_hi:[0,1,1]
	v_pk_fma_f32 v[6:7], v[220:221], v[194:195], v[6:7] op_sel_hi:[0,1,1]
	v_pk_fma_f32 v[8:9], v[220:221], v[196:197], v[8:9] op_sel_hi:[0,1,1]
	v_pk_fma_f32 v[30:31], v[212:213], v[194:195], v[30:31] op_sel:[1,0,0]
	v_pk_fma_f32 v[32:33], v[212:213], v[196:197], v[32:33] op_sel:[1,0,0]
	v_pk_fma_f32 v[18:19], v[216:217], v[194:195], v[18:19] op_sel:[1,0,0]
	v_pk_fma_f32 v[20:21], v[216:217], v[196:197], v[20:21] op_sel:[1,0,0]
	v_pk_fma_f32 v[2:3], v[220:221], v[194:195], v[2:3] op_sel:[1,0,0]
	v_pk_fma_f32 v[4:5], v[220:221], v[196:197], v[4:5] op_sel:[1,0,0]
	global_load_dwordx4 v[194:197], v[234:235], off
	v_lshl_add_u64 v[234:235], v[234:235], 0, s[12:13]
	ds_read_b128 v[210:213], v74 offset:49920
	ds_read_b128 v[214:217], v74 offset:49936
	ds_read_b128 v[218:221], v74 offset:49952
	s_waitcnt vmcnt(49) lgkmcnt(3)
; #define LAS __attribute__((address_space(3)))
; __device__ __forceinline__ void phase_prologue(const Frame& F) {
;     ...
;                 if (tid < 480) {
; #pragma unroll 2
;                     for (int kk = kl; kk < 256; kk += 10) {
;                         const f32x4 w4 = *(const f32x4*)(wada + (size_t)(kc * 256 + kk) * MODW + 48 * cb + 4 * cgp);
;                         const f32x2 w01 = (f32x2){w4[0], w4[1]}, w23 = (f32x2){w4[2], w4[3]};
;                         const LAS f32x4* sp = (const LAS f32x4*)(sT + kk * 52 + 12 * cdg);
;                         const f32x4 s0 = sp[0], s1 = sp[1], s2 = sp[2];
; #pragma unroll
;                         for (int c = 0; c < 4; ++c) {
;                             acc[c][0] = __builtin_elementwise_fma((f32x2){s0[c], s0[c]}, w01, acc[c][0]); acc[c][1] = __builtin_elementwise_fma((f32x2){s0[c], s0[c]}, w23, acc[c][1]);
;                             acc[4 + c][0] = __builtin_elementwise_fma((f32x2){s1[c], s1[c]}, w01, acc[4 + c][0]); acc[4 + c][1] = __builtin_elementwise_fma((f32x2){s1[c], s1[c]}, w23, acc[4 + c][1]);
;                             acc[8 + c][0] = __builtin_elementwise_fma((f32x2){s2[c], s2[c]}, w01, acc[8 + c][0]); acc[8 + c][1] = __builtin_elementwise_fma((f32x2){s2[c], s2[c]}, w23, acc[8 + c][1]); }
;                     }
	v_pk_fma_f32 v[46:47], v[222:223], v[198:199], v[46:47] op_sel_hi:[0,1,1]
	v_pk_fma_f32 v[48:49], v[222:223], v[200:201], v[48:49] op_sel_hi:[0,1,1]
	v_pk_fma_f32 v[34:35], v[226:227], v[198:199], v[34:35] op_sel_hi:[0,1,1]
	v_pk_fma_f32 v[36:37], v[226:227], v[200:201], v[36:37] op_sel_hi:[0,1,1]
	v_pk_fma_f32 v[14:15], v[230:231], v[198:199], v[14:15] op_sel_hi:[0,1,1]
	v_pk_fma_f32 v[16:17], v[230:231], v[200:201], v[16:17] op_sel_hi:[0,1,1]
	v_pk_fma_f32 v[42:43], v[222:223], v[198:199], v[42:43] op_sel:[1,0,0]
	v_pk_fma_f32 v[44:45], v[222:223], v[200:201], v[44:45] op_sel:[1,0,0]
	v_pk_fma_f32 v[26:27], v[226:227], v[198:199], v[26:27] op_sel:[1,0,0]
	v_pk_fma_f32 v[28:29], v[226:227], v[200:201], v[28:29] op_sel:[1,0,0]
	v_pk_fma_f32 v[10:11], v[230:231], v[198:199], v[10:11] op_sel:[1,0,0]
	v_pk_fma_f32 v[12:13], v[230:231], v[200:201], v[12:13] op_sel:[1,0,0]
	v_pk_fma_f32 v[38:39], v[224:225], v[198:199], v[38:39] op_sel_hi:[0,1,1]
	v_pk_fma_f32 v[40:41], v[224:225], v[200:201], v[40:41] op_sel_hi:[0,1,1]
	v_pk_fma_f32 v[22:23], v[228:229], v[198:199], v[22:23] op_sel_hi:[0,1,1]
	v_pk_fma_f32 v[24:25], v[228:229], v[200:201], v[24:25] op_sel_hi:[0,1,1]
	v_pk_fma_f32 v[6:7], v[232:233], v[198:199], v[6:7] op_sel_hi:[0,1,1]
	v_pk_fma_f32 v[8:9], v[232:233], v[200:201], v[8:9] op_sel_hi:[0,1,1]
	v_pk_fma_f32 v[30:31], v[224:225], v[198:199], v[30:31] op_sel:[1,0,0]
	v_pk_fma_f32 v[32:33], v[224:225], v[200:201], v[32:33] op_sel:[1,0,0]
	v_pk_fma_f32 v[18:19], v[228:229], v[198:199], v[18:19] op_sel:[1,0,0]
	v_pk_fma_f32 v[20:21], v[228:229], v[200:201], v[20:21] op_sel:[1,0,0]
	v_pk_fma_f32 v[2:3], v[232:233], v[198:199], v[2:3] op_sel:[1,0,0]
	v_pk_fma_f32 v[4:5], v[232:233], v[200:201], v[4:5] op_sel:[1,0,0]
	global_load_dwordx4 v[198:201], v[234:235], off
	v_lshl_add_u64 v[234:235], v[234:235], 0, s[12:13]
	ds_read_b128 v[222:225], v74 offset:52000
	ds_read_b128 v[226:229], v74 offset:52016
	ds_read_b128 v[230:233], v74 offset:52032
	s_waitcnt vmcnt(49) lgkmcnt(3)
	v_pk_fma_f32 v[46:47], v[210:211], v[202:203], v[46:47] op_sel_hi:[0,1,1]
	v_pk_fma_f32 v[48:49], v[210:211], v[204:205], v[48:49] op_sel_hi:[0,1,1]
	v_pk_fma_f32 v[34:35], v[214:215], v[202:203], v[34:35] op_sel_hi:[0,1,1]
	v_pk_fma_f32 v[36:37], v[214:215], v[204:205], v[36:37] op_sel_hi:[0,1,1]
	v_pk_fma_f32 v[14:15], v[218:219], v[202:203], v[14:15] op_sel_hi:[0,1,1]
	v_pk_fma_f32 v[16:17], v[218:219], v[204:205], v[16:17] op_sel_hi:[0,1,1]
	v_pk_fma_f32 v[42:43], v[210:211], v[202:203], v[42:43] op_sel:[1,0,0]
	v_pk_fma_f32 v[44:45], v[210:211], v[204:205], v[44:45] op_sel:[1,0,0]
	v_pk_fma_f32 v[26:27], v[214:215], v[202:203], v[26:27] op_sel:[1,0,0]
	v_pk_fma_f32 v[28:29], v[214:215], v[204:205], v[28:29] op_sel:[1,0,0]
	v_pk_fma_f32 v[10:11], v[218:219], v[202:203], v[10:11] op_sel:[1,0,0]
	v_pk_fma_f32 v[12:13], v[218:219], v[204:205], v[12:13] op_sel:[1,0,0]
	v_pk_fma_f32 v[38:39], v[212:213], v[202:203], v[38:39] op_sel_hi:[0,1,1]
	v_pk_fma_f32 v[40:41], v[212:213], v[204:205], v[40:41] op_sel_hi:[0,1,1]
	v_pk_fma_f32 v[22:23], v[216:217], v[202:203], v[22:23] op_sel_hi:[0,1,1]
	v_pk_fma_f32 v[24:25], v[216:217], v[204:205], v[24:25] op_sel_hi:[0,1,1]
	v_pk_fma_f32 v[6:7], v[220:221], v[202:203], v[6:7] op_sel_hi:[0,1,1]
	v_pk_fma_f32 v[8:9], v[220:221], v[204:205], v[8:9] op_sel_hi:[0,1,1]
	v_pk_fma_f32 v[30:31], v[212:213], v[202:203], v[30:31] op_sel:[1,0,0]
	v_pk_fma_f32 v[32:33], v[212:213], v[204:205], v[32:33] op_sel:[1,0,0]
	v_pk_fma_f32 v[18:19], v[216:217], v[202:203], v[18:19] op_sel:[1,0,0]
	v_pk_fma_f32 v[20:21], v[216:217], v[204:205], v[20:21] op_sel:[1,0,0]
	v_pk_fma_f32 v[2:3], v[220:221], v[202:203], v[2:3] op_sel:[1,0,0]
	v_pk_fma_f32 v[4:5], v[220:221], v[204:205], v[4:5] op_sel:[1,0,0]
	global_load_dwordx4 v[202:205], v[234:235], off
	v_lshl_add_u64 v[234:235], v[234:235], 0, v[236:237]
	s_waitcnt vmcnt(49) lgkmcnt(0)
	s_andn2_b64 exec, exec, s[4:5]
	v_pk_fma_f32 v[46:47], v[222:223], v[206:207], v[46:47] op_sel_hi:[0,1,1]
	v_pk_fma_f32 v[48:49], v[222:223], v[208:209], v[48:49] op_sel_hi:[0,1,1]
	v_pk_fma_f32 v[34:35], v[226:227], v[206:207], v[34:35] op_sel_hi:[0,1,1]
	v_pk_fma_f32 v[36:37], v[226:227], v[208:209], v[36:37] op_sel_hi:[0,1,1]
	v_pk_fma_f32 v[14:15], v[230:231], v[206:207], v[14:15] op_sel_hi:[0,1,1]
	v_pk_fma_f32 v[16:17], v[230:231], v[208:209], v[16:17] op_sel_hi:[0,1,1]
	v_pk_fma_f32 v[42:43], v[222:223], v[206:207], v[42:43] op_sel:[1,0,0]
	v_pk_fma_f32 v[44:45], v[222:223], v[208:209], v[44:45] op_sel:[1,0,0]
	v_pk_fma_f32 v[26:27], v[226:227], v[206:207], v[26:27] op_sel:[1,0,0]
	v_pk_fma_f32 v[28:29], v[226:227], v[208:209], v[28:29] op_sel:[1,0,0]
	v_pk_fma_f32 v[10:11], v[230:231], v[206:207], v[10:11] op_sel:[1,0,0]
	v_pk_fma_f32 v[12:13], v[230:231], v[208:209], v[12:13] op_sel:[1,0,0]
	v_pk_fma_f32 v[38:39], v[224:225], v[206:207], v[38:39] op_sel_hi:[0,1,1]
	v_pk_fma_f32 v[40:41], v[224:225], v[208:209], v[40:41] op_sel_hi:[0,1,1]
	v_pk_fma_f32 v[22:23], v[228:229], v[206:207], v[22:23] op_sel_hi:[0,1,1]
	v_pk_fma_f32 v[24:25], v[228:229], v[208:209], v[24:25] op_sel_hi:[0,1,1]
	v_pk_fma_f32 v[6:7], v[232:233], v[206:207], v[6:7] op_sel_hi:[0,1,1]
	v_pk_fma_f32 v[8:9], v[232:233], v[208:209], v[8:9] op_sel_hi:[0,1,1]
	v_pk_fma_f32 v[30:31], v[224:225], v[206:207], v[30:31] op_sel:[1,0,0]
	v_pk_fma_f32 v[32:33], v[224:225], v[208:209], v[32:33] op_sel:[1,0,0]
	v_pk_fma_f32 v[18:19], v[228:229], v[206:207], v[18:19] op_sel:[1,0,0]
	v_pk_fma_f32 v[20:21], v[228:229], v[208:209], v[20:21] op_sel:[1,0,0]
	v_pk_fma_f32 v[2:3], v[232:233], v[206:207], v[2:3] op_sel:[1,0,0]
	v_pk_fma_f32 v[4:5], v[232:233], v[208:209], v[4:5] op_sel:[1,0,0]
	s_and_b64 exec, s[10:11], s[0:1]
	global_load_dwordx4 v[206:209], v[234:235], off
	s_mov_b64 exec, s[10:11]
	s_add_i32 s30, s30, 1
	s_cmp_lt_u32 s30, 7
	s_cbranch_scc1 .Lmod_kc
; __device__ __forceinline__ float sigmoidf_(float x) { return 1.0f / (1.0f + __expf(-x)); }
; __device__ __forceinline__ void phase_prologue(const Frame& F) {
;     ...
;                 __syncthreads();
;                 for (int i = 0; i < 24; ++i) { const int idx = tid + 512 * i, cd = idx >> 8, kk = idx & 255;
;                     const float cv = cd < 16 ? cp[cd * D + kc * 256 + kk] : cs[(cd - 16) * D + kc * 256 + kk];
;                     sT[kk * 52 + cd] = cv * sigmoidf_(cv); }
;                 __syncthreads();
	s_barrier
	s_waitcnt vmcnt(26)
	v_mul_f32_e32 v210, 0xbfb8aa3b, v80
	v_mul_f32_e32 v211, 0xbfb8aa3b, v81
	v_mul_f32_e32 v212, 0xbfb8aa3b, v82
	v_mul_f32_e32 v213, 0xbfb8aa3b, v83
	v_exp_f32_e32 v210, v210
	v_exp_f32_e32 v211, v211
	v_exp_f32_e32 v212, v212
	v_exp_f32_e32 v213, v213
	v_add_f32_e32 v210, 1.0, v210
	v_add_f32_e32 v211, 1.0, v211
	v_add_f32_e32 v212, 1.0, v212
	v_add_f32_e32 v213, 1.0, v213
	v_rcp_f32_e32 v210, v210
	v_rcp_f32_e32 v211, v211
	v_rcp_f32_e32 v212, v212
	v_rcp_f32_e32 v213, v213
	v_mul_f32_e32 v210, v80, v210
	v_mul_f32_e32 v211, v81, v211
	v_mul_f32_e32 v212, v82, v212
	v_mul_f32_e32 v213, v83, v213
	ds_write_b32 v77, v210 offset:0
	ds_write_b32 v77, v211 offset:8
	ds_write_b32 v77, v212 offset:16
	ds_write_b32 v77, v213 offset:24
	v_mul_f32_e32 v214, 0xbfb8aa3b, v84
	v_mul_f32_e32 v215, 0xbfb8aa3b, v85
	v_mul_f32_e32 v216, 0xbfb8aa3b, v86
	v_mul_f32_e32 v217, 0xbfb8aa3b, v87
	v_exp_f32_e32 v214, v214
	v_exp_f32_e32 v215, v215
	v_exp_f32_e32 v216, v216
	v_exp_f32_e32 v217, v217
	v_add_f32_e32 v214, 1.0, v214
	v_add_f32_e32 v215, 1.0, v215
	v_add_f32_e32 v216, 1.0, v216
	v_add_f32_e32 v217, 1.0, v217
	v_rcp_f32_e32 v214, v214
	v_rcp_f32_e32 v215, v215
	v_rcp_f32_e32 v216, v216
	v_rcp_f32_e32 v217, v217
	v_mul_f32_e32 v214, v84, v214
	v_mul_f32_e32 v215, v85, v215
	v_mul_f32_e32 v216, v86, v216
	v_mul_f32_e32 v217, v87, v217
	ds_write_b32 v77, v214 offset:32
	ds_write_b32 v77, v215 offset:40
	ds_write_b32 v77, v216 offset:48
	ds_write_b32 v77, v217 offset:56
	v_mul_f32_e32 v218, 0xbfb8aa3b, v88
	v_mul_f32_e32 v219, 0xbfb8aa3b, v89
	v_mul_f32_e32 v220, 0xbfb8aa3b, v90
	v_mul_f32_e32 v221, 0xbfb8aa3b, v91
	v_exp_f32_e32 v218, v218
	v_exp_f32_e32 v219, v219
	v_exp_f32_e32 v220, v220
	v_exp_f32_e32 v221, v221
	v_add_f32_e32 v218, 1.0, v218
	v_add_f32_e32 v219, 1.0, v219
	v_add_f32_e32 v220, 1.0, v220
	v_add_f32_e32 v221, 1.0, v221
	v_rcp_f32_e32 v218, v218
	v_rcp_f32_e32 v219, v219
	v_rcp_f32_e32 v220, v220
	v_rcp_f32_e32 v221, v221
	v_mul_f32_e32 v218, v88, v218
	v_mul_f32_e32 v219, v89, v219
	v_mul_f32_e32 v220, v90, v220
	v_mul_f32_e32 v221, v91, v221
	ds_write_b32 v77, v218 offset:64
	ds_write_b32 v77, v219 offset:72
	ds_write_b32 v77, v220 offset:80
	ds_write_b32 v77, v221 offset:88
	v_mul_f32_e32 v222, 0xbfb8aa3b, v92
	v_mul_f32_e32 v223, 0xbfb8aa3b, v93
	v_mul_f32_e32 v224, 0xbfb8aa3b, v94
	v_mul_f32_e32 v225, 0xbfb8aa3b, v95
	v_exp_f32_e32 v222, v222
	v_exp_f32_e32 v223, v223
	v_exp_f32_e32 v224, v224
	v_exp_f32_e32 v225, v225
	v_add_f32_e32 v222, 1.0, v222
	v_add_f32_e32 v223, 1.0, v223
	v_add_f32_e32 v224, 1.0, v224
	v_add_f32_e32 v225, 1.0, v225
	v_rcp_f32_e32 v222, v222
	v_rcp_f32_e32 v223, v223
	v_rcp_f32_e32 v224, v224
	v_rcp_f32_e32 v225, v225
	v_mul_f32_e32 v222, v92, v222
	v_mul_f32_e32 v223, v93, v223
	v_mul_f32_e32 v224, v94, v224
	v_mul_f32_e32 v225, v95, v225
	ds_write_b32 v77, v222 offset:96
	ds_write_b32 v77, v223 offset:104
	ds_write_b32 v77, v224 offset:112
	ds_write_b32 v77, v225 offset:120
	v_mul_f32_e32 v226, 0xbfb8aa3b, v96
	v_mul_f32_e32 v227, 0xbfb8aa3b, v97
	v_mul_f32_e32 v228, 0xbfb8aa3b, v98
	v_mul_f32_e32 v229, 0xbfb8aa3b, v99
	v_exp_f32_e32 v226, v226
	v_exp_f32_e32 v227, v227
	v_exp_f32_e32 v228, v228
	v_exp_f32_e32 v229, v229
	v_add_f32_e32 v226, 1.0, v226
	v_add_f32_e32 v227, 1.0, v227
	v_add_f32_e32 v228, 1.0, v228
	v_add_f32_e32 v229, 1.0, v229
	v_rcp_f32_e32 v226, v226
	v_rcp_f32_e32 v227, v227
	v_rcp_f32_e32 v228, v228
	v_rcp_f32_e32 v229, v229
	v_mul_f32_e32 v226, v96, v226
	v_mul_f32_e32 v227, v97, v227
	v_mul_f32_e32 v228, v98, v228
	v_mul_f32_e32 v229, v99, v229
	ds_write_b32 v77, v226 offset:128
	ds_write_b32 v77, v227 offset:136
	ds_write_b32 v77, v228 offset:144
	ds_write_b32 v77, v229 offset:152
	v_mul_f32_e32 v230, 0xbfb8aa3b, v100
	v_mul_f32_e32 v231, 0xbfb8aa3b, v101
	v_mul_f32_e32 v232, 0xbfb8aa3b, v102
	v_mul_f32_e32 v233, 0xbfb8aa3b, v103
	v_exp_f32_e32 v230, v230
	v_exp_f32_e32 v231, v231
	v_exp_f32_e32 v232, v232
	v_exp_f32_e32 v233, v233
	v_add_f32_e32 v230, 1.0, v230
	v_add_f32_e32 v231, 1.0, v231
	v_add_f32_e32 v232, 1.0, v232
	v_add_f32_e32 v233, 1.0, v233
	v_rcp_f32_e32 v230, v230
	v_rcp_f32_e32 v231, v231
	v_rcp_f32_e32 v232, v232
	v_rcp_f32_e32 v233, v233
	v_mul_f32_e32 v230, v100, v230
	v_mul_f32_e32 v231, v101, v231
	v_mul_f32_e32 v232, v102, v232
	v_mul_f32_e32 v233, v103, v233
	ds_write_b32 v77, v230 offset:160
	ds_write_b32 v77, v231 offset:168
	ds_write_b32 v77, v232 offset:176
	ds_write_b32 v77, v233 offset:184
	s_waitcnt lgkmcnt(0)
	s_barrier
; #define LAS __attribute__((address_space(3)))
; __device__ __forceinline__ void phase_prologue(const Frame& F) {
;     ...
;                 if (tid < 480) {
; #pragma unroll 2
;                     for (int kk = kl; kk < 256; kk += 10) {
;                         const f32x4 w4 = *(const f32x4*)(wada + (size_t)(kc * 256 + kk) * MODW + 48 * cb + 4 * cgp);
;                         const f32x2 w01 = (f32x2){w4[0], w4[1]}, w23 = (f32x2){w4[2], w4[3]};
;                         const LAS f32x4* sp = (const LAS f32x4*)(sT + kk * 52 + 12 * cdg);
;                         const f32x4 s0 = sp[0], s1 = sp[1], s2 = sp[2];
; #pragma unroll
;                         for (int c = 0; c < 4; ++c) {
;                             acc[c][0] = __builtin_elementwise_fma((f32x2){s0[c], s0[c]}, w01, acc[c][0]); acc[c][1] = __builtin_elementwise_fma((f32x2){s0[c], s0[c]}, w23, acc[c][1]);
;                             acc[4 + c][0] = __builtin_elementwise_fma((f32x2){s1[c], s1[c]}, w01, acc[4 + c][0]); acc[4 + c][1] = __builtin_elementwise_fma((f32x2){s1[c], s1[c]}, w23, acc[4 + c][1]);
;                             acc[8 + c][0] = __builtin_elementwise_fma((f32x2){s2[c], s2[c]}, w01, acc[8 + c][0]); acc[8 + c][1] = __builtin_elementwise_fma((f32x2){s2[c], s2[c]}, w23, acc[8 + c][1]); }
;                     }
	s_and_saveexec_b64 s[10:11], s[0:1]
	ds_read_b128 v[210:213], v74 offset:0
	ds_read_b128 v[214:217], v74 offset:16
	ds_read_b128 v[218:221], v74 offset:32
	ds_read_b128 v[222:225], v74 offset:2080
	ds_read_b128 v[226:229], v74 offset:2096
	ds_read_b128 v[230:233], v74 offset:2112
	s_waitcnt vmcnt(25) lgkmcnt(3)
	v_pk_fma_f32 v[46:47], v[210:211], v[104:105], v[46:47] op_sel_hi:[0,1,1]
	v_pk_fma_f32 v[48:49], v[210:211], v[106:107], v[48:49] op_sel_hi:[0,1,1]
	v_pk_fma_f32 v[34:35], v[214:215], v[104:105], v[34:35] op_sel_hi:[0,1,1]
	v_pk_fma_f32 v[36:37], v[214:215], v[106:107], v[36:37] op_sel_hi:[0,1,1]
	v_pk_fma_f32 v[14:15], v[218:219], v[104:105], v[14:15] op_sel_hi:[0,1,1]
	v_pk_fma_f32 v[16:17], v[218:219], v[106:107], v[16:17] op_sel_hi:[0,1,1]
	v_pk_fma_f32 v[42:43], v[210:211], v[104:105], v[42:43] op_sel:[1,0,0]
	v_pk_fma_f32 v[44:45], v[210:211], v[106:107], v[44:45] op_sel:[1,0,0]
	v_pk_fma_f32 v[26:27], v[214:215], v[104:105], v[26:27] op_sel:[1,0,0]
	v_pk_fma_f32 v[28:29], v[214:215], v[106:107], v[28:29] op_sel:[1,0,0]
	v_pk_fma_f32 v[10:11], v[218:219], v[104:105], v[10:11] op_sel:[1,0,0]
	v_pk_fma_f32 v[12:13], v[218:219], v[106:107], v[12:13] op_sel:[1,0,0]
	v_pk_fma_f32 v[38:39], v[212:213], v[104:105], v[38:39] op_sel_hi:[0,1,1]
	v_pk_fma_f32 v[40:41], v[212:213], v[106:107], v[40:41] op_sel_hi:[0,1,1]
	v_pk_fma_f32 v[22:23], v[216:217], v[104:105], v[22:23] op_sel_hi:[0,1,1]
	v_pk_fma_f32 v[24:25], v[216:217], v[106:107], v[24:25] op_sel_hi:[0,1,1]
	v_pk_fma_f32 v[6:7], v[220:221], v[104:105], v[6:7] op_sel_hi:[0,1,1]
	v_pk_fma_f32 v[8:9], v[220:221], v[106:107], v[8:9] op_sel_hi:[0,1,1]
	v_pk_fma_f32 v[30:31], v[212:213], v[104:105], v[30:31] op_sel:[1,0,0]
	v_pk_fma_f32 v[32:33], v[212:213], v[106:107], v[32:33] op_sel:[1,0,0]
	v_pk_fma_f32 v[18:19], v[216:217], v[104:105], v[18:19] op_sel:[1,0,0]
	v_pk_fma_f32 v[20:21], v[216:217], v[106:107], v[20:21] op_sel:[1,0,0]
	v_pk_fma_f32 v[2:3], v[220:221], v[104:105], v[2:3] op_sel:[1,0,0]
	v_pk_fma_f32 v[4:5], v[220:221], v[106:107], v[4:5] op_sel:[1,0,0]
	ds_read_b128 v[210:213], v74 offset:4160
	ds_read_b128 v[214:217], v74 offset:4176
	ds_read_b128 v[218:221], v74 offset:4192
	s_waitcnt vmcnt(24) lgkmcnt(3)
	v_pk_fma_f32 v[46:47], v[222:223], v[108:109], v[46:47] op_sel_hi:[0,1,1]
	v_pk_fma_f32 v[48:49], v[222:223], v[110:111], v[48:49] op_sel_hi:[0,1,1]
	v_pk_fma_f32 v[34:35], v[226:227], v[108:109], v[34:35] op_sel_hi:[0,1,1]
	v_pk_fma_f32 v[36:37], v[226:227], v[110:111], v[36:37] op_sel_hi:[0,1,1]
	v_pk_fma_f32 v[14:15], v[230:231], v[108:109], v[14:15] op_sel_hi:[0,1,1]
	v_pk_fma_f32 v[16:17], v[230:231], v[110:111], v[16:17] op_sel_hi:[0,1,1]
	v_pk_fma_f32 v[42:43], v[222:223], v[108:109], v[42:43] op_sel:[1,0,0]
	v_pk_fma_f32 v[44:45], v[222:223], v[110:111], v[44:45] op_sel:[1,0,0]
	v_pk_fma_f32 v[26:27], v[226:227], v[108:109], v[26:27] op_sel:[1,0,0]
	v_pk_fma_f32 v[28:29], v[226:227], v[110:111], v[28:29] op_sel:[1,0,0]
	v_pk_fma_f32 v[10:11], v[230:231], v[108:109], v[10:11] op_sel:[1,0,0]
	v_pk_fma_f32 v[12:13], v[230:231], v[110:111], v[12:13] op_sel:[1,0,0]
	v_pk_fma_f32 v[38:39], v[224:225], v[108:109], v[38:39] op_sel_hi:[0,1,1]
	v_pk_fma_f32 v[40:41], v[224:225], v[110:111], v[40:41] op_sel_hi:[0,1,1]
	v_pk_fma_f32 v[22:23], v[228:229], v[108:109], v[22:23] op_sel_hi:[0,1,1]
	v_pk_fma_f32 v[24:25], v[228:229], v[110:111], v[24:25] op_sel_hi:[0,1,1]
	v_pk_fma_f32 v[6:7], v[232:233], v[108:109], v[6:7] op_sel_hi:[0,1,1]
	v_pk_fma_f32 v[8:9], v[232:233], v[110:111], v[8:9] op_sel_hi:[0,1,1]
	v_pk_fma_f32 v[30:31], v[224:225], v[108:109], v[30:31] op_sel:[1,0,0]
	v_pk_fma_f32 v[32:33], v[224:225], v[110:111], v[32:33] op_sel:[1,0,0]
	v_pk_fma_f32 v[18:19], v[228:229], v[108:109], v[18:19] op_sel:[1,0,0]
	v_pk_fma_f32 v[20:21], v[228:229], v[110:111], v[20:21] op_sel:[1,0,0]
	v_pk_fma_f32 v[2:3], v[232:233], v[108:109], v[2:3] op_sel:[1,0,0]
	v_pk_fma_f32 v[4:5], v[232:233], v[110:111], v[4:5] op_sel:[1,0,0]
	ds_read_b128 v[222:225], v74 offset:6240
	ds_read_b128 v[226:229], v74 offset:6256
	ds_read_b128 v[230:233], v74 offset:6272
	s_waitcnt vmcnt(23) lgkmcnt(3)
	v_pk_fma_f32 v[46:47], v[210:211], v[112:113], v[46:47] op_sel_hi:[0,1,1]
	v_pk_fma_f32 v[48:49], v[210:211], v[114:115], v[48:49] op_sel_hi:[0,1,1]
	v_pk_fma_f32 v[34:35], v[214:215], v[112:113], v[34:35] op_sel_hi:[0,1,1]
	v_pk_fma_f32 v[36:37], v[214:215], v[114:115], v[36:37] op_sel_hi:[0,1,1]
	v_pk_fma_f32 v[14:15], v[218:219], v[112:113], v[14:15] op_sel_hi:[0,1,1]
	v_pk_fma_f32 v[16:17], v[218:219], v[114:115], v[16:17] op_sel_hi:[0,1,1]
	v_pk_fma_f32 v[42:43], v[210:211], v[112:113], v[42:43] op_sel:[1,0,0]
	v_pk_fma_f32 v[44:45], v[210:211], v[114:115], v[44:45] op_sel:[1,0,0]
	v_pk_fma_f32 v[26:27], v[214:215], v[112:113], v[26:27] op_sel:[1,0,0]
	v_pk_fma_f32 v[28:29], v[214:215], v[114:115], v[28:29] op_sel:[1,0,0]
	v_pk_fma_f32 v[10:11], v[218:219], v[112:113], v[10:11] op_sel:[1,0,0]
	v_pk_fma_f32 v[12:13], v[218:219], v[114:115], v[12:13] op_sel:[1,0,0]
	v_pk_fma_f32 v[38:39], v[212:213], v[112:113], v[38:39] op_sel_hi:[0,1,1]
	v_pk_fma_f32 v[40:41], v[212:213], v[114:115], v[40:41] op_sel_hi:[0,1,1]
	v_pk_fma_f32 v[22:23], v[216:217], v[112:113], v[22:23] op_sel_hi:[0,1,1]
	v_pk_fma_f32 v[24:25], v[216:217], v[114:115], v[24:25] op_sel_hi:[0,1,1]
	v_pk_fma_f32 v[6:7], v[220:221], v[112:113], v[6:7] op_sel_hi:[0,1,1]
	v_pk_fma_f32 v[8:9], v[220:221], v[114:115], v[8:9] op_sel_hi:[0,1,1]
	v_pk_fma_f32 v[30:31], v[212:213], v[112:113], v[30:31] op_sel:[1,0,0]
	v_pk_fma_f32 v[32:33], v[212:213], v[114:115], v[32:33] op_sel:[1,0,0]
	v_pk_fma_f32 v[18:19], v[216:217], v[112:113], v[18:19] op_sel:[1,0,0]
	v_pk_fma_f32 v[20:21], v[216:217], v[114:115], v[20:21] op_sel:[1,0,0]
	v_pk_fma_f32 v[2:3], v[220:221], v[112:113], v[2:3] op_sel:[1,0,0]
	v_pk_fma_f32 v[4:5], v[220:221], v[114:115], v[4:5] op_sel:[1,0,0]
	ds_read_b128 v[210:213], v74 offset:8320
	ds_read_b128 v[214:217], v74 offset:8336
	ds_read_b128 v[218:221], v74 offset:8352
	s_waitcnt vmcnt(22) lgkmcnt(3)
; #define LAS __attribute__((address_space(3)))
; __device__ __forceinline__ void phase_prologue(const Frame& F) {
;     ...
;                 if (tid < 480) {
; #pragma unroll 2
;                     for (int kk = kl; kk < 256; kk += 10) {
;                         const f32x4 w4 = *(const f32x4*)(wada + (size_t)(kc * 256 + kk) * MODW + 48 * cb + 4 * cgp);
;                         const f32x2 w01 = (f32x2){w4[0], w4[1]}, w23 = (f32x2){w4[2], w4[3]};
;                         const LAS f32x4* sp = (const LAS f32x4*)(sT + kk * 52 + 12 * cdg);
;                         const f32x4 s0 = sp[0], s1 = sp[1], s2 = sp[2];
; #pragma unroll
;                         for (int c = 0; c < 4; ++c) {
;                             acc[c][0] = __builtin_elementwise_fma((f32x2){s0[c], s0[c]}, w01, acc[c][0]); acc[c][1] = __builtin_elementwise_fma((f32x2){s0[c], s0[c]}, w23, acc[c][1]);
;                             acc[4 + c][0] = __builtin_elementwise_fma((f32x2){s1[c], s1[c]}, w01, acc[4 + c][0]); acc[4 + c][1] = __builtin_elementwise_fma((f32x2){s1[c], s1[c]}, w23, acc[4 + c][1]);
;                             acc[8 + c][0] = __builtin_elementwise_fma((f32x2){s2[c], s2[c]}, w01, acc[8 + c][0]); acc[8 + c][1] = __builtin_elementwise_fma((f32x2){s2[c], s2[c]}, w23, acc[8 + c][1]); }
;                     }
	v_pk_fma_f32 v[46:47], v[222:223], v[116:117], v[46:47] op_sel_hi:[0,1,1]
	v_pk_fma_f32 v[48:49], v[222:223], v[118:119], v[48:49] op_sel_hi:[0,1,1]
	v_pk_fma_f32 v[34:35], v[226:227], v[116:117], v[34:35] op_sel_hi:[0,1,1]
	v_pk_fma_f32 v[36:37], v[226:227], v[118:119], v[36:37] op_sel_hi:[0,1,1]
	v_pk_fma_f32 v[14:15], v[230:231], v[116:117], v[14:15] op_sel_hi:[0,1,1]
	v_pk_fma_f32 v[16:17], v[230:231], v[118:119], v[16:17] op_sel_hi:[0,1,1]
	v_pk_fma_f32 v[42:43], v[222:223], v[116:117], v[42:43] op_sel:[1,0,0]
	v_pk_fma_f32 v[44:45], v[222:223], v[118:119], v[44:45] op_sel:[1,0,0]
	v_pk_fma_f32 v[26:27], v[226:227], v[116:117], v[26:27] op_sel:[1,0,0]
	v_pk_fma_f32 v[28:29], v[226:227], v[118:119], v[28:29] op_sel:[1,0,0]
	v_pk_fma_f32 v[10:11], v[230:231], v[116:117], v[10:11] op_sel:[1,0,0]
	v_pk_fma_f32 v[12:13], v[230:231], v[118:119], v[12:13] op_sel:[1,0,0]
	v_pk_fma_f32 v[38:39], v[224:225], v[116:117], v[38:39] op_sel_hi:[0,1,1]
	v_pk_fma_f32 v[40:41], v[224:225], v[118:119], v[40:41] op_sel_hi:[0,1,1]
	v_pk_fma_f32 v[22:23], v[228:229], v[116:117], v[22:23] op_sel_hi:[0,1,1]
	v_pk_fma_f32 v[24:25], v[228:229], v[118:119], v[24:25] op_sel_hi:[0,1,1]
	v_pk_fma_f32 v[6:7], v[232:233], v[116:117], v[6:7] op_sel_hi:[0,1,1]
	v_pk_fma_f32 v[8:9], v[232:233], v[118:119], v[8:9] op_sel_hi:[0,1,1]
	v_pk_fma_f32 v[30:31], v[224:225], v[116:117], v[30:31] op_sel:[1,0,0]
	v_pk_fma_f32 v[32:33], v[224:225], v[118:119], v[32:33] op_sel:[1,0,0]
	v_pk_fma_f32 v[18:19], v[228:229], v[116:117], v[18:19] op_sel:[1,0,0]
	v_pk_fma_f32 v[20:21], v[228:229], v[118:119], v[20:21] op_sel:[1,0,0]
	v_pk_fma_f32 v[2:3], v[232:233], v[116:117], v[2:3] op_sel:[1,0,0]
	v_pk_fma_f32 v[4:5], v[232:233], v[118:119], v[4:5] op_sel:[1,0,0]
	ds_read_b128 v[222:225], v74 offset:10400
	ds_read_b128 v[226:229], v74 offset:10416
	ds_read_b128 v[230:233], v74 offset:10432
	s_waitcnt vmcnt(21) lgkmcnt(3)
	v_pk_fma_f32 v[46:47], v[210:211], v[120:121], v[46:47] op_sel_hi:[0,1,1]
	v_pk_fma_f32 v[48:49], v[210:211], v[122:123], v[48:49] op_sel_hi:[0,1,1]
	v_pk_fma_f32 v[34:35], v[214:215], v[120:121], v[34:35] op_sel_hi:[0,1,1]
	v_pk_fma_f32 v[36:37], v[214:215], v[122:123], v[36:37] op_sel_hi:[0,1,1]
	v_pk_fma_f32 v[14:15], v[218:219], v[120:121], v[14:15] op_sel_hi:[0,1,1]
	v_pk_fma_f32 v[16:17], v[218:219], v[122:123], v[16:17] op_sel_hi:[0,1,1]
	v_pk_fma_f32 v[42:43], v[210:211], v[120:121], v[42:43] op_sel:[1,0,0]
	v_pk_fma_f32 v[44:45], v[210:211], v[122:123], v[44:45] op_sel:[1,0,0]
	v_pk_fma_f32 v[26:27], v[214:215], v[120:121], v[26:27] op_sel:[1,0,0]
	v_pk_fma_f32 v[28:29], v[214:215], v[122:123], v[28:29] op_sel:[1,0,0]
	v_pk_fma_f32 v[10:11], v[218:219], v[120:121], v[10:11] op_sel:[1,0,0]
	v_pk_fma_f32 v[12:13], v[218:219], v[122:123], v[12:13] op_sel:[1,0,0]
	v_pk_fma_f32 v[38:39], v[212:213], v[120:121], v[38:39] op_sel_hi:[0,1,1]
	v_pk_fma_f32 v[40:41], v[212:213], v[122:123], v[40:41] op_sel_hi:[0,1,1]
	v_pk_fma_f32 v[22:23], v[216:217], v[120:121], v[22:23] op_sel_hi:[0,1,1]
	v_pk_fma_f32 v[24:25], v[216:217], v[122:123], v[24:25] op_sel_hi:[0,1,1]
	v_pk_fma_f32 v[6:7], v[220:221], v[120:121], v[6:7] op_sel_hi:[0,1,1]
	v_pk_fma_f32 v[8:9], v[220:221], v[122:123], v[8:9] op_sel_hi:[0,1,1]
	v_pk_fma_f32 v[30:31], v[212:213], v[120:121], v[30:31] op_sel:[1,0,0]
	v_pk_fma_f32 v[32:33], v[212:213], v[122:123], v[32:33] op_sel:[1,0,0]
	v_pk_fma_f32 v[18:19], v[216:217], v[120:121], v[18:19] op_sel:[1,0,0]
	v_pk_fma_f32 v[20:21], v[216:217], v[122:123], v[20:21] op_sel:[1,0,0]
	v_pk_fma_f32 v[2:3], v[220:221], v[120:121], v[2:3] op_sel:[1,0,0]
	v_pk_fma_f32 v[4:5], v[220:221], v[122:123], v[4:5] op_sel:[1,0,0]
	ds_read_b128 v[210:213], v74 offset:12480
	ds_read_b128 v[214:217], v74 offset:12496
	ds_read_b128 v[218:221], v74 offset:12512
	s_waitcnt vmcnt(20) lgkmcnt(3)
	v_pk_fma_f32 v[46:47], v[222:223], v[124:125], v[46:47] op_sel_hi:[0,1,1]
	v_pk_fma_f32 v[48:49], v[222:223], v[126:127], v[48:49] op_sel_hi:[0,1,1]
	v_pk_fma_f32 v[34:35], v[226:227], v[124:125], v[34:35] op_sel_hi:[0,1,1]
	v_pk_fma_f32 v[36:37], v[226:227], v[126:127], v[36:37] op_sel_hi:[0,1,1]
	v_pk_fma_f32 v[14:15], v[230:231], v[124:125], v[14:15] op_sel_hi:[0,1,1]
	v_pk_fma_f32 v[16:17], v[230:231], v[126:127], v[16:17] op_sel_hi:[0,1,1]
	v_pk_fma_f32 v[42:43], v[222:223], v[124:125], v[42:43] op_sel:[1,0,0]
	v_pk_fma_f32 v[44:45], v[222:223], v[126:127], v[44:45] op_sel:[1,0,0]
	v_pk_fma_f32 v[26:27], v[226:227], v[124:125], v[26:27] op_sel:[1,0,0]
	v_pk_fma_f32 v[28:29], v[226:227], v[126:127], v[28:29] op_sel:[1,0,0]
	v_pk_fma_f32 v[10:11], v[230:231], v[124:125], v[10:11] op_sel:[1,0,0]
	v_pk_fma_f32 v[12:13], v[230:231], v[126:127], v[12:13] op_sel:[1,0,0]
	v_pk_fma_f32 v[38:39], v[224:225], v[124:125], v[38:39] op_sel_hi:[0,1,1]
	v_pk_fma_f32 v[40:41], v[224:225], v[126:127], v[40:41] op_sel_hi:[0,1,1]
	v_pk_fma_f32 v[22:23], v[228:229], v[124:125], v[22:23] op_sel_hi:[0,1,1]
	v_pk_fma_f32 v[24:25], v[228:229], v[126:127], v[24:25] op_sel_hi:[0,1,1]
	v_pk_fma_f32 v[6:7], v[232:233], v[124:125], v[6:7] op_sel_hi:[0,1,1]
	v_pk_fma_f32 v[8:9], v[232:233], v[126:127], v[8:9] op_sel_hi:[0,1,1]
	v_pk_fma_f32 v[30:31], v[224:225], v[124:125], v[30:31] op_sel:[1,0,0]
	v_pk_fma_f32 v[32:33], v[224:225], v[126:127], v[32:33] op_sel:[1,0,0]
	v_pk_fma_f32 v[18:19], v[228:229], v[124:125], v[18:19] op_sel:[1,0,0]
	v_pk_fma_f32 v[20:21], v[228:229], v[126:127], v[20:21] op_sel:[1,0,0]
	v_pk_fma_f32 v[2:3], v[232:233], v[124:125], v[2:3] op_sel:[1,0,0]
	v_pk_fma_f32 v[4:5], v[232:233], v[126:127], v[4:5] op_sel:[1,0,0]
	ds_read_b128 v[222:225], v74 offset:14560
	ds_read_b128 v[226:229], v74 offset:14576
	ds_read_b128 v[230:233], v74 offset:14592
	s_waitcnt vmcnt(19) lgkmcnt(3)
; #define LAS __attribute__((address_space(3)))
; __device__ __forceinline__ void phase_prologue(const Frame& F) {
;     ...
;                 if (tid < 480) {
; #pragma unroll 2
;                     for (int kk = kl; kk < 256; kk += 10) {
;                         const f32x4 w4 = *(const f32x4*)(wada + (size_t)(kc * 256 + kk) * MODW + 48 * cb + 4 * cgp);
;                         const f32x2 w01 = (f32x2){w4[0], w4[1]}, w23 = (f32x2){w4[2], w4[3]};
;                         const LAS f32x4* sp = (const LAS f32x4*)(sT + kk * 52 + 12 * cdg);
;                         const f32x4 s0 = sp[0], s1 = sp[1], s2 = sp[2];
; #pragma unroll
;                         for (int c = 0; c < 4; ++c) {
;                             acc[c][0] = __builtin_elementwise_fma((f32x2){s0[c], s0[c]}, w01, acc[c][0]); acc[c][1] = __builtin_elementwise_fma((f32x2){s0[c], s0[c]}, w23, acc[c][1]);
;                             acc[4 + c][0] = __builtin_elementwise_fma((f32x2){s1[c], s1[c]}, w01, acc[4 + c][0]); acc[4 + c][1] = __builtin_elementwise_fma((f32x2){s1[c], s1[c]}, w23, acc[4 + c][1]);
;                             acc[8 + c][0] = __builtin_elementwise_fma((f32x2){s2[c], s2[c]}, w01, acc[8 + c][0]); acc[8 + c][1] = __builtin_elementwise_fma((f32x2){s2[c], s2[c]}, w23, acc[8 + c][1]); }
;                     }
	v_pk_fma_f32 v[46:47], v[210:211], v[128:129], v[46:47] op_sel_hi:[0,1,1]
	v_pk_fma_f32 v[48:49], v[210:211], v[130:131], v[48:49] op_sel_hi:[0,1,1]
	v_pk_fma_f32 v[34:35], v[214:215], v[128:129], v[34:35] op_sel_hi:[0,1,1]
	v_pk_fma_f32 v[36:37], v[214:215], v[130:131], v[36:37] op_sel_hi:[0,1,1]
	v_pk_fma_f32 v[14:15], v[218:219], v[128:129], v[14:15] op_sel_hi:[0,1,1]
	v_pk_fma_f32 v[16:17], v[218:219], v[130:131], v[16:17] op_sel_hi:[0,1,1]
	v_pk_fma_f32 v[42:43], v[210:211], v[128:129], v[42:43] op_sel:[1,0,0]
	v_pk_fma_f32 v[44:45], v[210:211], v[130:131], v[44:45] op_sel:[1,0,0]
	v_pk_fma_f32 v[26:27], v[214:215], v[128:129], v[26:27] op_sel:[1,0,0]
	v_pk_fma_f32 v[28:29], v[214:215], v[130:131], v[28:29] op_sel:[1,0,0]
	v_pk_fma_f32 v[10:11], v[218:219], v[128:129], v[10:11] op_sel:[1,0,0]
	v_pk_fma_f32 v[12:13], v[218:219], v[130:131], v[12:13] op_sel:[1,0,0]
	v_pk_fma_f32 v[38:39], v[212:213], v[128:129], v[38:39] op_sel_hi:[0,1,1]
	v_pk_fma_f32 v[40:41], v[212:213], v[130:131], v[40:41] op_sel_hi:[0,1,1]
	v_pk_fma_f32 v[22:23], v[216:217], v[128:129], v[22:23] op_sel_hi:[0,1,1]
	v_pk_fma_f32 v[24:25], v[216:217], v[130:131], v[24:25] op_sel_hi:[0,1,1]
	v_pk_fma_f32 v[6:7], v[220:221], v[128:129], v[6:7] op_sel_hi:[0,1,1]
	v_pk_fma_f32 v[8:9], v[220:221], v[130:131], v[8:9] op_sel_hi:[0,1,1]
	v_pk_fma_f32 v[30:31], v[212:213], v[128:129], v[30:31] op_sel:[1,0,0]
	v_pk_fma_f32 v[32:33], v[212:213], v[130:131], v[32:33] op_sel:[1,0,0]
	v_pk_fma_f32 v[18:19], v[216:217], v[128:129], v[18:19] op_sel:[1,0,0]
	v_pk_fma_f32 v[20:21], v[216:217], v[130:131], v[20:21] op_sel:[1,0,0]
	v_pk_fma_f32 v[2:3], v[220:221], v[128:129], v[2:3] op_sel:[1,0,0]
	v_pk_fma_f32 v[4:5], v[220:221], v[130:131], v[4:5] op_sel:[1,0,0]
	ds_read_b128 v[210:213], v74 offset:16640
	ds_read_b128 v[214:217], v74 offset:16656
	ds_read_b128 v[218:221], v74 offset:16672
	s_waitcnt vmcnt(18) lgkmcnt(3)
	v_pk_fma_f32 v[46:47], v[222:223], v[132:133], v[46:47] op_sel_hi:[0,1,1]
	v_pk_fma_f32 v[48:49], v[222:223], v[134:135], v[48:49] op_sel_hi:[0,1,1]
	v_pk_fma_f32 v[34:35], v[226:227], v[132:133], v[34:35] op_sel_hi:[0,1,1]
	v_pk_fma_f32 v[36:37], v[226:227], v[134:135], v[36:37] op_sel_hi:[0,1,1]
	v_pk_fma_f32 v[14:15], v[230:231], v[132:133], v[14:15] op_sel_hi:[0,1,1]
	v_pk_fma_f32 v[16:17], v[230:231], v[134:135], v[16:17] op_sel_hi:[0,1,1]
	v_pk_fma_f32 v[42:43], v[222:223], v[132:133], v[42:43] op_sel:[1,0,0]
	v_pk_fma_f32 v[44:45], v[222:223], v[134:135], v[44:45] op_sel:[1,0,0]
	v_pk_fma_f32 v[26:27], v[226:227], v[132:133], v[26:27] op_sel:[1,0,0]
	v_pk_fma_f32 v[28:29], v[226:227], v[134:135], v[28:29] op_sel:[1,0,0]
	v_pk_fma_f32 v[10:11], v[230:231], v[132:133], v[10:11] op_sel:[1,0,0]
	v_pk_fma_f32 v[12:13], v[230:231], v[134:135], v[12:13] op_sel:[1,0,0]
	v_pk_fma_f32 v[38:39], v[224:225], v[132:133], v[38:39] op_sel_hi:[0,1,1]
	v_pk_fma_f32 v[40:41], v[224:225], v[134:135], v[40:41] op_sel_hi:[0,1,1]
	v_pk_fma_f32 v[22:23], v[228:229], v[132:133], v[22:23] op_sel_hi:[0,1,1]
	v_pk_fma_f32 v[24:25], v[228:229], v[134:135], v[24:25] op_sel_hi:[0,1,1]
	v_pk_fma_f32 v[6:7], v[232:233], v[132:133], v[6:7] op_sel_hi:[0,1,1]
	v_pk_fma_f32 v[8:9], v[232:233], v[134:135], v[8:9] op_sel_hi:[0,1,1]
	v_pk_fma_f32 v[30:31], v[224:225], v[132:133], v[30:31] op_sel:[1,0,0]
	v_pk_fma_f32 v[32:33], v[224:225], v[134:135], v[32:33] op_sel:[1,0,0]
	v_pk_fma_f32 v[18:19], v[228:229], v[132:133], v[18:19] op_sel:[1,0,0]
	v_pk_fma_f32 v[20:21], v[228:229], v[134:135], v[20:21] op_sel:[1,0,0]
	v_pk_fma_f32 v[2:3], v[232:233], v[132:133], v[2:3] op_sel:[1,0,0]
	v_pk_fma_f32 v[4:5], v[232:233], v[134:135], v[4:5] op_sel:[1,0,0]
	ds_read_b128 v[222:225], v74 offset:18720
	ds_read_b128 v[226:229], v74 offset:18736
	ds_read_b128 v[230:233], v74 offset:18752
	s_waitcnt vmcnt(17) lgkmcnt(3)
	v_pk_fma_f32 v[46:47], v[210:211], v[136:137], v[46:47] op_sel_hi:[0,1,1]
	v_pk_fma_f32 v[48:49], v[210:211], v[138:139], v[48:49] op_sel_hi:[0,1,1]
	v_pk_fma_f32 v[34:35], v[214:215], v[136:137], v[34:35] op_sel_hi:[0,1,1]
	v_pk_fma_f32 v[36:37], v[214:215], v[138:139], v[36:37] op_sel_hi:[0,1,1]
	v_pk_fma_f32 v[14:15], v[218:219], v[136:137], v[14:15] op_sel_hi:[0,1,1]
	v_pk_fma_f32 v[16:17], v[218:219], v[138:139], v[16:17] op_sel_hi:[0,1,1]
	v_pk_fma_f32 v[42:43], v[210:211], v[136:137], v[42:43] op_sel:[1,0,0]
	v_pk_fma_f32 v[44:45], v[210:211], v[138:139], v[44:45] op_sel:[1,0,0]
	v_pk_fma_f32 v[26:27], v[214:215], v[136:137], v[26:27] op_sel:[1,0,0]
	v_pk_fma_f32 v[28:29], v[214:215], v[138:139], v[28:29] op_sel:[1,0,0]
	v_pk_fma_f32 v[10:11], v[218:219], v[136:137], v[10:11] op_sel:[1,0,0]
	v_pk_fma_f32 v[12:13], v[218:219], v[138:139], v[12:13] op_sel:[1,0,0]
	v_pk_fma_f32 v[38:39], v[212:213], v[136:137], v[38:39] op_sel_hi:[0,1,1]
	v_pk_fma_f32 v[40:41], v[212:213], v[138:139], v[40:41] op_sel_hi:[0,1,1]
	v_pk_fma_f32 v[22:23], v[216:217], v[136:137], v[22:23] op_sel_hi:[0,1,1]
	v_pk_fma_f32 v[24:25], v[216:217], v[138:139], v[24:25] op_sel_hi:[0,1,1]
	v_pk_fma_f32 v[6:7], v[220:221], v[136:137], v[6:7] op_sel_hi:[0,1,1]
	v_pk_fma_f32 v[8:9], v[220:221], v[138:139], v[8:9] op_sel_hi:[0,1,1]
	v_pk_fma_f32 v[30:31], v[212:213], v[136:137], v[30:31] op_sel:[1,0,0]
	v_pk_fma_f32 v[32:33], v[212:213], v[138:139], v[32:33] op_sel:[1,0,0]
	v_pk_fma_f32 v[18:19], v[216:217], v[136:137], v[18:19] op_sel:[1,0,0]
	v_pk_fma_f32 v[20:21], v[216:217], v[138:139], v[20:21] op_sel:[1,0,0]
	v_pk_fma_f32 v[2:3], v[220:221], v[136:137], v[2:3] op_sel:[1,0,0]
	v_pk_fma_f32 v[4:5], v[220:221], v[138:139], v[4:5] op_sel:[1,0,0]
	ds_read_b128 v[210:213], v74 offset:20800
	ds_read_b128 v[214:217], v74 offset:20816
	ds_read_b128 v[218:221], v74 offset:20832
	s_waitcnt vmcnt(16) lgkmcnt(3)
; #define LAS __attribute__((address_space(3)))
; __device__ __forceinline__ void phase_prologue(const Frame& F) {
;     ...
;                 if (tid < 480) {
; #pragma unroll 2
;                     for (int kk = kl; kk < 256; kk += 10) {
;                         const f32x4 w4 = *(const f32x4*)(wada + (size_t)(kc * 256 + kk) * MODW + 48 * cb + 4 * cgp);
;                         const f32x2 w01 = (f32x2){w4[0], w4[1]}, w23 = (f32x2){w4[2], w4[3]};
;                         const LAS f32x4* sp = (const LAS f32x4*)(sT + kk * 52 + 12 * cdg);
;                         const f32x4 s0 = sp[0], s1 = sp[1], s2 = sp[2];
; #pragma unroll
;                         for (int c = 0; c < 4; ++c) {
;                             acc[c][0] = __builtin_elementwise_fma((f32x2){s0[c], s0[c]}, w01, acc[c][0]); acc[c][1] = __builtin_elementwise_fma((f32x2){s0[c], s0[c]}, w23, acc[c][1]);
;                             acc[4 + c][0] = __builtin_elementwise_fma((f32x2){s1[c], s1[c]}, w01, acc[4 + c][0]); acc[4 + c][1] = __builtin_elementwise_fma((f32x2){s1[c], s1[c]}, w23, acc[4 + c][1]);
;                             acc[8 + c][0] = __builtin_elementwise_fma((f32x2){s2[c], s2[c]}, w01, acc[8 + c][0]); acc[8 + c][1] = __builtin_elementwise_fma((f32x2){s2[c], s2[c]}, w23, acc[8 + c][1]); }
;                     }
	v_pk_fma_f32 v[46:47], v[222:223], v[140:141], v[46:47] op_sel_hi:[0,1,1]
	v_pk_fma_f32 v[48:49], v[222:223], v[142:143], v[48:49] op_sel_hi:[0,1,1]
	v_pk_fma_f32 v[34:35], v[226:227], v[140:141], v[34:35] op_sel_hi:[0,1,1]
	v_pk_fma_f32 v[36:37], v[226:227], v[142:143], v[36:37] op_sel_hi:[0,1,1]
	v_pk_fma_f32 v[14:15], v[230:231], v[140:141], v[14:15] op_sel_hi:[0,1,1]
	v_pk_fma_f32 v[16:17], v[230:231], v[142:143], v[16:17] op_sel_hi:[0,1,1]
	v_pk_fma_f32 v[42:43], v[222:223], v[140:141], v[42:43] op_sel:[1,0,0]
	v_pk_fma_f32 v[44:45], v[222:223], v[142:143], v[44:45] op_sel:[1,0,0]
	v_pk_fma_f32 v[26:27], v[226:227], v[140:141], v[26:27] op_sel:[1,0,0]
	v_pk_fma_f32 v[28:29], v[226:227], v[142:143], v[28:29] op_sel:[1,0,0]
	v_pk_fma_f32 v[10:11], v[230:231], v[140:141], v[10:11] op_sel:[1,0,0]
	v_pk_fma_f32 v[12:13], v[230:231], v[142:143], v[12:13] op_sel:[1,0,0]
	v_pk_fma_f32 v[38:39], v[224:225], v[140:141], v[38:39] op_sel_hi:[0,1,1]
	v_pk_fma_f32 v[40:41], v[224:225], v[142:143], v[40:41] op_sel_hi:[0,1,1]
	v_pk_fma_f32 v[22:23], v[228:229], v[140:141], v[22:23] op_sel_hi:[0,1,1]
	v_pk_fma_f32 v[24:25], v[228:229], v[142:143], v[24:25] op_sel_hi:[0,1,1]
	v_pk_fma_f32 v[6:7], v[232:233], v[140:141], v[6:7] op_sel_hi:[0,1,1]
	v_pk_fma_f32 v[8:9], v[232:233], v[142:143], v[8:9] op_sel_hi:[0,1,1]
	v_pk_fma_f32 v[30:31], v[224:225], v[140:141], v[30:31] op_sel:[1,0,0]
	v_pk_fma_f32 v[32:33], v[224:225], v[142:143], v[32:33] op_sel:[1,0,0]
	v_pk_fma_f32 v[18:19], v[228:229], v[140:141], v[18:19] op_sel:[1,0,0]
	v_pk_fma_f32 v[20:21], v[228:229], v[142:143], v[20:21] op_sel:[1,0,0]
	v_pk_fma_f32 v[2:3], v[232:233], v[140:141], v[2:3] op_sel:[1,0,0]
	v_pk_fma_f32 v[4:5], v[232:233], v[142:143], v[4:5] op_sel:[1,0,0]
	ds_read_b128 v[222:225], v74 offset:22880
	ds_read_b128 v[226:229], v74 offset:22896
	ds_read_b128 v[230:233], v74 offset:22912
	s_waitcnt vmcnt(15) lgkmcnt(3)
	v_pk_fma_f32 v[46:47], v[210:211], v[144:145], v[46:47] op_sel_hi:[0,1,1]
	v_pk_fma_f32 v[48:49], v[210:211], v[146:147], v[48:49] op_sel_hi:[0,1,1]
	v_pk_fma_f32 v[34:35], v[214:215], v[144:145], v[34:35] op_sel_hi:[0,1,1]
	v_pk_fma_f32 v[36:37], v[214:215], v[146:147], v[36:37] op_sel_hi:[0,1,1]
	v_pk_fma_f32 v[14:15], v[218:219], v[144:145], v[14:15] op_sel_hi:[0,1,1]
	v_pk_fma_f32 v[16:17], v[218:219], v[146:147], v[16:17] op_sel_hi:[0,1,1]
	v_pk_fma_f32 v[42:43], v[210:211], v[144:145], v[42:43] op_sel:[1,0,0]
	v_pk_fma_f32 v[44:45], v[210:211], v[146:147], v[44:45] op_sel:[1,0,0]
	v_pk_fma_f32 v[26:27], v[214:215], v[144:145], v[26:27] op_sel:[1,0,0]
	v_pk_fma_f32 v[28:29], v[214:215], v[146:147], v[28:29] op_sel:[1,0,0]
	v_pk_fma_f32 v[10:11], v[218:219], v[144:145], v[10:11] op_sel:[1,0,0]
	v_pk_fma_f32 v[12:13], v[218:219], v[146:147], v[12:13] op_sel:[1,0,0]
	v_pk_fma_f32 v[38:39], v[212:213], v[144:145], v[38:39] op_sel_hi:[0,1,1]
	v_pk_fma_f32 v[40:41], v[212:213], v[146:147], v[40:41] op_sel_hi:[0,1,1]
	v_pk_fma_f32 v[22:23], v[216:217], v[144:145], v[22:23] op_sel_hi:[0,1,1]
	v_pk_fma_f32 v[24:25], v[216:217], v[146:147], v[24:25] op_sel_hi:[0,1,1]
	v_pk_fma_f32 v[6:7], v[220:221], v[144:145], v[6:7] op_sel_hi:[0,1,1]
	v_pk_fma_f32 v[8:9], v[220:221], v[146:147], v[8:9] op_sel_hi:[0,1,1]
	v_pk_fma_f32 v[30:31], v[212:213], v[144:145], v[30:31] op_sel:[1,0,0]
	v_pk_fma_f32 v[32:33], v[212:213], v[146:147], v[32:33] op_sel:[1,0,0]
	v_pk_fma_f32 v[18:19], v[216:217], v[144:145], v[18:19] op_sel:[1,0,0]
	v_pk_fma_f32 v[20:21], v[216:217], v[146:147], v[20:21] op_sel:[1,0,0]
	v_pk_fma_f32 v[2:3], v[220:221], v[144:145], v[2:3] op_sel:[1,0,0]
	v_pk_fma_f32 v[4:5], v[220:221], v[146:147], v[4:5] op_sel:[1,0,0]
	ds_read_b128 v[210:213], v74 offset:24960
	ds_read_b128 v[214:217], v74 offset:24976
	ds_read_b128 v[218:221], v74 offset:24992
	s_waitcnt vmcnt(14) lgkmcnt(3)
	v_pk_fma_f32 v[46:47], v[222:223], v[148:149], v[46:47] op_sel_hi:[0,1,1]
	v_pk_fma_f32 v[48:49], v[222:223], v[150:151], v[48:49] op_sel_hi:[0,1,1]
	v_pk_fma_f32 v[34:35], v[226:227], v[148:149], v[34:35] op_sel_hi:[0,1,1]
	v_pk_fma_f32 v[36:37], v[226:227], v[150:151], v[36:37] op_sel_hi:[0,1,1]
	v_pk_fma_f32 v[14:15], v[230:231], v[148:149], v[14:15] op_sel_hi:[0,1,1]
	v_pk_fma_f32 v[16:17], v[230:231], v[150:151], v[16:17] op_sel_hi:[0,1,1]
	v_pk_fma_f32 v[42:43], v[222:223], v[148:149], v[42:43] op_sel:[1,0,0]
	v_pk_fma_f32 v[44:45], v[222:223], v[150:151], v[44:45] op_sel:[1,0,0]
	v_pk_fma_f32 v[26:27], v[226:227], v[148:149], v[26:27] op_sel:[1,0,0]
	v_pk_fma_f32 v[28:29], v[226:227], v[150:151], v[28:29] op_sel:[1,0,0]
	v_pk_fma_f32 v[10:11], v[230:231], v[148:149], v[10:11] op_sel:[1,0,0]
	v_pk_fma_f32 v[12:13], v[230:231], v[150:151], v[12:13] op_sel:[1,0,0]
	v_pk_fma_f32 v[38:39], v[224:225], v[148:149], v[38:39] op_sel_hi:[0,1,1]
	v_pk_fma_f32 v[40:41], v[224:225], v[150:151], v[40:41] op_sel_hi:[0,1,1]
	v_pk_fma_f32 v[22:23], v[228:229], v[148:149], v[22:23] op_sel_hi:[0,1,1]
	v_pk_fma_f32 v[24:25], v[228:229], v[150:151], v[24:25] op_sel_hi:[0,1,1]
	v_pk_fma_f32 v[6:7], v[232:233], v[148:149], v[6:7] op_sel_hi:[0,1,1]
	v_pk_fma_f32 v[8:9], v[232:233], v[150:151], v[8:9] op_sel_hi:[0,1,1]
	v_pk_fma_f32 v[30:31], v[224:225], v[148:149], v[30:31] op_sel:[1,0,0]
	v_pk_fma_f32 v[32:33], v[224:225], v[150:151], v[32:33] op_sel:[1,0,0]
	v_pk_fma_f32 v[18:19], v[228:229], v[148:149], v[18:19] op_sel:[1,0,0]
	v_pk_fma_f32 v[20:21], v[228:229], v[150:151], v[20:21] op_sel:[1,0,0]
	v_pk_fma_f32 v[2:3], v[232:233], v[148:149], v[2:3] op_sel:[1,0,0]
	v_pk_fma_f32 v[4:5], v[232:233], v[150:151], v[4:5] op_sel:[1,0,0]
	ds_read_b128 v[222:225], v74 offset:27040
	ds_read_b128 v[226:229], v74 offset:27056
	ds_read_b128 v[230:233], v74 offset:27072
	s_waitcnt vmcnt(13) lgkmcnt(3)
; #define LAS __attribute__((address_space(3)))
; __device__ __forceinline__ void phase_prologue(const Frame& F) {
;     ...
;                 if (tid < 480) {
; #pragma unroll 2
;                     for (int kk = kl; kk < 256; kk += 10) {
;                         const f32x4 w4 = *(const f32x4*)(wada + (size_t)(kc * 256 + kk) * MODW + 48 * cb + 4 * cgp);
;                         const f32x2 w01 = (f32x2){w4[0], w4[1]}, w23 = (f32x2){w4[2], w4[3]};
;                         const LAS f32x4* sp = (const LAS f32x4*)(sT + kk * 52 + 12 * cdg);
;                         const f32x4 s0 = sp[0], s1 = sp[1], s2 = sp[2];
; #pragma unroll
;                         for (int c = 0; c < 4; ++c) {
;                             acc[c][0] = __builtin_elementwise_fma((f32x2){s0[c], s0[c]}, w01, acc[c][0]); acc[c][1] = __builtin_elementwise_fma((f32x2){s0[c], s0[c]}, w23, acc[c][1]);
;                             acc[4 + c][0] = __builtin_elementwise_fma((f32x2){s1[c], s1[c]}, w01, acc[4 + c][0]); acc[4 + c][1] = __builtin_elementwise_fma((f32x2){s1[c], s1[c]}, w23, acc[4 + c][1]);
;                             acc[8 + c][0] = __builtin_elementwise_fma((f32x2){s2[c], s2[c]}, w01, acc[8 + c][0]); acc[8 + c][1] = __builtin_elementwise_fma((f32x2){s2[c], s2[c]}, w23, acc[8 + c][1]); }
;                     }
	v_pk_fma_f32 v[46:47], v[210:211], v[152:153], v[46:47] op_sel_hi:[0,1,1]
	v_pk_fma_f32 v[48:49], v[210:211], v[154:155], v[48:49] op_sel_hi:[0,1,1]
	v_pk_fma_f32 v[34:35], v[214:215], v[152:153], v[34:35] op_sel_hi:[0,1,1]
	v_pk_fma_f32 v[36:37], v[214:215], v[154:155], v[36:37] op_sel_hi:[0,1,1]
	v_pk_fma_f32 v[14:15], v[218:219], v[152:153], v[14:15] op_sel_hi:[0,1,1]
	v_pk_fma_f32 v[16:17], v[218:219], v[154:155], v[16:17] op_sel_hi:[0,1,1]
	v_pk_fma_f32 v[42:43], v[210:211], v[152:153], v[42:43] op_sel:[1,0,0]
	v_pk_fma_f32 v[44:45], v[210:211], v[154:155], v[44:45] op_sel:[1,0,0]
	v_pk_fma_f32 v[26:27], v[214:215], v[152:153], v[26:27] op_sel:[1,0,0]
	v_pk_fma_f32 v[28:29], v[214:215], v[154:155], v[28:29] op_sel:[1,0,0]
	v_pk_fma_f32 v[10:11], v[218:219], v[152:153], v[10:11] op_sel:[1,0,0]
	v_pk_fma_f32 v[12:13], v[218:219], v[154:155], v[12:13] op_sel:[1,0,0]
	v_pk_fma_f32 v[38:39], v[212:213], v[152:153], v[38:39] op_sel_hi:[0,1,1]
	v_pk_fma_f32 v[40:41], v[212:213], v[154:155], v[40:41] op_sel_hi:[0,1,1]
	v_pk_fma_f32 v[22:23], v[216:217], v[152:153], v[22:23] op_sel_hi:[0,1,1]
	v_pk_fma_f32 v[24:25], v[216:217], v[154:155], v[24:25] op_sel_hi:[0,1,1]
	v_pk_fma_f32 v[6:7], v[220:221], v[152:153], v[6:7] op_sel_hi:[0,1,1]
	v_pk_fma_f32 v[8:9], v[220:221], v[154:155], v[8:9] op_sel_hi:[0,1,1]
	v_pk_fma_f32 v[30:31], v[212:213], v[152:153], v[30:31] op_sel:[1,0,0]
	v_pk_fma_f32 v[32:33], v[212:213], v[154:155], v[32:33] op_sel:[1,0,0]
	v_pk_fma_f32 v[18:19], v[216:217], v[152:153], v[18:19] op_sel:[1,0,0]
	v_pk_fma_f32 v[20:21], v[216:217], v[154:155], v[20:21] op_sel:[1,0,0]
	v_pk_fma_f32 v[2:3], v[220:221], v[152:153], v[2:3] op_sel:[1,0,0]
	v_pk_fma_f32 v[4:5], v[220:221], v[154:155], v[4:5] op_sel:[1,0,0]
	ds_read_b128 v[210:213], v74 offset:29120
	ds_read_b128 v[214:217], v74 offset:29136
	ds_read_b128 v[218:221], v74 offset:29152
	s_waitcnt vmcnt(12) lgkmcnt(3)
	v_pk_fma_f32 v[46:47], v[222:223], v[156:157], v[46:47] op_sel_hi:[0,1,1]
	v_pk_fma_f32 v[48:49], v[222:223], v[158:159], v[48:49] op_sel_hi:[0,1,1]
	v_pk_fma_f32 v[34:35], v[226:227], v[156:157], v[34:35] op_sel_hi:[0,1,1]
	v_pk_fma_f32 v[36:37], v[226:227], v[158:159], v[36:37] op_sel_hi:[0,1,1]
	v_pk_fma_f32 v[14:15], v[230:231], v[156:157], v[14:15] op_sel_hi:[0,1,1]
	v_pk_fma_f32 v[16:17], v[230:231], v[158:159], v[16:17] op_sel_hi:[0,1,1]
	v_pk_fma_f32 v[42:43], v[222:223], v[156:157], v[42:43] op_sel:[1,0,0]
	v_pk_fma_f32 v[44:45], v[222:223], v[158:159], v[44:45] op_sel:[1,0,0]
	v_pk_fma_f32 v[26:27], v[226:227], v[156:157], v[26:27] op_sel:[1,0,0]
	v_pk_fma_f32 v[28:29], v[226:227], v[158:159], v[28:29] op_sel:[1,0,0]
	v_pk_fma_f32 v[10:11], v[230:231], v[156:157], v[10:11] op_sel:[1,0,0]
	v_pk_fma_f32 v[12:13], v[230:231], v[158:159], v[12:13] op_sel:[1,0,0]
	v_pk_fma_f32 v[38:39], v[224:225], v[156:157], v[38:39] op_sel_hi:[0,1,1]
	v_pk_fma_f32 v[40:41], v[224:225], v[158:159], v[40:41] op_sel_hi:[0,1,1]
	v_pk_fma_f32 v[22:23], v[228:229], v[156:157], v[22:23] op_sel_hi:[0,1,1]
	v_pk_fma_f32 v[24:25], v[228:229], v[158:159], v[24:25] op_sel_hi:[0,1,1]
	v_pk_fma_f32 v[6:7], v[232:233], v[156:157], v[6:7] op_sel_hi:[0,1,1]
	v_pk_fma_f32 v[8:9], v[232:233], v[158:159], v[8:9] op_sel_hi:[0,1,1]
	v_pk_fma_f32 v[30:31], v[224:225], v[156:157], v[30:31] op_sel:[1,0,0]
	v_pk_fma_f32 v[32:33], v[224:225], v[158:159], v[32:33] op_sel:[1,0,0]
	v_pk_fma_f32 v[18:19], v[228:229], v[156:157], v[18:19] op_sel:[1,0,0]
	v_pk_fma_f32 v[20:21], v[228:229], v[158:159], v[20:21] op_sel:[1,0,0]
	v_pk_fma_f32 v[2:3], v[232:233], v[156:157], v[2:3] op_sel:[1,0,0]
	v_pk_fma_f32 v[4:5], v[232:233], v[158:159], v[4:5] op_sel:[1,0,0]
	ds_read_b128 v[222:225], v74 offset:31200
	ds_read_b128 v[226:229], v74 offset:31216
	ds_read_b128 v[230:233], v74 offset:31232
	s_waitcnt vmcnt(11) lgkmcnt(3)
	v_pk_fma_f32 v[46:47], v[210:211], v[160:161], v[46:47] op_sel_hi:[0,1,1]
	v_pk_fma_f32 v[48:49], v[210:211], v[162:163], v[48:49] op_sel_hi:[0,1,1]
	v_pk_fma_f32 v[34:35], v[214:215], v[160:161], v[34:35] op_sel_hi:[0,1,1]
	v_pk_fma_f32 v[36:37], v[214:215], v[162:163], v[36:37] op_sel_hi:[0,1,1]
	v_pk_fma_f32 v[14:15], v[218:219], v[160:161], v[14:15] op_sel_hi:[0,1,1]
	v_pk_fma_f32 v[16:17], v[218:219], v[162:163], v[16:17] op_sel_hi:[0,1,1]
	v_pk_fma_f32 v[42:43], v[210:211], v[160:161], v[42:43] op_sel:[1,0,0]
	v_pk_fma_f32 v[44:45], v[210:211], v[162:163], v[44:45] op_sel:[1,0,0]
	v_pk_fma_f32 v[26:27], v[214:215], v[160:161], v[26:27] op_sel:[1,0,0]
	v_pk_fma_f32 v[28:29], v[214:215], v[162:163], v[28:29] op_sel:[1,0,0]
	v_pk_fma_f32 v[10:11], v[218:219], v[160:161], v[10:11] op_sel:[1,0,0]
	v_pk_fma_f32 v[12:13], v[218:219], v[162:163], v[12:13] op_sel:[1,0,0]
	v_pk_fma_f32 v[38:39], v[212:213], v[160:161], v[38:39] op_sel_hi:[0,1,1]
	v_pk_fma_f32 v[40:41], v[212:213], v[162:163], v[40:41] op_sel_hi:[0,1,1]
	v_pk_fma_f32 v[22:23], v[216:217], v[160:161], v[22:23] op_sel_hi:[0,1,1]
	v_pk_fma_f32 v[24:25], v[216:217], v[162:163], v[24:25] op_sel_hi:[0,1,1]
	v_pk_fma_f32 v[6:7], v[220:221], v[160:161], v[6:7] op_sel_hi:[0,1,1]
	v_pk_fma_f32 v[8:9], v[220:221], v[162:163], v[8:9] op_sel_hi:[0,1,1]
	v_pk_fma_f32 v[30:31], v[212:213], v[160:161], v[30:31] op_sel:[1,0,0]
	v_pk_fma_f32 v[32:33], v[212:213], v[162:163], v[32:33] op_sel:[1,0,0]
	v_pk_fma_f32 v[18:19], v[216:217], v[160:161], v[18:19] op_sel:[1,0,0]
	v_pk_fma_f32 v[20:21], v[216:217], v[162:163], v[20:21] op_sel:[1,0,0]
	v_pk_fma_f32 v[2:3], v[220:221], v[160:161], v[2:3] op_sel:[1,0,0]
	v_pk_fma_f32 v[4:5], v[220:221], v[162:163], v[4:5] op_sel:[1,0,0]
	ds_read_b128 v[210:213], v74 offset:33280
	ds_read_b128 v[214:217], v74 offset:33296
	ds_read_b128 v[218:221], v74 offset:33312
	s_waitcnt vmcnt(10) lgkmcnt(3)
; #define LAS __attribute__((address_space(3)))
; __device__ __forceinline__ void phase_prologue(const Frame& F) {
;     ...
;                 if (tid < 480) {
; #pragma unroll 2
;                     for (int kk = kl; kk < 256; kk += 10) {
;                         const f32x4 w4 = *(const f32x4*)(wada + (size_t)(kc * 256 + kk) * MODW + 48 * cb + 4 * cgp);
;                         const f32x2 w01 = (f32x2){w4[0], w4[1]}, w23 = (f32x2){w4[2], w4[3]};
;                         const LAS f32x4* sp = (const LAS f32x4*)(sT + kk * 52 + 12 * cdg);
;                         const f32x4 s0 = sp[0], s1 = sp[1], s2 = sp[2];
; #pragma unroll
;                         for (int c = 0; c < 4; ++c) {
;                             acc[c][0] = __builtin_elementwise_fma((f32x2){s0[c], s0[c]}, w01, acc[c][0]); acc[c][1] = __builtin_elementwise_fma((f32x2){s0[c], s0[c]}, w23, acc[c][1]);
;                             acc[4 + c][0] = __builtin_elementwise_fma((f32x2){s1[c], s1[c]}, w01, acc[4 + c][0]); acc[4 + c][1] = __builtin_elementwise_fma((f32x2){s1[c], s1[c]}, w23, acc[4 + c][1]);
;                             acc[8 + c][0] = __builtin_elementwise_fma((f32x2){s2[c], s2[c]}, w01, acc[8 + c][0]); acc[8 + c][1] = __builtin_elementwise_fma((f32x2){s2[c], s2[c]}, w23, acc[8 + c][1]); }
;                     }
	v_pk_fma_f32 v[46:47], v[222:223], v[164:165], v[46:47] op_sel_hi:[0,1,1]
	v_pk_fma_f32 v[48:49], v[222:223], v[166:167], v[48:49] op_sel_hi:[0,1,1]
	v_pk_fma_f32 v[34:35], v[226:227], v[164:165], v[34:35] op_sel_hi:[0,1,1]
	v_pk_fma_f32 v[36:37], v[226:227], v[166:167], v[36:37] op_sel_hi:[0,1,1]
	v_pk_fma_f32 v[14:15], v[230:231], v[164:165], v[14:15] op_sel_hi:[0,1,1]
	v_pk_fma_f32 v[16:17], v[230:231], v[166:167], v[16:17] op_sel_hi:[0,1,1]
	v_pk_fma_f32 v[42:43], v[222:223], v[164:165], v[42:43] op_sel:[1,0,0]
	v_pk_fma_f32 v[44:45], v[222:223], v[166:167], v[44:45] op_sel:[1,0,0]
	v_pk_fma_f32 v[26:27], v[226:227], v[164:165], v[26:27] op_sel:[1,0,0]
	v_pk_fma_f32 v[28:29], v[226:227], v[166:167], v[28:29] op_sel:[1,0,0]
	v_pk_fma_f32 v[10:11], v[230:231], v[164:165], v[10:11] op_sel:[1,0,0]
	v_pk_fma_f32 v[12:13], v[230:231], v[166:167], v[12:13] op_sel:[1,0,0]
	v_pk_fma_f32 v[38:39], v[224:225], v[164:165], v[38:39] op_sel_hi:[0,1,1]
	v_pk_fma_f32 v[40:41], v[224:225], v[166:167], v[40:41] op_sel_hi:[0,1,1]
	v_pk_fma_f32 v[22:23], v[228:229], v[164:165], v[22:23] op_sel_hi:[0,1,1]
	v_pk_fma_f32 v[24:25], v[228:229], v[166:167], v[24:25] op_sel_hi:[0,1,1]
	v_pk_fma_f32 v[6:7], v[232:233], v[164:165], v[6:7] op_sel_hi:[0,1,1]
	v_pk_fma_f32 v[8:9], v[232:233], v[166:167], v[8:9] op_sel_hi:[0,1,1]
	v_pk_fma_f32 v[30:31], v[224:225], v[164:165], v[30:31] op_sel:[1,0,0]
	v_pk_fma_f32 v[32:33], v[224:225], v[166:167], v[32:33] op_sel:[1,0,0]
	v_pk_fma_f32 v[18:19], v[228:229], v[164:165], v[18:19] op_sel:[1,0,0]
	v_pk_fma_f32 v[20:21], v[228:229], v[166:167], v[20:21] op_sel:[1,0,0]
	v_pk_fma_f32 v[2:3], v[232:233], v[164:165], v[2:3] op_sel:[1,0,0]
	v_pk_fma_f32 v[4:5], v[232:233], v[166:167], v[4:5] op_sel:[1,0,0]
	ds_read_b128 v[222:225], v74 offset:35360
	ds_read_b128 v[226:229], v74 offset:35376
	ds_read_b128 v[230:233], v74 offset:35392
	s_waitcnt vmcnt(9) lgkmcnt(3)
	v_pk_fma_f32 v[46:47], v[210:211], v[168:169], v[46:47] op_sel_hi:[0,1,1]
	v_pk_fma_f32 v[48:49], v[210:211], v[170:171], v[48:49] op_sel_hi:[0,1,1]
	v_pk_fma_f32 v[34:35], v[214:215], v[168:169], v[34:35] op_sel_hi:[0,1,1]
	v_pk_fma_f32 v[36:37], v[214:215], v[170:171], v[36:37] op_sel_hi:[0,1,1]
	v_pk_fma_f32 v[14:15], v[218:219], v[168:169], v[14:15] op_sel_hi:[0,1,1]
	v_pk_fma_f32 v[16:17], v[218:219], v[170:171], v[16:17] op_sel_hi:[0,1,1]
	v_pk_fma_f32 v[42:43], v[210:211], v[168:169], v[42:43] op_sel:[1,0,0]
	v_pk_fma_f32 v[44:45], v[210:211], v[170:171], v[44:45] op_sel:[1,0,0]
	v_pk_fma_f32 v[26:27], v[214:215], v[168:169], v[26:27] op_sel:[1,0,0]
	v_pk_fma_f32 v[28:29], v[214:215], v[170:171], v[28:29] op_sel:[1,0,0]
	v_pk_fma_f32 v[10:11], v[218:219], v[168:169], v[10:11] op_sel:[1,0,0]
	v_pk_fma_f32 v[12:13], v[218:219], v[170:171], v[12:13] op_sel:[1,0,0]
	v_pk_fma_f32 v[38:39], v[212:213], v[168:169], v[38:39] op_sel_hi:[0,1,1]
	v_pk_fma_f32 v[40:41], v[212:213], v[170:171], v[40:41] op_sel_hi:[0,1,1]
	v_pk_fma_f32 v[22:23], v[216:217], v[168:169], v[22:23] op_sel_hi:[0,1,1]
	v_pk_fma_f32 v[24:25], v[216:217], v[170:171], v[24:25] op_sel_hi:[0,1,1]
	v_pk_fma_f32 v[6:7], v[220:221], v[168:169], v[6:7] op_sel_hi:[0,1,1]
	v_pk_fma_f32 v[8:9], v[220:221], v[170:171], v[8:9] op_sel_hi:[0,1,1]
	v_pk_fma_f32 v[30:31], v[212:213], v[168:169], v[30:31] op_sel:[1,0,0]
	v_pk_fma_f32 v[32:33], v[212:213], v[170:171], v[32:33] op_sel:[1,0,0]
	v_pk_fma_f32 v[18:19], v[216:217], v[168:169], v[18:19] op_sel:[1,0,0]
	v_pk_fma_f32 v[20:21], v[216:217], v[170:171], v[20:21] op_sel:[1,0,0]
	v_pk_fma_f32 v[2:3], v[220:221], v[168:169], v[2:3] op_sel:[1,0,0]
	v_pk_fma_f32 v[4:5], v[220:221], v[170:171], v[4:5] op_sel:[1,0,0]
	ds_read_b128 v[210:213], v74 offset:37440
	ds_read_b128 v[214:217], v74 offset:37456
	ds_read_b128 v[218:221], v74 offset:37472
	s_waitcnt vmcnt(8) lgkmcnt(3)
	v_pk_fma_f32 v[46:47], v[222:223], v[172:173], v[46:47] op_sel_hi:[0,1,1]
	v_pk_fma_f32 v[48:49], v[222:223], v[174:175], v[48:49] op_sel_hi:[0,1,1]
	v_pk_fma_f32 v[34:35], v[226:227], v[172:173], v[34:35] op_sel_hi:[0,1,1]
	v_pk_fma_f32 v[36:37], v[226:227], v[174:175], v[36:37] op_sel_hi:[0,1,1]
	v_pk_fma_f32 v[14:15], v[230:231], v[172:173], v[14:15] op_sel_hi:[0,1,1]
	v_pk_fma_f32 v[16:17], v[230:231], v[174:175], v[16:17] op_sel_hi:[0,1,1]
	v_pk_fma_f32 v[42:43], v[222:223], v[172:173], v[42:43] op_sel:[1,0,0]
	v_pk_fma_f32 v[44:45], v[222:223], v[174:175], v[44:45] op_sel:[1,0,0]
	v_pk_fma_f32 v[26:27], v[226:227], v[172:173], v[26:27] op_sel:[1,0,0]
	v_pk_fma_f32 v[28:29], v[226:227], v[174:175], v[28:29] op_sel:[1,0,0]
	v_pk_fma_f32 v[10:11], v[230:231], v[172:173], v[10:11] op_sel:[1,0,0]
	v_pk_fma_f32 v[12:13], v[230:231], v[174:175], v[12:13] op_sel:[1,0,0]
	v_pk_fma_f32 v[38:39], v[224:225], v[172:173], v[38:39] op_sel_hi:[0,1,1]
	v_pk_fma_f32 v[40:41], v[224:225], v[174:175], v[40:41] op_sel_hi:[0,1,1]
	v_pk_fma_f32 v[22:23], v[228:229], v[172:173], v[22:23] op_sel_hi:[0,1,1]
	v_pk_fma_f32 v[24:25], v[228:229], v[174:175], v[24:25] op_sel_hi:[0,1,1]
	v_pk_fma_f32 v[6:7], v[232:233], v[172:173], v[6:7] op_sel_hi:[0,1,1]
	v_pk_fma_f32 v[8:9], v[232:233], v[174:175], v[8:9] op_sel_hi:[0,1,1]
	v_pk_fma_f32 v[30:31], v[224:225], v[172:173], v[30:31] op_sel:[1,0,0]
	v_pk_fma_f32 v[32:33], v[224:225], v[174:175], v[32:33] op_sel:[1,0,0]
	v_pk_fma_f32 v[18:19], v[228:229], v[172:173], v[18:19] op_sel:[1,0,0]
	v_pk_fma_f32 v[20:21], v[228:229], v[174:175], v[20:21] op_sel:[1,0,0]
	v_pk_fma_f32 v[2:3], v[232:233], v[172:173], v[2:3] op_sel:[1,0,0]
	v_pk_fma_f32 v[4:5], v[232:233], v[174:175], v[4:5] op_sel:[1,0,0]
	ds_read_b128 v[222:225], v74 offset:39520
	ds_read_b128 v[226:229], v74 offset:39536
	ds_read_b128 v[230:233], v74 offset:39552
	s_waitcnt vmcnt(7) lgkmcnt(3)
; #define LAS __attribute__((address_space(3)))
; __device__ __forceinline__ void phase_prologue(const Frame& F) {
;     ...
;                 if (tid < 480) {
; #pragma unroll 2
;                     for (int kk = kl; kk < 256; kk += 10) {
;                         const f32x4 w4 = *(const f32x4*)(wada + (size_t)(kc * 256 + kk) * MODW + 48 * cb + 4 * cgp);
;                         const f32x2 w01 = (f32x2){w4[0], w4[1]}, w23 = (f32x2){w4[2], w4[3]};
;                         const LAS f32x4* sp = (const LAS f32x4*)(sT + kk * 52 + 12 * cdg);
;                         const f32x4 s0 = sp[0], s1 = sp[1], s2 = sp[2];
; #pragma unroll
;                         for (int c = 0; c < 4; ++c) {
;                             acc[c][0] = __builtin_elementwise_fma((f32x2){s0[c], s0[c]}, w01, acc[c][0]); acc[c][1] = __builtin_elementwise_fma((f32x2){s0[c], s0[c]}, w23, acc[c][1]);
;                             acc[4 + c][0] = __builtin_elementwise_fma((f32x2){s1[c], s1[c]}, w01, acc[4 + c][0]); acc[4 + c][1] = __builtin_elementwise_fma((f32x2){s1[c], s1[c]}, w23, acc[4 + c][1]);
;                             acc[8 + c][0] = __builtin_elementwise_fma((f32x2){s2[c], s2[c]}, w01, acc[8 + c][0]); acc[8 + c][1] = __builtin_elementwise_fma((f32x2){s2[c], s2[c]}, w23, acc[8 + c][1]); }
;                     }
	v_pk_fma_f32 v[46:47], v[210:211], v[176:177], v[46:47] op_sel_hi:[0,1,1]
	v_pk_fma_f32 v[48:49], v[210:211], v[178:179], v[48:49] op_sel_hi:[0,1,1]
	v_pk_fma_f32 v[34:35], v[214:215], v[176:177], v[34:35] op_sel_hi:[0,1,1]
	v_pk_fma_f32 v[36:37], v[214:215], v[178:179], v[36:37] op_sel_hi:[0,1,1]
	v_pk_fma_f32 v[14:15], v[218:219], v[176:177], v[14:15] op_sel_hi:[0,1,1]
	v_pk_fma_f32 v[16:17], v[218:219], v[178:179], v[16:17] op_sel_hi:[0,1,1]
	v_pk_fma_f32 v[42:43], v[210:211], v[176:177], v[42:43] op_sel:[1,0,0]
	v_pk_fma_f32 v[44:45], v[210:211], v[178:179], v[44:45] op_sel:[1,0,0]
	v_pk_fma_f32 v[26:27], v[214:215], v[176:177], v[26:27] op_sel:[1,0,0]
	v_pk_fma_f32 v[28:29], v[214:215], v[178:179], v[28:29] op_sel:[1,0,0]
	v_pk_fma_f32 v[10:11], v[218:219], v[176:177], v[10:11] op_sel:[1,0,0]
	v_pk_fma_f32 v[12:13], v[218:219], v[178:179], v[12:13] op_sel:[1,0,0]
	v_pk_fma_f32 v[38:39], v[212:213], v[176:177], v[38:39] op_sel_hi:[0,1,1]
	v_pk_fma_f32 v[40:41], v[212:213], v[178:179], v[40:41] op_sel_hi:[0,1,1]
	v_pk_fma_f32 v[22:23], v[216:217], v[176:177], v[22:23] op_sel_hi:[0,1,1]
	v_pk_fma_f32 v[24:25], v[216:217], v[178:179], v[24:25] op_sel_hi:[0,1,1]
	v_pk_fma_f32 v[6:7], v[220:221], v[176:177], v[6:7] op_sel_hi:[0,1,1]
	v_pk_fma_f32 v[8:9], v[220:221], v[178:179], v[8:9] op_sel_hi:[0,1,1]
	v_pk_fma_f32 v[30:31], v[212:213], v[176:177], v[30:31] op_sel:[1,0,0]
	v_pk_fma_f32 v[32:33], v[212:213], v[178:179], v[32:33] op_sel:[1,0,0]
	v_pk_fma_f32 v[18:19], v[216:217], v[176:177], v[18:19] op_sel:[1,0,0]
	v_pk_fma_f32 v[20:21], v[216:217], v[178:179], v[20:21] op_sel:[1,0,0]
	v_pk_fma_f32 v[2:3], v[220:221], v[176:177], v[2:3] op_sel:[1,0,0]
	v_pk_fma_f32 v[4:5], v[220:221], v[178:179], v[4:5] op_sel:[1,0,0]
	ds_read_b128 v[210:213], v74 offset:41600
	ds_read_b128 v[214:217], v74 offset:41616
	ds_read_b128 v[218:221], v74 offset:41632
	s_waitcnt vmcnt(6) lgkmcnt(3)
	v_pk_fma_f32 v[46:47], v[222:223], v[180:181], v[46:47] op_sel_hi:[0,1,1]
	v_pk_fma_f32 v[48:49], v[222:223], v[182:183], v[48:49] op_sel_hi:[0,1,1]
	v_pk_fma_f32 v[34:35], v[226:227], v[180:181], v[34:35] op_sel_hi:[0,1,1]
	v_pk_fma_f32 v[36:37], v[226:227], v[182:183], v[36:37] op_sel_hi:[0,1,1]
	v_pk_fma_f32 v[14:15], v[230:231], v[180:181], v[14:15] op_sel_hi:[0,1,1]
	v_pk_fma_f32 v[16:17], v[230:231], v[182:183], v[16:17] op_sel_hi:[0,1,1]
	v_pk_fma_f32 v[42:43], v[222:223], v[180:181], v[42:43] op_sel:[1,0,0]
	v_pk_fma_f32 v[44:45], v[222:223], v[182:183], v[44:45] op_sel:[1,0,0]
	v_pk_fma_f32 v[26:27], v[226:227], v[180:181], v[26:27] op_sel:[1,0,0]
	v_pk_fma_f32 v[28:29], v[226:227], v[182:183], v[28:29] op_sel:[1,0,0]
	v_pk_fma_f32 v[10:11], v[230:231], v[180:181], v[10:11] op_sel:[1,0,0]
	v_pk_fma_f32 v[12:13], v[230:231], v[182:183], v[12:13] op_sel:[1,0,0]
	v_pk_fma_f32 v[38:39], v[224:225], v[180:181], v[38:39] op_sel_hi:[0,1,1]
	v_pk_fma_f32 v[40:41], v[224:225], v[182:183], v[40:41] op_sel_hi:[0,1,1]
	v_pk_fma_f32 v[22:23], v[228:229], v[180:181], v[22:23] op_sel_hi:[0,1,1]
	v_pk_fma_f32 v[24:25], v[228:229], v[182:183], v[24:25] op_sel_hi:[0,1,1]
	v_pk_fma_f32 v[6:7], v[232:233], v[180:181], v[6:7] op_sel_hi:[0,1,1]
	v_pk_fma_f32 v[8:9], v[232:233], v[182:183], v[8:9] op_sel_hi:[0,1,1]
	v_pk_fma_f32 v[30:31], v[224:225], v[180:181], v[30:31] op_sel:[1,0,0]
	v_pk_fma_f32 v[32:33], v[224:225], v[182:183], v[32:33] op_sel:[1,0,0]
	v_pk_fma_f32 v[18:19], v[228:229], v[180:181], v[18:19] op_sel:[1,0,0]
	v_pk_fma_f32 v[20:21], v[228:229], v[182:183], v[20:21] op_sel:[1,0,0]
	v_pk_fma_f32 v[2:3], v[232:233], v[180:181], v[2:3] op_sel:[1,0,0]
	v_pk_fma_f32 v[4:5], v[232:233], v[182:183], v[4:5] op_sel:[1,0,0]
	ds_read_b128 v[222:225], v74 offset:43680
	ds_read_b128 v[226:229], v74 offset:43696
	ds_read_b128 v[230:233], v74 offset:43712
	s_waitcnt vmcnt(5) lgkmcnt(3)
	v_pk_fma_f32 v[46:47], v[210:211], v[184:185], v[46:47] op_sel_hi:[0,1,1]
	v_pk_fma_f32 v[48:49], v[210:211], v[186:187], v[48:49] op_sel_hi:[0,1,1]
	v_pk_fma_f32 v[34:35], v[214:215], v[184:185], v[34:35] op_sel_hi:[0,1,1]
	v_pk_fma_f32 v[36:37], v[214:215], v[186:187], v[36:37] op_sel_hi:[0,1,1]
	v_pk_fma_f32 v[14:15], v[218:219], v[184:185], v[14:15] op_sel_hi:[0,1,1]
	v_pk_fma_f32 v[16:17], v[218:219], v[186:187], v[16:17] op_sel_hi:[0,1,1]
	v_pk_fma_f32 v[42:43], v[210:211], v[184:185], v[42:43] op_sel:[1,0,0]
	v_pk_fma_f32 v[44:45], v[210:211], v[186:187], v[44:45] op_sel:[1,0,0]
	v_pk_fma_f32 v[26:27], v[214:215], v[184:185], v[26:27] op_sel:[1,0,0]
	v_pk_fma_f32 v[28:29], v[214:215], v[186:187], v[28:29] op_sel:[1,0,0]
	v_pk_fma_f32 v[10:11], v[218:219], v[184:185], v[10:11] op_sel:[1,0,0]
	v_pk_fma_f32 v[12:13], v[218:219], v[186:187], v[12:13] op_sel:[1,0,0]
	v_pk_fma_f32 v[38:39], v[212:213], v[184:185], v[38:39] op_sel_hi:[0,1,1]
	v_pk_fma_f32 v[40:41], v[212:213], v[186:187], v[40:41] op_sel_hi:[0,1,1]
	v_pk_fma_f32 v[22:23], v[216:217], v[184:185], v[22:23] op_sel_hi:[0,1,1]
	v_pk_fma_f32 v[24:25], v[216:217], v[186:187], v[24:25] op_sel_hi:[0,1,1]
	v_pk_fma_f32 v[6:7], v[220:221], v[184:185], v[6:7] op_sel_hi:[0,1,1]
	v_pk_fma_f32 v[8:9], v[220:221], v[186:187], v[8:9] op_sel_hi:[0,1,1]
	v_pk_fma_f32 v[30:31], v[212:213], v[184:185], v[30:31] op_sel:[1,0,0]
	v_pk_fma_f32 v[32:33], v[212:213], v[186:187], v[32:33] op_sel:[1,0,0]
	v_pk_fma_f32 v[18:19], v[216:217], v[184:185], v[18:19] op_sel:[1,0,0]
	v_pk_fma_f32 v[20:21], v[216:217], v[186:187], v[20:21] op_sel:[1,0,0]
	v_pk_fma_f32 v[2:3], v[220:221], v[184:185], v[2:3] op_sel:[1,0,0]
	v_pk_fma_f32 v[4:5], v[220:221], v[186:187], v[4:5] op_sel:[1,0,0]
	ds_read_b128 v[210:213], v74 offset:45760
	ds_read_b128 v[214:217], v74 offset:45776
	ds_read_b128 v[218:221], v74 offset:45792
	s_waitcnt vmcnt(4) lgkmcnt(3)
; #define LAS __attribute__((address_space(3)))
; __device__ __forceinline__ void phase_prologue(const Frame& F) {
;     ...
;                 if (tid < 480) {
; #pragma unroll 2
;                     for (int kk = kl; kk < 256; kk += 10) {
;                         const f32x4 w4 = *(const f32x4*)(wada + (size_t)(kc * 256 + kk) * MODW + 48 * cb + 4 * cgp);
;                         const f32x2 w01 = (f32x2){w4[0], w4[1]}, w23 = (f32x2){w4[2], w4[3]};
;                         const LAS f32x4* sp = (const LAS f32x4*)(sT + kk * 52 + 12 * cdg);
;                         const f32x4 s0 = sp[0], s1 = sp[1], s2 = sp[2];
; #pragma unroll
;                         for (int c = 0; c < 4; ++c) {
;                             acc[c][0] = __builtin_elementwise_fma((f32x2){s0[c], s0[c]}, w01, acc[c][0]); acc[c][1] = __builtin_elementwise_fma((f32x2){s0[c], s0[c]}, w23, acc[c][1]);
;                             acc[4 + c][0] = __builtin_elementwise_fma((f32x2){s1[c], s1[c]}, w01, acc[4 + c][0]); acc[4 + c][1] = __builtin_elementwise_fma((f32x2){s1[c], s1[c]}, w23, acc[4 + c][1]);
;                             acc[8 + c][0] = __builtin_elementwise_fma((f32x2){s2[c], s2[c]}, w01, acc[8 + c][0]); acc[8 + c][1] = __builtin_elementwise_fma((f32x2){s2[c], s2[c]}, w23, acc[8 + c][1]); }
;                     }
	v_pk_fma_f32 v[46:47], v[222:223], v[188:189], v[46:47] op_sel_hi:[0,1,1]
	v_pk_fma_f32 v[48:49], v[222:223], v[190:191], v[48:49] op_sel_hi:[0,1,1]
	v_pk_fma_f32 v[34:35], v[226:227], v[188:189], v[34:35] op_sel_hi:[0,1,1]
	v_pk_fma_f32 v[36:37], v[226:227], v[190:191], v[36:37] op_sel_hi:[0,1,1]
	v_pk_fma_f32 v[14:15], v[230:231], v[188:189], v[14:15] op_sel_hi:[0,1,1]
	v_pk_fma_f32 v[16:17], v[230:231], v[190:191], v[16:17] op_sel_hi:[0,1,1]
	v_pk_fma_f32 v[42:43], v[222:223], v[188:189], v[42:43] op_sel:[1,0,0]
	v_pk_fma_f32 v[44:45], v[222:223], v[190:191], v[44:45] op_sel:[1,0,0]
	v_pk_fma_f32 v[26:27], v[226:227], v[188:189], v[26:27] op_sel:[1,0,0]
	v_pk_fma_f32 v[28:29], v[226:227], v[190:191], v[28:29] op_sel:[1,0,0]
	v_pk_fma_f32 v[10:11], v[230:231], v[188:189], v[10:11] op_sel:[1,0,0]
	v_pk_fma_f32 v[12:13], v[230:231], v[190:191], v[12:13] op_sel:[1,0,0]
	v_pk_fma_f32 v[38:39], v[224:225], v[188:189], v[38:39] op_sel_hi:[0,1,1]
	v_pk_fma_f32 v[40:41], v[224:225], v[190:191], v[40:41] op_sel_hi:[0,1,1]
	v_pk_fma_f32 v[22:23], v[228:229], v[188:189], v[22:23] op_sel_hi:[0,1,1]
	v_pk_fma_f32 v[24:25], v[228:229], v[190:191], v[24:25] op_sel_hi:[0,1,1]
	v_pk_fma_f32 v[6:7], v[232:233], v[188:189], v[6:7] op_sel_hi:[0,1,1]
	v_pk_fma_f32 v[8:9], v[232:233], v[190:191], v[8:9] op_sel_hi:[0,1,1]
	v_pk_fma_f32 v[30:31], v[224:225], v[188:189], v[30:31] op_sel:[1,0,0]
	v_pk_fma_f32 v[32:33], v[224:225], v[190:191], v[32:33] op_sel:[1,0,0]
	v_pk_fma_f32 v[18:19], v[228:229], v[188:189], v[18:19] op_sel:[1,0,0]
	v_pk_fma_f32 v[20:21], v[228:229], v[190:191], v[20:21] op_sel:[1,0,0]
	v_pk_fma_f32 v[2:3], v[232:233], v[188:189], v[2:3] op_sel:[1,0,0]
	v_pk_fma_f32 v[4:5], v[232:233], v[190:191], v[4:5] op_sel:[1,0,0]
	ds_read_b128 v[222:225], v74 offset:47840
	ds_read_b128 v[226:229], v74 offset:47856
	ds_read_b128 v[230:233], v74 offset:47872
	s_waitcnt vmcnt(3) lgkmcnt(3)
	v_pk_fma_f32 v[46:47], v[210:211], v[194:195], v[46:47] op_sel_hi:[0,1,1]
	v_pk_fma_f32 v[48:49], v[210:211], v[196:197], v[48:49] op_sel_hi:[0,1,1]
	v_pk_fma_f32 v[34:35], v[214:215], v[194:195], v[34:35] op_sel_hi:[0,1,1]
	v_pk_fma_f32 v[36:37], v[214:215], v[196:197], v[36:37] op_sel_hi:[0,1,1]
	v_pk_fma_f32 v[14:15], v[218:219], v[194:195], v[14:15] op_sel_hi:[0,1,1]
	v_pk_fma_f32 v[16:17], v[218:219], v[196:197], v[16:17] op_sel_hi:[0,1,1]
	v_pk_fma_f32 v[42:43], v[210:211], v[194:195], v[42:43] op_sel:[1,0,0]
	v_pk_fma_f32 v[44:45], v[210:211], v[196:197], v[44:45] op_sel:[1,0,0]
	v_pk_fma_f32 v[26:27], v[214:215], v[194:195], v[26:27] op_sel:[1,0,0]
	v_pk_fma_f32 v[28:29], v[214:215], v[196:197], v[28:29] op_sel:[1,0,0]
	v_pk_fma_f32 v[10:11], v[218:219], v[194:195], v[10:11] op_sel:[1,0,0]
	v_pk_fma_f32 v[12:13], v[218:219], v[196:197], v[12:13] op_sel:[1,0,0]
	v_pk_fma_f32 v[38:39], v[212:213], v[194:195], v[38:39] op_sel_hi:[0,1,1]
	v_pk_fma_f32 v[40:41], v[212:213], v[196:197], v[40:41] op_sel_hi:[0,1,1]
	v_pk_fma_f32 v[22:23], v[216:217], v[194:195], v[22:23] op_sel_hi:[0,1,1]
	v_pk_fma_f32 v[24:25], v[216:217], v[196:197], v[24:25] op_sel_hi:[0,1,1]
	v_pk_fma_f32 v[6:7], v[220:221], v[194:195], v[6:7] op_sel_hi:[0,1,1]
	v_pk_fma_f32 v[8:9], v[220:221], v[196:197], v[8:9] op_sel_hi:[0,1,1]
	v_pk_fma_f32 v[30:31], v[212:213], v[194:195], v[30:31] op_sel:[1,0,0]
	v_pk_fma_f32 v[32:33], v[212:213], v[196:197], v[32:33] op_sel:[1,0,0]
	v_pk_fma_f32 v[18:19], v[216:217], v[194:195], v[18:19] op_sel:[1,0,0]
	v_pk_fma_f32 v[20:21], v[216:217], v[196:197], v[20:21] op_sel:[1,0,0]
	v_pk_fma_f32 v[2:3], v[220:221], v[194:195], v[2:3] op_sel:[1,0,0]
	v_pk_fma_f32 v[4:5], v[220:221], v[196:197], v[4:5] op_sel:[1,0,0]
	ds_read_b128 v[210:213], v74 offset:49920
	ds_read_b128 v[214:217], v74 offset:49936
	ds_read_b128 v[218:221], v74 offset:49952
	s_waitcnt vmcnt(2) lgkmcnt(3)
; #define LAS __attribute__((address_space(3)))
; __device__ __forceinline__ void phase_prologue(const Frame& F) {
;     ...
;                 if (tid < 480) {
; #pragma unroll 2
;                     for (int kk = kl; kk < 256; kk += 10) {
;                         const f32x4 w4 = *(const f32x4*)(wada + (size_t)(kc * 256 + kk) * MODW + 48 * cb + 4 * cgp);
;                         const f32x2 w01 = (f32x2){w4[0], w4[1]}, w23 = (f32x2){w4[2], w4[3]};
;                         const LAS f32x4* sp = (const LAS f32x4*)(sT + kk * 52 + 12 * cdg);
;                         const f32x4 s0 = sp[0], s1 = sp[1], s2 = sp[2];
; #pragma unroll
;                         for (int c = 0; c < 4; ++c) {
;                             acc[c][0] = __builtin_elementwise_fma((f32x2){s0[c], s0[c]}, w01, acc[c][0]); acc[c][1] = __builtin_elementwise_fma((f32x2){s0[c], s0[c]}, w23, acc[c][1]);
;                             acc[4 + c][0] = __builtin_elementwise_fma((f32x2){s1[c], s1[c]}, w01, acc[4 + c][0]); acc[4 + c][1] = __builtin_elementwise_fma((f32x2){s1[c], s1[c]}, w23, acc[4 + c][1]);
;                             acc[8 + c][0] = __builtin_elementwise_fma((f32x2){s2[c], s2[c]}, w01, acc[8 + c][0]); acc[8 + c][1] = __builtin_elementwise_fma((f32x2){s2[c], s2[c]}, w23, acc[8 + c][1]); }
;                     }
;                 }
;             }
	v_pk_fma_f32 v[46:47], v[222:223], v[198:199], v[46:47] op_sel_hi:[0,1,1]
	v_pk_fma_f32 v[48:49], v[222:223], v[200:201], v[48:49] op_sel_hi:[0,1,1]
	v_pk_fma_f32 v[34:35], v[226:227], v[198:199], v[34:35] op_sel_hi:[0,1,1]
	v_pk_fma_f32 v[36:37], v[226:227], v[200:201], v[36:37] op_sel_hi:[0,1,1]
	v_pk_fma_f32 v[14:15], v[230:231], v[198:199], v[14:15] op_sel_hi:[0,1,1]
	v_pk_fma_f32 v[16:17], v[230:231], v[200:201], v[16:17] op_sel_hi:[0,1,1]
	v_pk_fma_f32 v[42:43], v[222:223], v[198:199], v[42:43] op_sel:[1,0,0]
	v_pk_fma_f32 v[44:45], v[222:223], v[200:201], v[44:45] op_sel:[1,0,0]
	v_pk_fma_f32 v[26:27], v[226:227], v[198:199], v[26:27] op_sel:[1,0,0]
	v_pk_fma_f32 v[28:29], v[226:227], v[200:201], v[28:29] op_sel:[1,0,0]
	v_pk_fma_f32 v[10:11], v[230:231], v[198:199], v[10:11] op_sel:[1,0,0]
	v_pk_fma_f32 v[12:13], v[230:231], v[200:201], v[12:13] op_sel:[1,0,0]
	v_pk_fma_f32 v[38:39], v[224:225], v[198:199], v[38:39] op_sel_hi:[0,1,1]
	v_pk_fma_f32 v[40:41], v[224:225], v[200:201], v[40:41] op_sel_hi:[0,1,1]
	v_pk_fma_f32 v[22:23], v[228:229], v[198:199], v[22:23] op_sel_hi:[0,1,1]
	v_pk_fma_f32 v[24:25], v[228:229], v[200:201], v[24:25] op_sel_hi:[0,1,1]
	v_pk_fma_f32 v[6:7], v[232:233], v[198:199], v[6:7] op_sel_hi:[0,1,1]
	v_pk_fma_f32 v[8:9], v[232:233], v[200:201], v[8:9] op_sel_hi:[0,1,1]
	v_pk_fma_f32 v[30:31], v[224:225], v[198:199], v[30:31] op_sel:[1,0,0]
	v_pk_fma_f32 v[32:33], v[224:225], v[200:201], v[32:33] op_sel:[1,0,0]
	v_pk_fma_f32 v[18:19], v[228:229], v[198:199], v[18:19] op_sel:[1,0,0]
	v_pk_fma_f32 v[20:21], v[228:229], v[200:201], v[20:21] op_sel:[1,0,0]
	v_pk_fma_f32 v[2:3], v[232:233], v[198:199], v[2:3] op_sel:[1,0,0]
	v_pk_fma_f32 v[4:5], v[232:233], v[200:201], v[4:5] op_sel:[1,0,0]
	ds_read_b128 v[222:225], v74 offset:52000
	ds_read_b128 v[226:229], v74 offset:52016
	ds_read_b128 v[230:233], v74 offset:52032
	s_waitcnt vmcnt(1) lgkmcnt(3)
	v_pk_fma_f32 v[46:47], v[210:211], v[202:203], v[46:47] op_sel_hi:[0,1,1]
	v_pk_fma_f32 v[48:49], v[210:211], v[204:205], v[48:49] op_sel_hi:[0,1,1]
	v_pk_fma_f32 v[34:35], v[214:215], v[202:203], v[34:35] op_sel_hi:[0,1,1]
	v_pk_fma_f32 v[36:37], v[214:215], v[204:205], v[36:37] op_sel_hi:[0,1,1]
	v_pk_fma_f32 v[14:15], v[218:219], v[202:203], v[14:15] op_sel_hi:[0,1,1]
	v_pk_fma_f32 v[16:17], v[218:219], v[204:205], v[16:17] op_sel_hi:[0,1,1]
	v_pk_fma_f32 v[42:43], v[210:211], v[202:203], v[42:43] op_sel:[1,0,0]
	v_pk_fma_f32 v[44:45], v[210:211], v[204:205], v[44:45] op_sel:[1,0,0]
	v_pk_fma_f32 v[26:27], v[214:215], v[202:203], v[26:27] op_sel:[1,0,0]
	v_pk_fma_f32 v[28:29], v[214:215], v[204:205], v[28:29] op_sel:[1,0,0]
	v_pk_fma_f32 v[10:11], v[218:219], v[202:203], v[10:11] op_sel:[1,0,0]
	v_pk_fma_f32 v[12:13], v[218:219], v[204:205], v[12:13] op_sel:[1,0,0]
	v_pk_fma_f32 v[38:39], v[212:213], v[202:203], v[38:39] op_sel_hi:[0,1,1]
	v_pk_fma_f32 v[40:41], v[212:213], v[204:205], v[40:41] op_sel_hi:[0,1,1]
	v_pk_fma_f32 v[22:23], v[216:217], v[202:203], v[22:23] op_sel_hi:[0,1,1]
	v_pk_fma_f32 v[24:25], v[216:217], v[204:205], v[24:25] op_sel_hi:[0,1,1]
	v_pk_fma_f32 v[6:7], v[220:221], v[202:203], v[6:7] op_sel_hi:[0,1,1]
	v_pk_fma_f32 v[8:9], v[220:221], v[204:205], v[8:9] op_sel_hi:[0,1,1]
	v_pk_fma_f32 v[30:31], v[212:213], v[202:203], v[30:31] op_sel:[1,0,0]
	v_pk_fma_f32 v[32:33], v[212:213], v[204:205], v[32:33] op_sel:[1,0,0]
	v_pk_fma_f32 v[18:19], v[216:217], v[202:203], v[18:19] op_sel:[1,0,0]
	v_pk_fma_f32 v[20:21], v[216:217], v[204:205], v[20:21] op_sel:[1,0,0]
	v_pk_fma_f32 v[2:3], v[220:221], v[202:203], v[2:3] op_sel:[1,0,0]
	v_pk_fma_f32 v[4:5], v[220:221], v[204:205], v[4:5] op_sel:[1,0,0]
	s_waitcnt vmcnt(0) lgkmcnt(0)
	s_andn2_b64 exec, exec, s[4:5]
	v_pk_fma_f32 v[46:47], v[222:223], v[206:207], v[46:47] op_sel_hi:[0,1,1]
	v_pk_fma_f32 v[48:49], v[222:223], v[208:209], v[48:49] op_sel_hi:[0,1,1]
	v_pk_fma_f32 v[34:35], v[226:227], v[206:207], v[34:35] op_sel_hi:[0,1,1]
	v_pk_fma_f32 v[36:37], v[226:227], v[208:209], v[36:37] op_sel_hi:[0,1,1]
	v_pk_fma_f32 v[14:15], v[230:231], v[206:207], v[14:15] op_sel_hi:[0,1,1]
	v_pk_fma_f32 v[16:17], v[230:231], v[208:209], v[16:17] op_sel_hi:[0,1,1]
	v_pk_fma_f32 v[42:43], v[222:223], v[206:207], v[42:43] op_sel:[1,0,0]
	v_pk_fma_f32 v[44:45], v[222:223], v[208:209], v[44:45] op_sel:[1,0,0]
	v_pk_fma_f32 v[26:27], v[226:227], v[206:207], v[26:27] op_sel:[1,0,0]
	v_pk_fma_f32 v[28:29], v[226:227], v[208:209], v[28:29] op_sel:[1,0,0]
	v_pk_fma_f32 v[10:11], v[230:231], v[206:207], v[10:11] op_sel:[1,0,0]
	v_pk_fma_f32 v[12:13], v[230:231], v[208:209], v[12:13] op_sel:[1,0,0]
	v_pk_fma_f32 v[38:39], v[224:225], v[206:207], v[38:39] op_sel_hi:[0,1,1]
	v_pk_fma_f32 v[40:41], v[224:225], v[208:209], v[40:41] op_sel_hi:[0,1,1]
	v_pk_fma_f32 v[22:23], v[228:229], v[206:207], v[22:23] op_sel_hi:[0,1,1]
	v_pk_fma_f32 v[24:25], v[228:229], v[208:209], v[24:25] op_sel_hi:[0,1,1]
	v_pk_fma_f32 v[6:7], v[232:233], v[206:207], v[6:7] op_sel_hi:[0,1,1]
	v_pk_fma_f32 v[8:9], v[232:233], v[208:209], v[8:9] op_sel_hi:[0,1,1]
	v_pk_fma_f32 v[30:31], v[224:225], v[206:207], v[30:31] op_sel:[1,0,0]
	v_pk_fma_f32 v[32:33], v[224:225], v[208:209], v[32:33] op_sel:[1,0,0]
	v_pk_fma_f32 v[18:19], v[228:229], v[206:207], v[18:19] op_sel:[1,0,0]
	v_pk_fma_f32 v[20:21], v[228:229], v[208:209], v[20:21] op_sel:[1,0,0]
	v_pk_fma_f32 v[2:3], v[232:233], v[206:207], v[2:3] op_sel:[1,0,0]
	v_pk_fma_f32 v[4:5], v[232:233], v[208:209], v[4:5] op_sel:[1,0,0]
	s_and_b64 exec, s[10:11], s[0:1]
	s_mov_b64 exec, s[10:11]

; #define REP(k) for (int rep_##k = 0; rep_##k < ((REPEAT_PHASE == (k)) ? 2 : 1); ++rep_##k)
; #define LAS __attribute__((address_space(3)))
; #define SEAM(k) do { if (IN(k) && IN((k) + 1)) { if ((k) == 0) cg::this_grid().sync(); else xcd_barrier(xbar); } } while (0)
; __device__ __forceinline__ void xcd_barrier(const XcdBarrier& b) {
;     asm volatile("s_waitcnt vmcnt(0)" ::: "memory");
;     __syncthreads();
;     if (threadIdx.x == 0) {
;         unsigned* bar = b.bar;
;         __builtin_amdgcn_s_waitcnt(0);
;         unsigned nloc = b.st[0], nx = b.st[1];
;         if (nloc == 0u) { xcd_barrier_complete(bar, b.x, nloc, nx); b.st[0] = nloc; b.st[1] = nx; }
; __global__ void __launch_bounds__(NTHREADS, 2) fwd_kernel(KArgs a) {
;     ...
;     volatile LAS unsigned* xst = (volatile LAS unsigned*)(F.lds + LDS_BYTES - 16);
;     if (F.tid < 4) xst[F.tid] = 0u;
;     __syncthreads();
;     XcdBarrier xbar; xbar.bar = (unsigned*)ws; xbar.x = 0; xbar.st = xst;
;     if (hi - lo > 1) xbar = xcd_barrier_post((unsigned*)ws, xst);
;     if (IN(0)) REP(0) phase_prologue(F);
;     SEAM(0);
.LBB0_131:
	s_cmp_gt_i32 s97, 1
	v_readlane_b32 s2, v254, 21
	s_cselect_b64 s[0:1], -1, 0
	v_readlane_b32 s3, v254, 22
	s_and_b64 s[2:3], s[2:3], s[0:1]
	s_andn2_b64 vcc, exec, s[2:3]
	s_cbranch_vccnz .LBB0_143
	s_waitcnt vmcnt(0)
	v_cmp_eq_u32_e32 vcc, 0, v192
	s_barrier
	s_and_saveexec_b64 s[4:5], vcc
	s_cbranch_execz .Lxb0_205
	s_add_i32 s2, 0, 0x23ff0
	v_mov_b32_e32 v0, s2
	s_waitcnt vmcnt(0) expcnt(0) lgkmcnt(0)
	ds_read_b32 v2, v0
	s_add_i32 s2, 0, 0x23ff4
	v_mov_b32_e32 v0, s2
	ds_read_b32 v0, v0
	s_waitcnt lgkmcnt(1)
	v_cmp_ne_u32_e32 vcc, 0, v2
	s_cbranch_vccnz .Lxb0_173
	v_readlane_b32 s6, v254, 0
	v_readlane_b32 s7, v254, 1
	s_load_dwordx2 s[2:3], s[6:7], 0x4
	s_add_u32 s6, s66, 0x1000
	s_addc_u32 s7, s67, 0
	s_add_u32 s8, s66, 0x1100
	s_addc_u32 s9, s67, 0
	s_add_u32 s10, s66, 0x1200
	s_addc_u32 s11, s67, 0
	s_waitcnt lgkmcnt(0)
	s_mul_i32 s2, s2, s92
	s_add_u32 s12, s66, 0x1300
	s_mul_i32 s2, s2, s3
	s_addc_u32 s13, s67, 0
	s_mov_b32 s3, 1
	v_mov_b32_e32 v16, 0
	s_branch .Lxb0_161

; #define LAS __attribute__((address_space(3)))
; __device__ __forceinline__ unsigned cvt_pk_bf16(float lo, float hi) { unsigned r; asm volatile("v_cvt_pk_bf16_f32 %0, %1, %2" : "=v"(r) : "v"(lo), "v"(hi)); return r; }
; __device__ __forceinline__ void xcd_barrier(const XcdBarrier& b) {
;     ...
;             asm volatile("s_waitcnt vmcnt(0)" ::: "memory");
;         }
;     }
;     __syncthreads();
; }
; __device__ __forceinline__ void phase_ln_in(const Frame& F) {
;     constexpr int LP = 2064;
;     LAS bf16_t* wgB = (LAS bf16_t*)F.lds;
;     LAS bf16_t* ub = (LAS bf16_t*)(F.lds + 16 * LP * 2);
;     LAS float* red = (LAS float*)(F.lds + 32 * LP * 2);
;     const float* win = F.in[10];
;     for (int k = F.tid; k < D; k += NTHREADS) { const float* sp = win + (size_t)k * NIN + 9216;
; #pragma unroll
;         for (int q = 0; q < 4; ++q) { const f32x4 v = *(const f32x4*)(sp + 4 * q); const unsigned w01 = cvt_pk_bf16(v[0], v[1]), w23 = cvt_pk_bf16(v[2], v[3]);
;             wgB[(4 * q + 0) * LP + k] = (bf16_t)(w01 & 0xffffu); wgB[(4 * q + 1) * LP + k] = (bf16_t)(w01 >> 16); wgB[(4 * q + 2) * LP + k] = (bf16_t)(w23 & 0xffffu); wgB[(4 * q + 3) * LP + k] = (bf16_t)(w23 >> 16); } }
.Lxb0_205:
	s_or_b64 exec, exec, s[4:5]
	s_waitcnt lgkmcnt(0)
	s_barrier
.LBB0_143:
	s_cmp_lt_i32 s96, 2
	s_cselect_b64 s[2:3], -1, 0
	s_lshr_b32 s93, s36, 6
	s_add_u32 s4, s66, 0x8ed4000
	s_addc_u32 s5, s67, 0
	v_writelane_b32 v254, s4, 36
	v_and_b32_e32 v147, 63, v192
	s_nop 0
	v_writelane_b32 v254, s5, 37
	s_and_b64 s[4:5], s[2:3], s[0:1]
	s_andn2_b64 vcc, exec, s[4:5]
	s_cbranch_vccnz .LBB0_156
	s_mov_b32 s0, 0xd040
	v_mov_b64_e32 v[0:1], s[80:81]
	v_mad_u64_u32 v[0:1], s[0:1], v192, s0, v[0:1]
	s_mov_b64 s[0:1], 0x9000
	s_nop 0
	v_lshl_add_u64 v[0:1], v[0:1], 0, s[0:1]
	v_add_u32_e32 v2, 0xfffffe00, v192
	v_lshl_add_u32 v3, v192, 1, 0
	s_mov_b64 s[0:1], 0
	s_mov_b64 s[6:7], 0x1a08000
	s_movk_i32 s2, 0x5ff
